# row-reduction butterflies in EpiRes/EpiResFin/EpiGelu epilogues: ds_bpermute round trips replaced by v_permlane16/32_swap (64 sites), plus flat->global conversion
# speedup vs baseline: 1.0109x; 1.0086x over previous
; #define LAS __attribute__((address_space(3)))
; __device__ __forceinline__ unsigned cvt_pk_bf16(float lo, float hi) { unsigned r; asm volatile("v_cvt_pk_bf16_f32 %0, %1, %2" : "=v"(r) : "v"(lo), "v"(hi)); return r; }
;     __device__ __forceinline__ void operator()(const f32x4 (&acc)[2][2][4][2], const Unit& u, int wr, int wc, int fr, int fq) const {
;         const int row0 = u.pm * BM + wr * 64 + fr, col0 = u.pn * BM + wc * 32 + 8 * fq;
;         LAS float* part = (LAS float*)(lds + PART_OFF);
;         u32x4 bb[2][4][2];
; #pragma unroll
;         for (int ai = 0; ai < 2; ++ai)
; #pragma unroll
;             for (int m = 0; m < 4; ++m)
; #pragma unroll
;                 for (int bj = 0; bj < 2; ++bj) bb[ai][m][bj] = *(const u32x4*)(xb + (size_t)(row0 + ai * HALF + m * 16) * D + col0 + bj * HALF);
; #pragma unroll
;         for (int ai = 0; ai < 2; ++ai)
; #pragma unroll
;             for (int m = 0; m < 4; ++m) { const size_t off = (size_t)(row0 + ai * HALF + m * 16) * D + col0; float sq = 0.f;
; #pragma unroll
;                 for (int bj = 0; bj < 2; ++bj) { const u32x4 b = bb[ai][m][bj];
;                     const f32x4 v0 = acc[ai][bj][m][0] + (f32x4){bflo(b.x), bfhi(b.x), bflo(b.y), bfhi(b.y)}, v1 = acc[ai][bj][m][1] + (f32x4){bflo(b.z), bfhi(b.z), bflo(b.w), bfhi(b.w)};
;                     u32x4 w; w.x = cvt_pk_bf16(v0[0], v0[1]); w.y = cvt_pk_bf16(v0[2], v0[3]); w.z = cvt_pk_bf16(v1[0], v1[1]); w.w = cvt_pk_bf16(v1[2], v1[3]);
;                     *(u32x4*)(xb + off + bj * HALF) = w;
;                     const float r0 = bflo(w.x), r1 = bfhi(w.x), r2 = bflo(w.y), r3 = bfhi(w.y), r4 = bflo(w.z), r5 = bfhi(w.z), r6 = bflo(w.w), r7 = bfhi(w.w);
;                     sq += ((r0 * r0 + r1 * r1) + (r2 * r2 + r3 * r3)) + ((r4 * r4 + r5 * r5) + (r6 * r6 + r7 * r7)); }
;                 sq += __shfl_xor(sq, 16); sq += __shfl_xor(sq, 32);
;                 if (fq == 0) part[(ai * HALF + wr * 64 + m * 16 + fr) * 4 + wc] = sq; }
.LBB0_154:
	s_lshl_b32 s35, s35, 8
	v_lshl_or_b32 v192, s34, 8, v243
	v_add_u32_e32 v108, s35, v242
	v_ashrrev_i32_e32 v193, 31, v192
	v_lshlrev_b64 v[216:217], 1, v[192:193]
	v_ashrrev_i32_e32 v109, 31, v108
	v_lshl_add_u64 v[110:111], s[18:19], 0, v[216:217]
	v_lshlrev_b64 v[218:219], 11, v[108:109]
	v_lshl_add_u64 v[120:121], v[110:111], 0, v[218:219]
	global_load_dwordx4 v[248:251], v[120:121], off
	global_load_dwordx4 v[188:191], v[120:121], off offset:256
	v_or_b32_e32 v120, 16, v108
	v_ashrrev_i32_e32 v121, 31, v120
	v_lshlrev_b64 v[214:215], 11, v[120:121]
	v_lshl_add_u64 v[120:121], v[110:111], 0, v[214:215]
	global_load_dwordx4 v[184:187], v[120:121], off
	global_load_dwordx4 v[180:183], v[120:121], off offset:256
	v_or_b32_e32 v120, 32, v108
	v_or_b32_e32 v108, 48, v108
	v_ashrrev_i32_e32 v121, 31, v120
	v_ashrrev_i32_e32 v109, 31, v108
	v_lshlrev_b64 v[212:213], 11, v[120:121]
	v_lshlrev_b64 v[210:211], 11, v[108:109]
	s_mov_b64 s[4:5], 0x40000
	v_lshl_add_u64 v[120:121], v[110:111], 0, v[212:213]
	v_lshl_add_u64 v[108:109], v[110:111], 0, v[210:211]
	v_lshl_add_u64 v[208:209], v[218:219], 0, s[4:5]
	s_mov_b64 s[4:5], 0x48000
	global_load_dwordx4 v[176:179], v[120:121], off
	global_load_dwordx4 v[164:167], v[120:121], off offset:256
	global_load_dwordx4 v[160:163], v[108:109], off
	global_load_dwordx4 v[156:159], v[108:109], off offset:256
	v_lshl_add_u64 v[108:109], v[110:111], 0, v[208:209]
	v_lshl_add_u64 v[206:207], v[218:219], 0, s[4:5]
	s_mov_b64 s[4:5], 0x50000
	global_load_dwordx4 v[152:155], v[108:109], off
	global_load_dwordx4 v[148:151], v[108:109], off offset:256
	v_lshl_add_u64 v[108:109], v[110:111], 0, v[206:207]
	v_lshl_add_u64 v[204:205], v[218:219], 0, s[4:5]
	s_mov_b64 s[4:5], 0x58000
	global_load_dwordx4 v[144:147], v[108:109], off
	global_load_dwordx4 v[136:139], v[108:109], off offset:256
	v_lshl_add_u64 v[108:109], v[110:111], 0, v[204:205]
	v_lshl_add_u64 v[202:203], v[218:219], 0, s[4:5]
	global_load_dwordx4 v[132:135], v[108:109], off
	global_load_dwordx4 v[128:131], v[108:109], off offset:256
	v_lshl_add_u64 v[108:109], v[110:111], 0, v[202:203]
	global_load_dwordx4 v[120:123], v[108:109], off
	s_nop 0
	global_load_dwordx4 v[108:111], v[108:109], off offset:256
	s_waitcnt vmcnt(0) lgkmcnt(0)
	v_lshlrev_b32_e32 v252, 16, v248
	v_and_b32_e32 v253, 0xffff0000, v248
	v_lshlrev_b32_e32 v248, 16, v249
	v_and_b32_e32 v249, 0xffff0000, v249
	v_pk_add_f32 v[174:175], v[174:175], v[248:249]
	v_lshlrev_b32_e32 v248, 16, v250
	v_and_b32_e32 v249, 0xffff0000, v250
	v_pk_add_f32 v[172:173], v[172:173], v[252:253]
	v_lshlrev_b32_e32 v250, 16, v251
	v_and_b32_e32 v251, 0xffff0000, v251
	v_pk_add_f32 v[168:169], v[168:169], v[248:249]
	v_pk_add_f32 v[250:251], v[170:171], v[250:251]
	v_cvt_pk_bf16_f32 v170, v172, v173
	v_cvt_pk_bf16_f32 v171, v174, v175
	v_cvt_pk_bf16_f32 v172, v168, v169
	v_lshl_add_u64 v[168:169], s[18:19], 0, v[218:219]
	v_lshl_add_u64 v[168:169], v[168:169], 0, v[216:217]
	v_cvt_pk_bf16_f32 v173, v250, v251
	global_store_dwordx4 v[168:169], v[170:173], off
	v_lshlrev_b32_e32 v174, 16, v170
	v_lshlrev_b32_e32 v175, 16, v171
	v_and_b32_e32 v170, 0xffff0000, v170
	v_and_b32_e32 v171, 0xffff0000, v171
	v_mul_f32_e32 v170, v170, v170
	v_mul_f32_e32 v171, v171, v171
	v_lshlrev_b32_e32 v216, 16, v172
	v_and_b32_e32 v172, 0xffff0000, v172
	v_lshlrev_b32_e32 v217, 16, v173
	v_and_b32_e32 v173, 0xffff0000, v173
	v_fmac_f32_e32 v170, v174, v174
	v_fmac_f32_e32 v171, v175, v175
	v_add_f32_e32 v170, v170, v171
	v_mul_f32_e32 v171, v172, v172
	v_mul_f32_e32 v172, v173, v173
	v_fmac_f32_e32 v171, v216, v216
	v_fmac_f32_e32 v172, v217, v217
	v_add_f32_e32 v171, v171, v172
	v_add_f32_e32 v174, v170, v171
	v_lshlrev_b32_e32 v170, 16, v188
	v_and_b32_e32 v171, 0xffff0000, v188
	v_lshlrev_b32_e32 v172, 16, v189
	v_and_b32_e32 v173, 0xffff0000, v189
	v_pk_add_f32 v[142:143], v[142:143], v[172:173]
	v_pk_add_f32 v[140:141], v[140:141], v[170:171]
	v_lshlrev_b32_e32 v170, 16, v190
	v_and_b32_e32 v171, 0xffff0000, v190
	v_lshlrev_b32_e32 v172, 16, v191
	v_and_b32_e32 v173, 0xffff0000, v191
	v_pk_add_f32 v[172:173], v[126:127], v[172:173]
	v_pk_add_f32 v[126:127], v[124:125], v[170:171]
	v_cvt_pk_bf16_f32 v124, v140, v141
	v_cvt_pk_bf16_f32 v125, v142, v143
	s_nop 0
	v_cvt_pk_bf16_f32 v126, v126, v127
	v_cvt_pk_bf16_f32 v127, v172, v173
	global_store_dwordx4 v[168:169], v[124:127], off offset:256
	v_lshlrev_b32_e32 v140, 16, v124
	v_lshlrev_b32_e32 v141, 16, v125
	v_and_b32_e32 v124, 0xffff0000, v124
	v_and_b32_e32 v125, 0xffff0000, v125
	v_mul_f32_e32 v124, v124, v124
	v_mul_f32_e32 v125, v125, v125
	v_lshlrev_b32_e32 v142, 16, v126
	v_and_b32_e32 v126, 0xffff0000, v126
	v_lshlrev_b32_e32 v143, 16, v127
	v_and_b32_e32 v127, 0xffff0000, v127
	v_fmac_f32_e32 v124, v140, v140
	v_fmac_f32_e32 v125, v141, v141
	v_add_f32_e32 v124, v124, v125
	v_mul_f32_e32 v125, v126, v126
	v_mul_f32_e32 v126, v127, v127
	v_fmac_f32_e32 v125, v142, v142
	v_fmac_f32_e32 v126, v143, v143
	v_add_f32_e32 v125, v125, v126
	v_add_f32_e32 v124, v124, v125
	v_and_b32_e32 v126, 64, v226
	v_add_f32_e32 v125, v174, v124
	v_xor_b32_e32 v124, 16, v226
	v_add_u32_e32 v127, 64, v126
	v_cmp_lt_i32_e32 vcc, v124, v127
	s_nop 1
	v_cndmask_b32_e32 v124, v226, v124, vcc
	v_lshlrev_b32_e32 v124, 2, v124
	v_mov_b32_e32 v126, v125
	s_nop 1
	v_permlane16_swap_b32_e32 v126, v125
	s_waitcnt lgkmcnt(0)
	v_add_f32_e32 v126, v125, v126
	v_xor_b32_e32 v125, 32, v226
	v_cmp_lt_i32_e32 vcc, v125, v127
	s_nop 1
	v_cndmask_b32_e32 v125, v226, v125, vcc
	v_lshlrev_b32_e32 v125, 2, v125
	v_mov_b32_e32 v127, v126
	s_nop 1
	v_permlane32_swap_b32_e32 v127, v126
	s_and_saveexec_b64 s[4:5], s[6:7]
	s_cbranch_execz .LBB0_156
	s_waitcnt lgkmcnt(0)
	v_add_f32_e32 v126, v126, v127
	ds_write_b32 v246, v126
; __device__ __forceinline__ unsigned cvt_pk_bf16(float lo, float hi) { unsigned r; asm volatile("v_cvt_pk_bf16_f32 %0, %1, %2" : "=v"(r) : "v"(lo), "v"(hi)); return r; }
;     __device__ __forceinline__ void operator()(const f32x4 (&acc)[2][2][4][2], const Unit& u, int wr, int wc, int fr, int fq) const {
;     ...
;             for (int m = 0; m < 4; ++m) { const size_t off = (size_t)(row0 + ai * HALF + m * 16) * D + col0; float sq = 0.f;
; #pragma unroll
;                 for (int bj = 0; bj < 2; ++bj) { const u32x4 b = bb[ai][m][bj];
;                     const f32x4 v0 = acc[ai][bj][m][0] + (f32x4){bflo(b.x), bfhi(b.x), bflo(b.y), bfhi(b.y)}, v1 = acc[ai][bj][m][1] + (f32x4){bflo(b.z), bfhi(b.z), bflo(b.w), bfhi(b.w)};
;                     u32x4 w; w.x = cvt_pk_bf16(v0[0], v0[1]); w.y = cvt_pk_bf16(v0[2], v0[3]); w.z = cvt_pk_bf16(v1[0], v1[1]); w.w = cvt_pk_bf16(v1[2], v1[3]);
;                     *(u32x4*)(xb + off + bj * HALF) = w;
;                     const float r0 = bflo(w.x), r1 = bfhi(w.x), r2 = bflo(w.y), r3 = bfhi(w.y), r4 = bflo(w.z), r5 = bfhi(w.z), r6 = bflo(w.w), r7 = bfhi(w.w);
;                     sq += ((r0 * r0 + r1 * r1) + (r2 * r2 + r3 * r3)) + ((r4 * r4 + r5 * r5) + (r6 * r6 + r7 * r7)); }
;                 sq += __shfl_xor(sq, 16); sq += __shfl_xor(sq, 32);
;                 if (fq == 0) part[(ai * HALF + wr * 64 + m * 16 + fr) * 4 + wc] = sq; }
.LBB0_156:
	s_or_b64 exec, exec, s[4:5]
	v_lshlrev_b32_e32 v126, 16, v184
	s_waitcnt lgkmcnt(0)
	v_and_b32_e32 v127, 0xffff0000, v184
	v_lshlrev_b32_e32 v140, 16, v185
	v_and_b32_e32 v141, 0xffff0000, v185
	v_pk_add_f32 v[118:119], v[118:119], v[140:141]
	v_pk_add_f32 v[116:117], v[116:117], v[126:127]
	v_lshlrev_b32_e32 v126, 16, v186
	v_and_b32_e32 v127, 0xffff0000, v186
	v_lshlrev_b32_e32 v140, 16, v187
	v_and_b32_e32 v141, 0xffff0000, v187
	v_pk_add_f32 v[140:141], v[114:115], v[140:141]
	v_pk_add_f32 v[114:115], v[112:113], v[126:127]
	v_cvt_pk_bf16_f32 v112, v116, v117
	v_lshl_add_u64 v[116:117], s[18:19], 0, v[214:215]
	v_cvt_pk_bf16_f32 v113, v118, v119
	v_lshl_add_u64 v[116:117], v[192:193], 1, v[116:117]
	v_cvt_pk_bf16_f32 v114, v114, v115
	v_cvt_pk_bf16_f32 v115, v140, v141
	global_store_dwordx4 v[116:117], v[112:115], off
	v_lshlrev_b32_e32 v118, 16, v112
	v_lshlrev_b32_e32 v119, 16, v113
	v_and_b32_e32 v112, 0xffff0000, v112
	v_and_b32_e32 v113, 0xffff0000, v113
	v_mul_f32_e32 v112, v112, v112
	v_mul_f32_e32 v113, v113, v113
	v_lshlrev_b32_e32 v126, 16, v114
	v_and_b32_e32 v114, 0xffff0000, v114
	v_lshlrev_b32_e32 v127, 16, v115
	v_and_b32_e32 v115, 0xffff0000, v115
	v_fmac_f32_e32 v112, v118, v118
	v_fmac_f32_e32 v113, v119, v119
	v_add_f32_e32 v112, v112, v113
	v_mul_f32_e32 v113, v114, v114
	v_mul_f32_e32 v114, v115, v115
	v_fmac_f32_e32 v113, v126, v126
	v_fmac_f32_e32 v114, v127, v127
	v_add_f32_e32 v113, v113, v114
	v_add_f32_e32 v118, v112, v113
	v_lshlrev_b32_e32 v112, 16, v180
	v_and_b32_e32 v113, 0xffff0000, v180
	v_lshlrev_b32_e32 v114, 16, v181
	v_and_b32_e32 v115, 0xffff0000, v181
	v_pk_add_f32 v[104:105], v[104:105], v[112:113]
	v_lshlrev_b32_e32 v112, 16, v182
	v_and_b32_e32 v113, 0xffff0000, v182
	v_pk_add_f32 v[106:107], v[106:107], v[114:115]
	v_lshlrev_b32_e32 v114, 16, v183
	v_and_b32_e32 v115, 0xffff0000, v183
	v_pk_add_f32 v[100:101], v[100:101], v[112:113]
	v_pk_add_f32 v[114:115], v[102:103], v[114:115]
	v_cvt_pk_bf16_f32 v102, v104, v105
	v_cvt_pk_bf16_f32 v103, v106, v107
	v_cvt_pk_bf16_f32 v104, v100, v101
	s_nop 0
	v_and_b32_e32 v101, 0xffff0000, v102
	v_lshlrev_b32_e32 v100, 16, v102
	v_and_b32_e32 v107, 0xffff0000, v103
	v_mul_f32_e32 v101, v101, v101
	v_lshlrev_b32_e32 v106, 16, v103
	v_fmac_f32_e32 v101, v100, v100
	v_mul_f32_e32 v100, v107, v107
	v_cvt_pk_bf16_f32 v105, v114, v115
	v_and_b32_e32 v113, 0xffff0000, v104
	v_and_b32_e32 v115, 0xffff0000, v105
	v_fmac_f32_e32 v100, v106, v106
	v_lshlrev_b32_e32 v112, 16, v104
	v_lshlrev_b32_e32 v114, 16, v105
	v_add_f32_e32 v100, v101, v100
	v_mul_f32_e32 v101, v113, v113
	v_mul_f32_e32 v106, v115, v115
	v_fmac_f32_e32 v101, v112, v112
	v_fmac_f32_e32 v106, v114, v114
	v_add_f32_e32 v101, v101, v106
	v_add_f32_e32 v100, v100, v101
	v_add_f32_e32 v100, v118, v100
	v_mov_b32_e32 v101, v100
	s_nop 1
	v_permlane16_swap_b32_e32 v101, v100
	global_store_dwordx4 v[116:117], v[102:105], off offset:256
	s_waitcnt lgkmcnt(0)
	v_add_f32_e32 v100, v100, v101
	v_mov_b32_e32 v101, v100
	s_nop 1
	v_permlane32_swap_b32_e32 v101, v100
	s_and_saveexec_b64 s[4:5], s[6:7]
	s_cbranch_execz .LBB0_158
	s_waitcnt lgkmcnt(0)
	v_add_f32_e32 v100, v100, v101
	ds_write_b32 v246, v100 offset:256
.LBB0_158:
	s_or_b64 exec, exec, s[4:5]
	v_lshlrev_b32_e32 v100, 16, v176
	s_waitcnt lgkmcnt(0)
	v_and_b32_e32 v101, 0xffff0000, v176
	v_lshlrev_b32_e32 v102, 16, v177
	v_and_b32_e32 v103, 0xffff0000, v177
	v_pk_add_f32 v[98:99], v[98:99], v[102:103]
	v_pk_add_f32 v[96:97], v[96:97], v[100:101]
	v_lshlrev_b32_e32 v100, 16, v178
	v_and_b32_e32 v101, 0xffff0000, v178
	v_lshlrev_b32_e32 v102, 16, v179
	v_and_b32_e32 v103, 0xffff0000, v179
	v_pk_add_f32 v[102:103], v[94:95], v[102:103]
	v_pk_add_f32 v[94:95], v[92:93], v[100:101]
	v_cvt_pk_bf16_f32 v92, v96, v97
	v_lshl_add_u64 v[96:97], s[18:19], 0, v[212:213]
	v_cvt_pk_bf16_f32 v93, v98, v99
	v_lshl_add_u64 v[96:97], v[192:193], 1, v[96:97]
	v_cvt_pk_bf16_f32 v94, v94, v95
	v_cvt_pk_bf16_f32 v95, v102, v103
	global_store_dwordx4 v[96:97], v[92:95], off
	v_lshlrev_b32_e32 v98, 16, v92
	v_lshlrev_b32_e32 v99, 16, v93
	v_and_b32_e32 v92, 0xffff0000, v92
	v_and_b32_e32 v93, 0xffff0000, v93
	v_mul_f32_e32 v92, v92, v92
	v_mul_f32_e32 v93, v93, v93
	v_lshlrev_b32_e32 v100, 16, v94
	v_and_b32_e32 v94, 0xffff0000, v94
	v_lshlrev_b32_e32 v101, 16, v95
	v_and_b32_e32 v95, 0xffff0000, v95
	v_fmac_f32_e32 v92, v98, v98
	v_fmac_f32_e32 v93, v99, v99
	v_add_f32_e32 v92, v92, v93
	v_mul_f32_e32 v93, v94, v94
	v_mul_f32_e32 v94, v95, v95
	v_fmac_f32_e32 v93, v100, v100
	v_fmac_f32_e32 v94, v101, v101
	v_add_f32_e32 v93, v93, v94
	v_add_f32_e32 v98, v92, v93
	v_lshlrev_b32_e32 v92, 16, v164
	v_and_b32_e32 v93, 0xffff0000, v164
	v_lshlrev_b32_e32 v94, 16, v165
	v_and_b32_e32 v95, 0xffff0000, v165
	v_pk_add_f32 v[88:89], v[88:89], v[92:93]
	v_lshlrev_b32_e32 v92, 16, v166
	v_and_b32_e32 v93, 0xffff0000, v166
	v_pk_add_f32 v[90:91], v[90:91], v[94:95]
	v_lshlrev_b32_e32 v94, 16, v167
	v_and_b32_e32 v95, 0xffff0000, v167
	v_pk_add_f32 v[84:85], v[84:85], v[92:93]
	v_pk_add_f32 v[94:95], v[86:87], v[94:95]
	v_cvt_pk_bf16_f32 v86, v88, v89
	v_cvt_pk_bf16_f32 v87, v90, v91
	v_cvt_pk_bf16_f32 v88, v84, v85
	s_nop 0
	v_and_b32_e32 v85, 0xffff0000, v86
	v_lshlrev_b32_e32 v84, 16, v86
	v_and_b32_e32 v91, 0xffff0000, v87
	v_mul_f32_e32 v85, v85, v85
	v_lshlrev_b32_e32 v90, 16, v87
	v_fmac_f32_e32 v85, v84, v84
	v_mul_f32_e32 v84, v91, v91
	v_cvt_pk_bf16_f32 v89, v94, v95
	v_and_b32_e32 v93, 0xffff0000, v88
	v_and_b32_e32 v95, 0xffff0000, v89
	v_fmac_f32_e32 v84, v90, v90
	v_lshlrev_b32_e32 v92, 16, v88
	v_lshlrev_b32_e32 v94, 16, v89
	v_add_f32_e32 v84, v85, v84
	v_mul_f32_e32 v85, v93, v93
	v_mul_f32_e32 v90, v95, v95
	v_fmac_f32_e32 v85, v92, v92
	v_fmac_f32_e32 v90, v94, v94
	v_add_f32_e32 v85, v85, v90
	v_add_f32_e32 v84, v84, v85
	v_add_f32_e32 v84, v98, v84
	v_mov_b32_e32 v85, v84
	s_nop 1
	v_permlane16_swap_b32_e32 v85, v84
	global_store_dwordx4 v[96:97], v[86:89], off offset:256
	s_waitcnt lgkmcnt(0)
	v_add_f32_e32 v84, v84, v85
	v_mov_b32_e32 v85, v84
	s_nop 1
	v_permlane32_swap_b32_e32 v85, v84
	s_and_saveexec_b64 s[4:5], s[6:7]
	s_cbranch_execz .LBB0_160
	s_waitcnt lgkmcnt(0)
	v_add_f32_e32 v84, v84, v85
	ds_write_b32 v246, v84 offset:512
; __device__ __forceinline__ unsigned cvt_pk_bf16(float lo, float hi) { unsigned r; asm volatile("v_cvt_pk_bf16_f32 %0, %1, %2" : "=v"(r) : "v"(lo), "v"(hi)); return r; }
;     __device__ __forceinline__ void operator()(const f32x4 (&acc)[2][2][4][2], const Unit& u, int wr, int wc, int fr, int fq) const {
;     ...
;             for (int m = 0; m < 4; ++m) { const size_t off = (size_t)(row0 + ai * HALF + m * 16) * D + col0; float sq = 0.f;
; #pragma unroll
;                 for (int bj = 0; bj < 2; ++bj) { const u32x4 b = bb[ai][m][bj];
;                     const f32x4 v0 = acc[ai][bj][m][0] + (f32x4){bflo(b.x), bfhi(b.x), bflo(b.y), bfhi(b.y)}, v1 = acc[ai][bj][m][1] + (f32x4){bflo(b.z), bfhi(b.z), bflo(b.w), bfhi(b.w)};
;                     u32x4 w; w.x = cvt_pk_bf16(v0[0], v0[1]); w.y = cvt_pk_bf16(v0[2], v0[3]); w.z = cvt_pk_bf16(v1[0], v1[1]); w.w = cvt_pk_bf16(v1[2], v1[3]);
;                     *(u32x4*)(xb + off + bj * HALF) = w;
;                     const float r0 = bflo(w.x), r1 = bfhi(w.x), r2 = bflo(w.y), r3 = bfhi(w.y), r4 = bflo(w.z), r5 = bfhi(w.z), r6 = bflo(w.w), r7 = bfhi(w.w);
;                     sq += ((r0 * r0 + r1 * r1) + (r2 * r2 + r3 * r3)) + ((r4 * r4 + r5 * r5) + (r6 * r6 + r7 * r7)); }
;                 sq += __shfl_xor(sq, 16); sq += __shfl_xor(sq, 32);
;                 if (fq == 0) part[(ai * HALF + wr * 64 + m * 16 + fr) * 4 + wc] = sq; }
.LBB0_160:
	s_or_b64 exec, exec, s[4:5]
	v_lshlrev_b32_e32 v84, 16, v160
	s_waitcnt lgkmcnt(0)
	v_and_b32_e32 v85, 0xffff0000, v160
	v_lshlrev_b32_e32 v86, 16, v161
	v_and_b32_e32 v87, 0xffff0000, v161
	v_pk_add_f32 v[82:83], v[82:83], v[86:87]
	v_pk_add_f32 v[80:81], v[80:81], v[84:85]
	v_lshlrev_b32_e32 v84, 16, v162
	v_and_b32_e32 v85, 0xffff0000, v162
	v_lshlrev_b32_e32 v86, 16, v163
	v_and_b32_e32 v87, 0xffff0000, v163
	v_pk_add_f32 v[86:87], v[78:79], v[86:87]
	v_pk_add_f32 v[78:79], v[76:77], v[84:85]
	v_cvt_pk_bf16_f32 v76, v80, v81
	v_lshl_add_u64 v[80:81], s[18:19], 0, v[210:211]
	v_cvt_pk_bf16_f32 v77, v82, v83
	v_lshl_add_u64 v[80:81], v[192:193], 1, v[80:81]
	v_cvt_pk_bf16_f32 v78, v78, v79
	v_cvt_pk_bf16_f32 v79, v86, v87
	global_store_dwordx4 v[80:81], v[76:79], off
	v_lshlrev_b32_e32 v82, 16, v76
	v_lshlrev_b32_e32 v83, 16, v77
	v_and_b32_e32 v76, 0xffff0000, v76
	v_and_b32_e32 v77, 0xffff0000, v77
	v_mul_f32_e32 v76, v76, v76
	v_mul_f32_e32 v77, v77, v77
	v_lshlrev_b32_e32 v84, 16, v78
	v_and_b32_e32 v78, 0xffff0000, v78
	v_lshlrev_b32_e32 v85, 16, v79
	v_and_b32_e32 v79, 0xffff0000, v79
	v_fmac_f32_e32 v76, v82, v82
	v_fmac_f32_e32 v77, v83, v83
	v_add_f32_e32 v76, v76, v77
	v_mul_f32_e32 v77, v78, v78
	v_mul_f32_e32 v78, v79, v79
	v_fmac_f32_e32 v77, v84, v84
	v_fmac_f32_e32 v78, v85, v85
	v_add_f32_e32 v77, v77, v78
	v_add_f32_e32 v82, v76, v77
	v_lshlrev_b32_e32 v76, 16, v156
	v_and_b32_e32 v77, 0xffff0000, v156
	v_lshlrev_b32_e32 v78, 16, v157
	v_and_b32_e32 v79, 0xffff0000, v157
	v_pk_add_f32 v[72:73], v[72:73], v[76:77]
	v_lshlrev_b32_e32 v76, 16, v158
	v_and_b32_e32 v77, 0xffff0000, v158
	v_pk_add_f32 v[74:75], v[74:75], v[78:79]
	v_lshlrev_b32_e32 v78, 16, v159
	v_and_b32_e32 v79, 0xffff0000, v159
	v_pk_add_f32 v[68:69], v[68:69], v[76:77]
	v_pk_add_f32 v[78:79], v[70:71], v[78:79]
	v_cvt_pk_bf16_f32 v70, v72, v73
	v_cvt_pk_bf16_f32 v71, v74, v75
	v_cvt_pk_bf16_f32 v72, v68, v69
	s_nop 0
	v_and_b32_e32 v69, 0xffff0000, v70
	v_lshlrev_b32_e32 v68, 16, v70
	v_and_b32_e32 v75, 0xffff0000, v71
	v_mul_f32_e32 v69, v69, v69
	v_lshlrev_b32_e32 v74, 16, v71
	v_fmac_f32_e32 v69, v68, v68
	v_mul_f32_e32 v68, v75, v75
	v_cvt_pk_bf16_f32 v73, v78, v79
	v_and_b32_e32 v77, 0xffff0000, v72
	v_and_b32_e32 v79, 0xffff0000, v73
	v_fmac_f32_e32 v68, v74, v74
	v_lshlrev_b32_e32 v76, 16, v72
	v_lshlrev_b32_e32 v78, 16, v73
	v_add_f32_e32 v68, v69, v68
	v_mul_f32_e32 v69, v77, v77
	v_mul_f32_e32 v74, v79, v79
	v_fmac_f32_e32 v69, v76, v76
	v_fmac_f32_e32 v74, v78, v78
	v_add_f32_e32 v69, v69, v74
	v_add_f32_e32 v68, v68, v69
	v_add_f32_e32 v68, v82, v68
	v_mov_b32_e32 v69, v68
	s_nop 1
	v_permlane16_swap_b32_e32 v69, v68
	global_store_dwordx4 v[80:81], v[70:73], off offset:256
	s_waitcnt lgkmcnt(0)
	v_add_f32_e32 v68, v68, v69
	v_mov_b32_e32 v69, v68
	s_nop 1
	v_permlane32_swap_b32_e32 v69, v68
	s_and_saveexec_b64 s[4:5], s[6:7]
	s_cbranch_execz .LBB0_162
	s_waitcnt lgkmcnt(0)
	v_add_f32_e32 v68, v68, v69
	ds_write_b32 v246, v68 offset:768
.LBB0_162:
	s_or_b64 exec, exec, s[4:5]
	v_lshlrev_b32_e32 v68, 16, v152
	s_waitcnt lgkmcnt(0)
	v_and_b32_e32 v69, 0xffff0000, v152
	v_lshlrev_b32_e32 v70, 16, v153
	v_and_b32_e32 v71, 0xffff0000, v153
	v_pk_add_f32 v[66:67], v[66:67], v[70:71]
	v_pk_add_f32 v[64:65], v[64:65], v[68:69]
	v_lshlrev_b32_e32 v68, 16, v154
	v_and_b32_e32 v69, 0xffff0000, v154
	v_lshlrev_b32_e32 v70, 16, v155
	v_and_b32_e32 v71, 0xffff0000, v155
	v_pk_add_f32 v[70:71], v[62:63], v[70:71]
	v_pk_add_f32 v[62:63], v[60:61], v[68:69]
	v_cvt_pk_bf16_f32 v60, v64, v65
	v_lshl_add_u64 v[64:65], s[18:19], 0, v[208:209]
	v_cvt_pk_bf16_f32 v61, v66, v67
	v_lshl_add_u64 v[64:65], v[192:193], 1, v[64:65]
	v_cvt_pk_bf16_f32 v62, v62, v63
	v_cvt_pk_bf16_f32 v63, v70, v71
	global_store_dwordx4 v[64:65], v[60:63], off
	v_lshlrev_b32_e32 v66, 16, v60
	v_lshlrev_b32_e32 v67, 16, v61
	v_and_b32_e32 v60, 0xffff0000, v60
	v_and_b32_e32 v61, 0xffff0000, v61
	v_mul_f32_e32 v60, v60, v60
	v_mul_f32_e32 v61, v61, v61
	v_lshlrev_b32_e32 v68, 16, v62
	v_and_b32_e32 v62, 0xffff0000, v62
	v_lshlrev_b32_e32 v69, 16, v63
	v_and_b32_e32 v63, 0xffff0000, v63
	v_fmac_f32_e32 v60, v66, v66
	v_fmac_f32_e32 v61, v67, v67
	v_add_f32_e32 v60, v60, v61
	v_mul_f32_e32 v61, v62, v62
	v_mul_f32_e32 v62, v63, v63
	v_fmac_f32_e32 v61, v68, v68
	v_fmac_f32_e32 v62, v69, v69
	v_add_f32_e32 v61, v61, v62
	v_add_f32_e32 v66, v60, v61
	v_lshlrev_b32_e32 v60, 16, v148
	v_and_b32_e32 v61, 0xffff0000, v148
	v_lshlrev_b32_e32 v62, 16, v149
	v_and_b32_e32 v63, 0xffff0000, v149
	v_pk_add_f32 v[56:57], v[56:57], v[60:61]
	v_lshlrev_b32_e32 v60, 16, v150
	v_and_b32_e32 v61, 0xffff0000, v150
	v_pk_add_f32 v[58:59], v[58:59], v[62:63]
	v_lshlrev_b32_e32 v62, 16, v151
	v_and_b32_e32 v63, 0xffff0000, v151
	v_pk_add_f32 v[52:53], v[52:53], v[60:61]
	v_pk_add_f32 v[62:63], v[54:55], v[62:63]
	v_cvt_pk_bf16_f32 v54, v56, v57
	v_cvt_pk_bf16_f32 v55, v58, v59
	v_cvt_pk_bf16_f32 v56, v52, v53
	s_nop 0
	v_and_b32_e32 v53, 0xffff0000, v54
	v_lshlrev_b32_e32 v52, 16, v54
	v_and_b32_e32 v59, 0xffff0000, v55
	v_mul_f32_e32 v53, v53, v53
	v_lshlrev_b32_e32 v58, 16, v55
	v_fmac_f32_e32 v53, v52, v52
	v_mul_f32_e32 v52, v59, v59
	v_cvt_pk_bf16_f32 v57, v62, v63
	v_and_b32_e32 v61, 0xffff0000, v56
	v_and_b32_e32 v63, 0xffff0000, v57
	v_fmac_f32_e32 v52, v58, v58
	v_lshlrev_b32_e32 v60, 16, v56
	v_lshlrev_b32_e32 v62, 16, v57
	v_add_f32_e32 v52, v53, v52
	v_mul_f32_e32 v53, v61, v61
	v_mul_f32_e32 v58, v63, v63
	v_fmac_f32_e32 v53, v60, v60
	v_fmac_f32_e32 v58, v62, v62
	v_add_f32_e32 v53, v53, v58
	v_add_f32_e32 v52, v52, v53
	v_add_f32_e32 v52, v66, v52
	v_mov_b32_e32 v53, v52
	s_nop 1
	v_permlane16_swap_b32_e32 v53, v52
	global_store_dwordx4 v[64:65], v[54:57], off offset:256
	s_waitcnt lgkmcnt(0)
	v_add_f32_e32 v52, v52, v53
	v_mov_b32_e32 v53, v52
	s_nop 1
	v_permlane32_swap_b32_e32 v53, v52
	s_and_saveexec_b64 s[4:5], s[6:7]
	s_cbranch_execz .LBB0_164
	s_waitcnt lgkmcnt(0)
	v_add_f32_e32 v52, v52, v53
	ds_write_b32 v246, v52 offset:2048
; __device__ __forceinline__ unsigned cvt_pk_bf16(float lo, float hi) { unsigned r; asm volatile("v_cvt_pk_bf16_f32 %0, %1, %2" : "=v"(r) : "v"(lo), "v"(hi)); return r; }
;     __device__ __forceinline__ void operator()(const f32x4 (&acc)[2][2][4][2], const Unit& u, int wr, int wc, int fr, int fq) const {
;     ...
;             for (int m = 0; m < 4; ++m) { const size_t off = (size_t)(row0 + ai * HALF + m * 16) * D + col0; float sq = 0.f;
; #pragma unroll
;                 for (int bj = 0; bj < 2; ++bj) { const u32x4 b = bb[ai][m][bj];
;                     const f32x4 v0 = acc[ai][bj][m][0] + (f32x4){bflo(b.x), bfhi(b.x), bflo(b.y), bfhi(b.y)}, v1 = acc[ai][bj][m][1] + (f32x4){bflo(b.z), bfhi(b.z), bflo(b.w), bfhi(b.w)};
;                     u32x4 w; w.x = cvt_pk_bf16(v0[0], v0[1]); w.y = cvt_pk_bf16(v0[2], v0[3]); w.z = cvt_pk_bf16(v1[0], v1[1]); w.w = cvt_pk_bf16(v1[2], v1[3]);
;                     *(u32x4*)(xb + off + bj * HALF) = w;
;                     const float r0 = bflo(w.x), r1 = bfhi(w.x), r2 = bflo(w.y), r3 = bfhi(w.y), r4 = bflo(w.z), r5 = bfhi(w.z), r6 = bflo(w.w), r7 = bfhi(w.w);
;                     sq += ((r0 * r0 + r1 * r1) + (r2 * r2 + r3 * r3)) + ((r4 * r4 + r5 * r5) + (r6 * r6 + r7 * r7)); }
;                 sq += __shfl_xor(sq, 16); sq += __shfl_xor(sq, 32);
;                 if (fq == 0) part[(ai * HALF + wr * 64 + m * 16 + fr) * 4 + wc] = sq; }
.LBB0_164:
	s_or_b64 exec, exec, s[4:5]
	v_lshlrev_b32_e32 v52, 16, v144
	s_waitcnt lgkmcnt(0)
	v_and_b32_e32 v53, 0xffff0000, v144
	v_lshlrev_b32_e32 v54, 16, v145
	v_and_b32_e32 v55, 0xffff0000, v145
	v_pk_add_f32 v[50:51], v[50:51], v[54:55]
	v_pk_add_f32 v[48:49], v[48:49], v[52:53]
	v_lshlrev_b32_e32 v52, 16, v146
	v_and_b32_e32 v53, 0xffff0000, v146
	v_lshlrev_b32_e32 v54, 16, v147
	v_and_b32_e32 v55, 0xffff0000, v147
	v_pk_add_f32 v[54:55], v[46:47], v[54:55]
	v_pk_add_f32 v[46:47], v[44:45], v[52:53]
	v_cvt_pk_bf16_f32 v44, v48, v49
	v_lshl_add_u64 v[48:49], s[18:19], 0, v[206:207]
	v_cvt_pk_bf16_f32 v45, v50, v51
	v_lshl_add_u64 v[48:49], v[192:193], 1, v[48:49]
	v_cvt_pk_bf16_f32 v46, v46, v47
	v_cvt_pk_bf16_f32 v47, v54, v55
	global_store_dwordx4 v[48:49], v[44:47], off
	v_lshlrev_b32_e32 v50, 16, v44
	v_lshlrev_b32_e32 v51, 16, v45
	v_and_b32_e32 v44, 0xffff0000, v44
	v_and_b32_e32 v45, 0xffff0000, v45
	v_mul_f32_e32 v44, v44, v44
	v_mul_f32_e32 v45, v45, v45
	v_lshlrev_b32_e32 v52, 16, v46
	v_and_b32_e32 v46, 0xffff0000, v46
	v_lshlrev_b32_e32 v53, 16, v47
	v_and_b32_e32 v47, 0xffff0000, v47
	v_fmac_f32_e32 v44, v50, v50
	v_fmac_f32_e32 v45, v51, v51
	v_add_f32_e32 v44, v44, v45
	v_mul_f32_e32 v45, v46, v46
	v_mul_f32_e32 v46, v47, v47
	v_fmac_f32_e32 v45, v52, v52
	v_fmac_f32_e32 v46, v53, v53
	v_add_f32_e32 v45, v45, v46
	v_add_f32_e32 v50, v44, v45
	v_lshlrev_b32_e32 v44, 16, v136
	v_and_b32_e32 v45, 0xffff0000, v136
	v_lshlrev_b32_e32 v46, 16, v137
	v_and_b32_e32 v47, 0xffff0000, v137
	v_pk_add_f32 v[40:41], v[40:41], v[44:45]
	v_lshlrev_b32_e32 v44, 16, v138
	v_and_b32_e32 v45, 0xffff0000, v138
	v_pk_add_f32 v[42:43], v[42:43], v[46:47]
	v_lshlrev_b32_e32 v46, 16, v139
	v_and_b32_e32 v47, 0xffff0000, v139
	v_pk_add_f32 v[36:37], v[36:37], v[44:45]
	v_pk_add_f32 v[46:47], v[38:39], v[46:47]
	v_cvt_pk_bf16_f32 v38, v40, v41
	v_cvt_pk_bf16_f32 v39, v42, v43
	v_cvt_pk_bf16_f32 v40, v36, v37
	s_nop 0
	v_and_b32_e32 v37, 0xffff0000, v38
	v_lshlrev_b32_e32 v36, 16, v38
	v_and_b32_e32 v43, 0xffff0000, v39
	v_mul_f32_e32 v37, v37, v37
	v_lshlrev_b32_e32 v42, 16, v39
	v_fmac_f32_e32 v37, v36, v36
	v_mul_f32_e32 v36, v43, v43
	v_cvt_pk_bf16_f32 v41, v46, v47
	v_and_b32_e32 v45, 0xffff0000, v40
	v_and_b32_e32 v47, 0xffff0000, v41
	v_fmac_f32_e32 v36, v42, v42
	v_lshlrev_b32_e32 v44, 16, v40
	v_lshlrev_b32_e32 v46, 16, v41
	v_add_f32_e32 v36, v37, v36
	v_mul_f32_e32 v37, v45, v45
	v_mul_f32_e32 v42, v47, v47
	v_fmac_f32_e32 v37, v44, v44
	v_fmac_f32_e32 v42, v46, v46
	v_add_f32_e32 v37, v37, v42
	v_add_f32_e32 v36, v36, v37
	v_add_f32_e32 v36, v50, v36
	v_mov_b32_e32 v37, v36
	s_nop 1
	v_permlane16_swap_b32_e32 v37, v36
	global_store_dwordx4 v[48:49], v[38:41], off offset:256
	s_waitcnt lgkmcnt(0)
	v_add_f32_e32 v36, v36, v37
	v_mov_b32_e32 v37, v36
	s_nop 1
	v_permlane32_swap_b32_e32 v37, v36
	s_and_saveexec_b64 s[4:5], s[6:7]
	s_cbranch_execz .LBB0_166
	s_waitcnt lgkmcnt(0)
	v_add_f32_e32 v36, v36, v37
	ds_write_b32 v246, v36 offset:2304
; __device__ __forceinline__ unsigned cvt_pk_bf16(float lo, float hi) { unsigned r; asm volatile("v_cvt_pk_bf16_f32 %0, %1, %2" : "=v"(r) : "v"(lo), "v"(hi)); return r; }
;     __device__ __forceinline__ void operator()(const f32x4 (&acc)[2][2][4][2], const Unit& u, int wr, int wc, int fr, int fq) const {
;     ...
;             for (int m = 0; m < 4; ++m) { const size_t off = (size_t)(row0 + ai * HALF + m * 16) * D + col0; float sq = 0.f;
; #pragma unroll
;                 for (int bj = 0; bj < 2; ++bj) { const u32x4 b = bb[ai][m][bj];
;                     const f32x4 v0 = acc[ai][bj][m][0] + (f32x4){bflo(b.x), bfhi(b.x), bflo(b.y), bfhi(b.y)}, v1 = acc[ai][bj][m][1] + (f32x4){bflo(b.z), bfhi(b.z), bflo(b.w), bfhi(b.w)};
;                     u32x4 w; w.x = cvt_pk_bf16(v0[0], v0[1]); w.y = cvt_pk_bf16(v0[2], v0[3]); w.z = cvt_pk_bf16(v1[0], v1[1]); w.w = cvt_pk_bf16(v1[2], v1[3]);
;                     *(u32x4*)(xb + off + bj * HALF) = w;
;                     const float r0 = bflo(w.x), r1 = bfhi(w.x), r2 = bflo(w.y), r3 = bfhi(w.y), r4 = bflo(w.z), r5 = bfhi(w.z), r6 = bflo(w.w), r7 = bfhi(w.w);
;                     sq += ((r0 * r0 + r1 * r1) + (r2 * r2 + r3 * r3)) + ((r4 * r4 + r5 * r5) + (r6 * r6 + r7 * r7)); }
;                 sq += __shfl_xor(sq, 16); sq += __shfl_xor(sq, 32);
;                 if (fq == 0) part[(ai * HALF + wr * 64 + m * 16 + fr) * 4 + wc] = sq; }
.LBB0_166:
	s_or_b64 exec, exec, s[4:5]
	v_lshlrev_b32_e32 v36, 16, v132
	s_waitcnt lgkmcnt(0)
	v_and_b32_e32 v37, 0xffff0000, v132
	v_lshlrev_b32_e32 v38, 16, v133
	v_and_b32_e32 v39, 0xffff0000, v133
	v_pk_add_f32 v[34:35], v[34:35], v[38:39]
	v_pk_add_f32 v[32:33], v[32:33], v[36:37]
	v_lshlrev_b32_e32 v36, 16, v134
	v_and_b32_e32 v37, 0xffff0000, v134
	v_lshlrev_b32_e32 v38, 16, v135
	v_and_b32_e32 v39, 0xffff0000, v135
	v_pk_add_f32 v[38:39], v[30:31], v[38:39]
	v_pk_add_f32 v[30:31], v[28:29], v[36:37]
	v_cvt_pk_bf16_f32 v28, v32, v33
	v_lshl_add_u64 v[32:33], s[18:19], 0, v[204:205]
	v_cvt_pk_bf16_f32 v29, v34, v35
	v_lshl_add_u64 v[32:33], v[192:193], 1, v[32:33]
	v_cvt_pk_bf16_f32 v30, v30, v31
	v_cvt_pk_bf16_f32 v31, v38, v39
	global_store_dwordx4 v[32:33], v[28:31], off
	v_lshlrev_b32_e32 v34, 16, v28
	v_lshlrev_b32_e32 v35, 16, v29
	v_and_b32_e32 v28, 0xffff0000, v28
	v_and_b32_e32 v29, 0xffff0000, v29
	v_mul_f32_e32 v28, v28, v28
	v_mul_f32_e32 v29, v29, v29
	v_lshlrev_b32_e32 v36, 16, v30
	v_and_b32_e32 v30, 0xffff0000, v30
	v_lshlrev_b32_e32 v37, 16, v31
	v_and_b32_e32 v31, 0xffff0000, v31
	v_fmac_f32_e32 v28, v34, v34
	v_fmac_f32_e32 v29, v35, v35
	v_add_f32_e32 v28, v28, v29
	v_mul_f32_e32 v29, v30, v30
	v_mul_f32_e32 v30, v31, v31
	v_fmac_f32_e32 v29, v36, v36
	v_fmac_f32_e32 v30, v37, v37
	v_add_f32_e32 v29, v29, v30
	v_add_f32_e32 v34, v28, v29
	v_lshlrev_b32_e32 v28, 16, v128
	v_and_b32_e32 v29, 0xffff0000, v128
	v_lshlrev_b32_e32 v30, 16, v129
	v_and_b32_e32 v31, 0xffff0000, v129
	v_pk_add_f32 v[24:25], v[24:25], v[28:29]
	v_lshlrev_b32_e32 v28, 16, v130
	v_and_b32_e32 v29, 0xffff0000, v130
	v_pk_add_f32 v[26:27], v[26:27], v[30:31]
	v_lshlrev_b32_e32 v30, 16, v131
	v_and_b32_e32 v31, 0xffff0000, v131
	v_pk_add_f32 v[20:21], v[20:21], v[28:29]
	v_pk_add_f32 v[30:31], v[22:23], v[30:31]
	v_cvt_pk_bf16_f32 v22, v24, v25
	v_cvt_pk_bf16_f32 v23, v26, v27
	v_cvt_pk_bf16_f32 v24, v20, v21
	s_nop 0
	v_and_b32_e32 v21, 0xffff0000, v22
	v_lshlrev_b32_e32 v20, 16, v22
	v_and_b32_e32 v27, 0xffff0000, v23
	v_mul_f32_e32 v21, v21, v21
	v_lshlrev_b32_e32 v26, 16, v23
	v_fmac_f32_e32 v21, v20, v20
	v_mul_f32_e32 v20, v27, v27
	v_cvt_pk_bf16_f32 v25, v30, v31
	v_and_b32_e32 v29, 0xffff0000, v24
	v_and_b32_e32 v31, 0xffff0000, v25
	v_fmac_f32_e32 v20, v26, v26
	v_lshlrev_b32_e32 v28, 16, v24
	v_lshlrev_b32_e32 v30, 16, v25
	v_add_f32_e32 v20, v21, v20
	v_mul_f32_e32 v21, v29, v29
	v_mul_f32_e32 v26, v31, v31
	v_fmac_f32_e32 v21, v28, v28
	v_fmac_f32_e32 v26, v30, v30
	v_add_f32_e32 v21, v21, v26
	v_add_f32_e32 v20, v20, v21
	v_add_f32_e32 v20, v34, v20
	v_mov_b32_e32 v21, v20
	s_nop 1
	v_permlane16_swap_b32_e32 v21, v20
	global_store_dwordx4 v[32:33], v[22:25], off offset:256
	s_waitcnt lgkmcnt(0)
	v_add_f32_e32 v20, v20, v21
	v_mov_b32_e32 v21, v20
	s_nop 1
	v_permlane32_swap_b32_e32 v21, v20
	s_and_saveexec_b64 s[4:5], s[6:7]
	s_cbranch_execz .LBB0_168
	s_waitcnt lgkmcnt(0)
	v_add_f32_e32 v20, v20, v21
	ds_write_b32 v246, v20 offset:2560
.LBB0_168:
	s_or_b64 exec, exec, s[4:5]
	v_lshlrev_b32_e32 v20, 16, v120
	s_waitcnt lgkmcnt(0)
	v_and_b32_e32 v21, 0xffff0000, v120
	v_lshlrev_b32_e32 v22, 16, v121
	v_and_b32_e32 v23, 0xffff0000, v121
	v_pk_add_f32 v[18:19], v[18:19], v[22:23]
	v_pk_add_f32 v[16:17], v[16:17], v[20:21]
	v_lshlrev_b32_e32 v20, 16, v122
	v_and_b32_e32 v21, 0xffff0000, v122
	v_lshlrev_b32_e32 v22, 16, v123
	v_and_b32_e32 v23, 0xffff0000, v123
	v_pk_add_f32 v[22:23], v[14:15], v[22:23]
	v_pk_add_f32 v[14:15], v[12:13], v[20:21]
	v_cvt_pk_bf16_f32 v12, v16, v17
	v_lshl_add_u64 v[16:17], s[18:19], 0, v[202:203]
	v_cvt_pk_bf16_f32 v13, v18, v19
	v_lshl_add_u64 v[16:17], v[192:193], 1, v[16:17]
	v_cvt_pk_bf16_f32 v14, v14, v15
	v_cvt_pk_bf16_f32 v15, v22, v23
	global_store_dwordx4 v[16:17], v[12:15], off
	v_lshlrev_b32_e32 v18, 16, v12
	v_lshlrev_b32_e32 v19, 16, v13
	v_and_b32_e32 v12, 0xffff0000, v12
	v_and_b32_e32 v13, 0xffff0000, v13
	v_mul_f32_e32 v12, v12, v12
	v_mul_f32_e32 v13, v13, v13
	v_lshlrev_b32_e32 v20, 16, v14
	v_and_b32_e32 v14, 0xffff0000, v14
	v_lshlrev_b32_e32 v21, 16, v15
	v_and_b32_e32 v15, 0xffff0000, v15
	v_fmac_f32_e32 v12, v18, v18
	v_fmac_f32_e32 v13, v19, v19
	v_add_f32_e32 v12, v12, v13
	v_mul_f32_e32 v13, v14, v14
	v_mul_f32_e32 v14, v15, v15
	v_fmac_f32_e32 v13, v20, v20
	v_fmac_f32_e32 v14, v21, v21
	v_add_f32_e32 v13, v13, v14
	v_add_f32_e32 v18, v12, v13
	v_lshlrev_b32_e32 v12, 16, v108
	v_and_b32_e32 v13, 0xffff0000, v108
	v_lshlrev_b32_e32 v14, 16, v109
	v_and_b32_e32 v15, 0xffff0000, v109
	v_pk_add_f32 v[8:9], v[8:9], v[12:13]
	v_lshlrev_b32_e32 v12, 16, v110
	v_and_b32_e32 v13, 0xffff0000, v110
	v_pk_add_f32 v[10:11], v[10:11], v[14:15]
	v_lshlrev_b32_e32 v14, 16, v111
	v_and_b32_e32 v15, 0xffff0000, v111
	v_pk_add_f32 v[4:5], v[4:5], v[12:13]
	v_pk_add_f32 v[14:15], v[6:7], v[14:15]
	v_cvt_pk_bf16_f32 v6, v8, v9
	v_cvt_pk_bf16_f32 v7, v10, v11
	v_cvt_pk_bf16_f32 v8, v4, v5
	s_nop 0
	v_and_b32_e32 v5, 0xffff0000, v6
	v_lshlrev_b32_e32 v4, 16, v6
	v_and_b32_e32 v11, 0xffff0000, v7
	v_mul_f32_e32 v5, v5, v5
	v_lshlrev_b32_e32 v10, 16, v7
	v_fmac_f32_e32 v5, v4, v4
	v_mul_f32_e32 v4, v11, v11
	v_cvt_pk_bf16_f32 v9, v14, v15
	v_and_b32_e32 v13, 0xffff0000, v8
	v_and_b32_e32 v15, 0xffff0000, v9
	v_fmac_f32_e32 v4, v10, v10
	v_lshlrev_b32_e32 v12, 16, v8
	v_lshlrev_b32_e32 v14, 16, v9
	v_add_f32_e32 v4, v5, v4
	v_mul_f32_e32 v5, v13, v13
	v_mul_f32_e32 v10, v15, v15
	v_fmac_f32_e32 v5, v12, v12
	v_fmac_f32_e32 v10, v14, v14
	v_add_f32_e32 v5, v5, v10
	v_add_f32_e32 v4, v4, v5
	v_add_f32_e32 v4, v18, v4
	v_mov_b32_e32 v5, v4
	s_nop 1
	v_permlane16_swap_b32_e32 v5, v4
	global_store_dwordx4 v[16:17], v[6:9], off offset:256
	s_waitcnt lgkmcnt(0)
	v_add_f32_e32 v4, v4, v5
	v_mov_b32_e32 v5, v4
	s_nop 1
	v_permlane32_swap_b32_e32 v5, v4
	s_and_saveexec_b64 s[4:5], s[6:7]
	s_cbranch_execz .LBB0_170
	s_waitcnt lgkmcnt(0)
	v_add_f32_e32 v4, v4, v5
	ds_write_b32 v246, v4 offset:2816

; #define LAS __attribute__((address_space(3)))
;     __device__ __forceinline__ void operator()(f32x4 (&acc)[2][2][4][2], const Unit& u, int wr, int wc, int fr, int fq) const {
;         const int row0 = u.pm * BM + wr * 64 + fr, col0 = u.pn * BM + wc * 32 + 8 * fq;
;         LAS float* part = (LAS float*)(lds + PART_OFF); LAS float* rstab = part + 1024;
;         u32x4 bb[2][4][2];
; #pragma unroll
;         for (int ai = 0; ai < 2; ++ai)
; #pragma unroll
;             for (int m = 0; m < 4; ++m)
; #pragma unroll
;                 for (int bj = 0; bj < 2; ++bj) bb[ai][m][bj] = *(const u32x4*)(xb + (size_t)(row0 + ai * HALF + m * 16) * D + col0 + bj * HALF);
; #pragma unroll
;         for (int ai = 0; ai < 2; ++ai)
; #pragma unroll
;             for (int m = 0; m < 4; ++m) { float sq = 0.f;
; #pragma unroll
;                 for (int bj = 0; bj < 2; ++bj) { const u32x4 b = bb[ai][m][bj];
;                     const f32x4 v0 = acc[ai][bj][m][0] + (f32x4){bflo(b.x), bfhi(b.x), bflo(b.y), bfhi(b.y)}, v1 = acc[ai][bj][m][1] + (f32x4){bflo(b.z), bfhi(b.z), bflo(b.w), bfhi(b.w)};
;                     acc[ai][bj][m][0] = v0; acc[ai][bj][m][1] = v1;
;                     sq += ((v0[0] * v0[0] + v0[1] * v0[1]) + (v0[2] * v0[2] + v0[3] * v0[3])) + ((v1[0] * v1[0] + v1[1] * v1[1]) + (v1[2] * v1[2] + v1[3] * v1[3])); }
;                 sq += __shfl_xor(sq, 16); sq += __shfl_xor(sq, 32);
;                 if (fq == 0) part[(ai * HALF + wr * 64 + m * 16 + fr) * 4 + wc] = sq; }
.LBB0_204:
	s_lshl_b32 s51, s14, 8
	v_add_u32_e32 v202, s51, v208
	v_lshl_or_b32 v204, s96, 8, v209
	v_ashrrev_i32_e32 v205, 31, v204
	v_ashrrev_i32_e32 v203, 31, v202
	v_lshl_add_u64 v[130:131], v[204:205], 1, s[18:19]
	v_lshlrev_b64 v[132:133], 11, v[202:203]
	v_lshl_add_u64 v[138:139], v[130:131], 0, v[132:133]
	global_load_dwordx4 v[190:193], v[138:139], off
	global_load_dwordx4 v[186:189], v[138:139], off offset:256
	v_or_b32_e32 v132, 16, v202
	v_ashrrev_i32_e32 v133, 31, v132
	v_lshlrev_b64 v[132:133], 11, v[132:133]
	v_lshl_add_u64 v[132:133], v[130:131], 0, v[132:133]
	global_load_dwordx4 v[182:185], v[132:133], off
	global_load_dwordx4 v[178:181], v[132:133], off offset:256
	v_or_b32_e32 v132, 32, v202
	v_ashrrev_i32_e32 v133, 31, v132
	v_lshlrev_b64 v[132:133], 11, v[132:133]
	v_lshl_add_u64 v[132:133], v[130:131], 0, v[132:133]
	global_load_dwordx4 v[174:177], v[132:133], off
	global_load_dwordx4 v[170:173], v[132:133], off offset:256
	v_or_b32_e32 v132, 48, v202
	v_ashrrev_i32_e32 v133, 31, v132
	v_lshlrev_b64 v[132:133], 11, v[132:133]
	v_lshl_add_u64 v[130:131], v[130:131], 0, v[132:133]
	s_mov_b64 s[4:5], 0x40000
	global_load_dwordx4 v[166:169], v[130:131], off
	global_load_dwordx4 v[162:165], v[130:131], off offset:256
	v_lshl_add_u64 v[130:131], v[138:139], 0, s[4:5]
	s_mov_b32 s4, 0x40000
	v_add_co_u32_e32 v132, vcc, s4, v138
	s_mov_b64 s[4:5], 0x48000
	s_nop 0
	v_addc_co_u32_e32 v133, vcc, 0, v139, vcc
	global_load_dwordx4 v[158:161], v[132:133], off
	global_load_dwordx4 v[154:157], v[130:131], off offset:256
	v_lshl_add_u64 v[130:131], v[138:139], 0, s[4:5]
	s_mov_b32 s4, 0x48000
	v_add_co_u32_e32 v132, vcc, s4, v138
	s_mov_b64 s[4:5], 0x50000
	s_nop 0
	v_addc_co_u32_e32 v133, vcc, 0, v139, vcc
	v_lshl_add_u64 v[134:135], v[138:139], 0, s[4:5]
	s_mov_b32 s4, 0x50000
	v_add_co_u32_e32 v136, vcc, s4, v138
	s_mov_b64 s[4:5], 0x58000
	s_nop 0
	v_addc_co_u32_e32 v137, vcc, 0, v139, vcc
	v_lshl_add_u64 v[140:141], v[138:139], 0, s[4:5]
	s_mov_b32 s4, 0x58000
	v_add_co_u32_e32 v138, vcc, s4, v138
	global_load_dwordx4 v[142:145], v[132:133], off
	s_nop 0
	global_load_dwordx4 v[130:133], v[130:131], off offset:256
	v_addc_co_u32_e32 v139, vcc, 0, v139, vcc
	global_load_dwordx4 v[150:153], v[136:137], off
	s_nop 0
	global_load_dwordx4 v[134:137], v[134:135], off offset:256
	s_nop 0
	global_load_dwordx4 v[146:149], v[138:139], off
	s_nop 0
	global_load_dwordx4 v[138:141], v[140:141], off offset:256
	v_and_b32_e32 v249, 64, v226
	v_xor_b32_e32 v248, 16, v226
	v_add_u32_e32 v249, 64, v249
	v_cmp_lt_i32_e32 vcc, v248, v249
	v_xor_b32_e32 v250, 32, v226
	s_waitcnt vmcnt(0) lgkmcnt(0)
	v_and_b32_e32 v251, 0xffff0000, v190
	v_cndmask_b32_e32 v248, v226, v248, vcc
	v_cmp_lt_i32_e32 vcc, v250, v249
	v_lshlrev_b32_e32 v248, 2, v248
	s_nop 0
	v_cndmask_b32_e32 v249, v226, v250, vcc
	v_lshlrev_b32_e32 v250, 16, v190
	v_lshlrev_b32_e32 v190, 16, v191
	v_and_b32_e32 v191, 0xffff0000, v191
	v_pk_add_f32 v[128:129], v[128:129], v[190:191]
	v_pk_add_f32 v[126:127], v[126:127], v[250:251]
	v_lshlrev_b32_e32 v190, 16, v192
	v_and_b32_e32 v191, 0xffff0000, v192
	v_lshlrev_b32_e32 v192, 16, v193
	v_and_b32_e32 v193, 0xffff0000, v193
	v_pk_add_f32 v[122:123], v[122:123], v[190:191]
	v_mul_f32_e32 v190, v127, v127
	v_mul_f32_e32 v191, v129, v129
	v_pk_add_f32 v[124:125], v[124:125], v[192:193]
	v_fmac_f32_e32 v190, v126, v126
	v_fmac_f32_e32 v191, v128, v128
	v_add_f32_e32 v190, v190, v191
	v_mul_f32_e32 v191, v123, v123
	v_mul_f32_e32 v192, v125, v125
	v_fmac_f32_e32 v191, v122, v122
	v_fmac_f32_e32 v192, v124, v124
	v_add_f32_e32 v191, v191, v192
	v_add_f32_e32 v192, v190, v191
	v_lshlrev_b32_e32 v190, 16, v186
	v_and_b32_e32 v191, 0xffff0000, v186
	v_lshlrev_b32_e32 v186, 16, v187
	v_and_b32_e32 v187, 0xffff0000, v187
	v_pk_add_f32 v[120:121], v[120:121], v[186:187]
	v_pk_add_f32 v[118:119], v[118:119], v[190:191]
	v_lshlrev_b32_e32 v186, 16, v188
	v_and_b32_e32 v187, 0xffff0000, v188
	v_lshlrev_b32_e32 v188, 16, v189
	v_and_b32_e32 v189, 0xffff0000, v189
	v_pk_add_f32 v[114:115], v[114:115], v[186:187]
	v_mul_f32_e32 v186, v119, v119
	v_mul_f32_e32 v187, v121, v121
	v_pk_add_f32 v[116:117], v[116:117], v[188:189]
	v_fmac_f32_e32 v186, v118, v118
	v_fmac_f32_e32 v187, v120, v120
	v_add_f32_e32 v186, v186, v187
	v_mul_f32_e32 v187, v115, v115
	v_mul_f32_e32 v188, v117, v117
	v_fmac_f32_e32 v187, v114, v114
	v_fmac_f32_e32 v188, v116, v116
	v_add_f32_e32 v187, v187, v188
	v_add_f32_e32 v186, v186, v187
	v_add_f32_e32 v186, v192, v186
	v_mov_b32_e32 v187, v186
	s_nop 1
	v_permlane16_swap_b32_e32 v187, v186
	v_lshlrev_b32_e32 v249, 2, v249
	s_waitcnt lgkmcnt(0)
	v_add_f32_e32 v186, v186, v187
	ds_bpermute_b32 v187, v249, v186
	s_and_saveexec_b64 s[4:5], s[6:7]
	s_cbranch_execz .LBB0_206
	s_waitcnt lgkmcnt(0)
	v_add_f32_e32 v186, v186, v187
	ds_write_b32 v247, v186
;     __device__ __forceinline__ void operator()(f32x4 (&acc)[2][2][4][2], const Unit& u, int wr, int wc, int fr, int fq) const {
;     ...
;             for (int m = 0; m < 4; ++m) { float sq = 0.f;
; #pragma unroll
;                 for (int bj = 0; bj < 2; ++bj) { const u32x4 b = bb[ai][m][bj];
;                     const f32x4 v0 = acc[ai][bj][m][0] + (f32x4){bflo(b.x), bfhi(b.x), bflo(b.y), bfhi(b.y)}, v1 = acc[ai][bj][m][1] + (f32x4){bflo(b.z), bfhi(b.z), bflo(b.w), bfhi(b.w)};
;                     acc[ai][bj][m][0] = v0; acc[ai][bj][m][1] = v1;
;                     sq += ((v0[0] * v0[0] + v0[1] * v0[1]) + (v0[2] * v0[2] + v0[3] * v0[3])) + ((v1[0] * v1[0] + v1[1] * v1[1]) + (v1[2] * v1[2] + v1[3] * v1[3])); }
;                 sq += __shfl_xor(sq, 16); sq += __shfl_xor(sq, 32);
;                 if (fq == 0) part[(ai * HALF + wr * 64 + m * 16 + fr) * 4 + wc] = sq; }
.LBB0_206:
	s_or_b64 exec, exec, s[4:5]
	v_lshlrev_b32_e32 v186, 16, v182
	s_waitcnt lgkmcnt(0)
	v_and_b32_e32 v187, 0xffff0000, v182
	v_lshlrev_b32_e32 v182, 16, v183
	v_and_b32_e32 v183, 0xffff0000, v183
	v_pk_add_f32 v[112:113], v[112:113], v[182:183]
	v_pk_add_f32 v[110:111], v[110:111], v[186:187]
	v_lshlrev_b32_e32 v182, 16, v184
	v_and_b32_e32 v183, 0xffff0000, v184
	v_lshlrev_b32_e32 v184, 16, v185
	v_and_b32_e32 v185, 0xffff0000, v185
	v_pk_add_f32 v[106:107], v[106:107], v[182:183]
	v_mul_f32_e32 v182, v111, v111
	v_mul_f32_e32 v183, v113, v113
	v_pk_add_f32 v[108:109], v[108:109], v[184:185]
	v_fmac_f32_e32 v182, v110, v110
	v_fmac_f32_e32 v183, v112, v112
	v_add_f32_e32 v182, v182, v183
	v_mul_f32_e32 v183, v107, v107
	v_mul_f32_e32 v184, v109, v109
	v_fmac_f32_e32 v183, v106, v106
	v_fmac_f32_e32 v184, v108, v108
	v_add_f32_e32 v183, v183, v184
	v_add_f32_e32 v184, v182, v183
	v_lshlrev_b32_e32 v182, 16, v178
	v_and_b32_e32 v183, 0xffff0000, v178
	v_lshlrev_b32_e32 v178, 16, v179
	v_and_b32_e32 v179, 0xffff0000, v179
	v_pk_add_f32 v[104:105], v[104:105], v[178:179]
	v_pk_add_f32 v[102:103], v[102:103], v[182:183]
	v_lshlrev_b32_e32 v178, 16, v180
	v_and_b32_e32 v179, 0xffff0000, v180
	v_lshlrev_b32_e32 v180, 16, v181
	v_and_b32_e32 v181, 0xffff0000, v181
	v_pk_add_f32 v[98:99], v[98:99], v[178:179]
	v_mul_f32_e32 v178, v103, v103
	v_mul_f32_e32 v179, v105, v105
	v_pk_add_f32 v[100:101], v[100:101], v[180:181]
	v_fmac_f32_e32 v178, v102, v102
	v_fmac_f32_e32 v179, v104, v104
	v_add_f32_e32 v178, v178, v179
	v_mul_f32_e32 v179, v99, v99
	v_mul_f32_e32 v180, v101, v101
	v_fmac_f32_e32 v179, v98, v98
	v_fmac_f32_e32 v180, v100, v100
	v_add_f32_e32 v179, v179, v180
	v_add_f32_e32 v178, v178, v179
	v_add_f32_e32 v178, v184, v178
	v_mov_b32_e32 v179, v178
	s_nop 1
	v_permlane16_swap_b32_e32 v179, v178
	s_waitcnt lgkmcnt(0)
	v_add_f32_e32 v178, v178, v179
	ds_bpermute_b32 v179, v249, v178
	s_and_saveexec_b64 s[4:5], s[6:7]
	s_cbranch_execz .LBB0_208
	s_waitcnt lgkmcnt(0)
	v_add_f32_e32 v178, v178, v179
	ds_write_b32 v247, v178 offset:256
.LBB0_208:
	s_or_b64 exec, exec, s[4:5]
	v_lshlrev_b32_e32 v178, 16, v174
	s_waitcnt lgkmcnt(0)
	v_and_b32_e32 v179, 0xffff0000, v174
	v_lshlrev_b32_e32 v174, 16, v175
	v_and_b32_e32 v175, 0xffff0000, v175
	v_pk_add_f32 v[96:97], v[96:97], v[174:175]
	v_pk_add_f32 v[94:95], v[94:95], v[178:179]
	v_lshlrev_b32_e32 v174, 16, v176
	v_and_b32_e32 v175, 0xffff0000, v176
	v_lshlrev_b32_e32 v176, 16, v177
	v_and_b32_e32 v177, 0xffff0000, v177
	v_pk_add_f32 v[90:91], v[90:91], v[174:175]
	v_mul_f32_e32 v174, v95, v95
	v_mul_f32_e32 v175, v97, v97
	v_pk_add_f32 v[92:93], v[92:93], v[176:177]
	v_fmac_f32_e32 v174, v94, v94
	v_fmac_f32_e32 v175, v96, v96
	v_add_f32_e32 v174, v174, v175
	v_mul_f32_e32 v175, v91, v91
	v_mul_f32_e32 v176, v93, v93
	v_fmac_f32_e32 v175, v90, v90
	v_fmac_f32_e32 v176, v92, v92
	v_add_f32_e32 v175, v175, v176
	v_add_f32_e32 v176, v174, v175
	v_lshlrev_b32_e32 v174, 16, v170
	v_and_b32_e32 v175, 0xffff0000, v170
	v_lshlrev_b32_e32 v170, 16, v171
	v_and_b32_e32 v171, 0xffff0000, v171
	v_pk_add_f32 v[88:89], v[88:89], v[170:171]
	v_pk_add_f32 v[86:87], v[86:87], v[174:175]
	v_lshlrev_b32_e32 v170, 16, v172
	v_and_b32_e32 v171, 0xffff0000, v172
	v_lshlrev_b32_e32 v172, 16, v173
	v_and_b32_e32 v173, 0xffff0000, v173
	v_pk_add_f32 v[82:83], v[82:83], v[170:171]
	v_mul_f32_e32 v170, v87, v87
	v_mul_f32_e32 v171, v89, v89
	v_pk_add_f32 v[84:85], v[84:85], v[172:173]
	v_fmac_f32_e32 v170, v86, v86
	v_fmac_f32_e32 v171, v88, v88
	v_add_f32_e32 v170, v170, v171
	v_mul_f32_e32 v171, v83, v83
	v_mul_f32_e32 v172, v85, v85
	v_fmac_f32_e32 v171, v82, v82
	v_fmac_f32_e32 v172, v84, v84
	v_add_f32_e32 v171, v171, v172
	v_add_f32_e32 v170, v170, v171
	v_add_f32_e32 v170, v176, v170
	v_mov_b32_e32 v171, v170
	s_nop 1
	v_permlane16_swap_b32_e32 v171, v170
	s_waitcnt lgkmcnt(0)
	v_add_f32_e32 v170, v170, v171
	ds_bpermute_b32 v171, v249, v170
	s_and_saveexec_b64 s[4:5], s[6:7]
	s_cbranch_execz .LBB0_210
	s_waitcnt lgkmcnt(0)
	v_add_f32_e32 v170, v170, v171
	ds_write_b32 v247, v170 offset:512
.LBB0_210:
	s_or_b64 exec, exec, s[4:5]
	v_lshlrev_b32_e32 v170, 16, v166
	s_waitcnt lgkmcnt(0)
	v_and_b32_e32 v171, 0xffff0000, v166
	v_lshlrev_b32_e32 v166, 16, v167
	v_and_b32_e32 v167, 0xffff0000, v167
	v_pk_add_f32 v[80:81], v[80:81], v[166:167]
	v_pk_add_f32 v[78:79], v[78:79], v[170:171]
	v_lshlrev_b32_e32 v166, 16, v168
	v_and_b32_e32 v167, 0xffff0000, v168
	v_lshlrev_b32_e32 v168, 16, v169
	v_and_b32_e32 v169, 0xffff0000, v169
	v_pk_add_f32 v[74:75], v[74:75], v[166:167]
	v_mul_f32_e32 v166, v79, v79
	v_mul_f32_e32 v167, v81, v81
	v_pk_add_f32 v[76:77], v[76:77], v[168:169]
	v_fmac_f32_e32 v166, v78, v78
	v_fmac_f32_e32 v167, v80, v80
	v_add_f32_e32 v166, v166, v167
	v_mul_f32_e32 v167, v75, v75
	v_mul_f32_e32 v168, v77, v77
	v_fmac_f32_e32 v167, v74, v74
	v_fmac_f32_e32 v168, v76, v76
	v_add_f32_e32 v167, v167, v168
	v_add_f32_e32 v168, v166, v167
	v_lshlrev_b32_e32 v166, 16, v162
	v_and_b32_e32 v167, 0xffff0000, v162
	v_lshlrev_b32_e32 v162, 16, v163
	v_and_b32_e32 v163, 0xffff0000, v163
	v_pk_add_f32 v[72:73], v[72:73], v[162:163]
	v_pk_add_f32 v[70:71], v[70:71], v[166:167]
	v_lshlrev_b32_e32 v162, 16, v164
	v_and_b32_e32 v163, 0xffff0000, v164
	v_lshlrev_b32_e32 v164, 16, v165
	v_and_b32_e32 v165, 0xffff0000, v165
	v_pk_add_f32 v[66:67], v[66:67], v[162:163]
	v_mul_f32_e32 v162, v71, v71
	v_mul_f32_e32 v163, v73, v73
	v_pk_add_f32 v[68:69], v[68:69], v[164:165]
	v_fmac_f32_e32 v162, v70, v70
	v_fmac_f32_e32 v163, v72, v72
	v_add_f32_e32 v162, v162, v163
	v_mul_f32_e32 v163, v67, v67
	v_mul_f32_e32 v164, v69, v69
	v_fmac_f32_e32 v163, v66, v66
	v_fmac_f32_e32 v164, v68, v68
	v_add_f32_e32 v163, v163, v164
	v_add_f32_e32 v162, v162, v163
	v_add_f32_e32 v162, v168, v162
	v_mov_b32_e32 v163, v162
	s_nop 1
	v_permlane16_swap_b32_e32 v163, v162
	s_waitcnt lgkmcnt(0)
	v_add_f32_e32 v162, v162, v163
	ds_bpermute_b32 v163, v249, v162
	s_and_saveexec_b64 s[4:5], s[6:7]
	s_cbranch_execz .LBB0_212
	s_waitcnt lgkmcnt(0)
	v_add_f32_e32 v162, v162, v163
	ds_write_b32 v247, v162 offset:768
;     __device__ __forceinline__ void operator()(f32x4 (&acc)[2][2][4][2], const Unit& u, int wr, int wc, int fr, int fq) const {
;     ...
;             for (int m = 0; m < 4; ++m) { float sq = 0.f;
; #pragma unroll
;                 for (int bj = 0; bj < 2; ++bj) { const u32x4 b = bb[ai][m][bj];
;                     const f32x4 v0 = acc[ai][bj][m][0] + (f32x4){bflo(b.x), bfhi(b.x), bflo(b.y), bfhi(b.y)}, v1 = acc[ai][bj][m][1] + (f32x4){bflo(b.z), bfhi(b.z), bflo(b.w), bfhi(b.w)};
;                     acc[ai][bj][m][0] = v0; acc[ai][bj][m][1] = v1;
;                     sq += ((v0[0] * v0[0] + v0[1] * v0[1]) + (v0[2] * v0[2] + v0[3] * v0[3])) + ((v1[0] * v1[0] + v1[1] * v1[1]) + (v1[2] * v1[2] + v1[3] * v1[3])); }
;                 sq += __shfl_xor(sq, 16); sq += __shfl_xor(sq, 32);
;                 if (fq == 0) part[(ai * HALF + wr * 64 + m * 16 + fr) * 4 + wc] = sq; }
.LBB0_212:
	s_or_b64 exec, exec, s[4:5]
	v_lshlrev_b32_e32 v162, 16, v158
	s_waitcnt lgkmcnt(0)
	v_and_b32_e32 v163, 0xffff0000, v158
	v_lshlrev_b32_e32 v158, 16, v159
	v_and_b32_e32 v159, 0xffff0000, v159
	v_pk_add_f32 v[64:65], v[64:65], v[158:159]
	v_pk_add_f32 v[62:63], v[62:63], v[162:163]
	v_lshlrev_b32_e32 v158, 16, v160
	v_and_b32_e32 v159, 0xffff0000, v160
	v_lshlrev_b32_e32 v160, 16, v161
	v_and_b32_e32 v161, 0xffff0000, v161
	v_pk_add_f32 v[58:59], v[58:59], v[158:159]
	v_mul_f32_e32 v158, v63, v63
	v_mul_f32_e32 v159, v65, v65
	v_pk_add_f32 v[60:61], v[60:61], v[160:161]
	v_fmac_f32_e32 v158, v62, v62
	v_fmac_f32_e32 v159, v64, v64
	v_add_f32_e32 v158, v158, v159
	v_mul_f32_e32 v159, v59, v59
	v_mul_f32_e32 v160, v61, v61
	v_fmac_f32_e32 v159, v58, v58
	v_fmac_f32_e32 v160, v60, v60
	v_add_f32_e32 v159, v159, v160
	v_add_f32_e32 v160, v158, v159
	v_lshlrev_b32_e32 v158, 16, v154
	v_and_b32_e32 v159, 0xffff0000, v154
	v_lshlrev_b32_e32 v154, 16, v155
	v_and_b32_e32 v155, 0xffff0000, v155
	v_pk_add_f32 v[56:57], v[56:57], v[154:155]
	v_pk_add_f32 v[54:55], v[54:55], v[158:159]
	v_lshlrev_b32_e32 v154, 16, v156
	v_and_b32_e32 v155, 0xffff0000, v156
	v_lshlrev_b32_e32 v156, 16, v157
	v_and_b32_e32 v157, 0xffff0000, v157
	v_pk_add_f32 v[50:51], v[50:51], v[154:155]
	v_mul_f32_e32 v154, v55, v55
	v_mul_f32_e32 v155, v57, v57
	v_pk_add_f32 v[52:53], v[52:53], v[156:157]
	v_fmac_f32_e32 v154, v54, v54
	v_fmac_f32_e32 v155, v56, v56
	v_add_f32_e32 v154, v154, v155
	v_mul_f32_e32 v155, v51, v51
	v_mul_f32_e32 v156, v53, v53
	v_fmac_f32_e32 v155, v50, v50
	v_fmac_f32_e32 v156, v52, v52
	v_add_f32_e32 v155, v155, v156
	v_add_f32_e32 v154, v154, v155
	v_add_f32_e32 v154, v160, v154
	v_mov_b32_e32 v155, v154
	s_nop 1
	v_permlane16_swap_b32_e32 v155, v154
	s_waitcnt lgkmcnt(0)
	v_add_f32_e32 v154, v154, v155
	ds_bpermute_b32 v155, v249, v154
	s_and_saveexec_b64 s[4:5], s[6:7]
	s_cbranch_execz .LBB0_214
	s_waitcnt lgkmcnt(0)
	v_add_f32_e32 v154, v154, v155
	ds_write_b32 v247, v154 offset:2048
.LBB0_214:
	s_or_b64 exec, exec, s[4:5]
	v_lshlrev_b32_e32 v154, 16, v142
	s_waitcnt lgkmcnt(0)
	v_and_b32_e32 v155, 0xffff0000, v142
	v_lshlrev_b32_e32 v142, 16, v143
	v_and_b32_e32 v143, 0xffff0000, v143
	v_pk_add_f32 v[48:49], v[48:49], v[142:143]
	v_pk_add_f32 v[46:47], v[46:47], v[154:155]
	v_lshlrev_b32_e32 v142, 16, v144
	v_and_b32_e32 v143, 0xffff0000, v144
	v_lshlrev_b32_e32 v144, 16, v145
	v_and_b32_e32 v145, 0xffff0000, v145
	v_pk_add_f32 v[42:43], v[42:43], v[142:143]
	v_mul_f32_e32 v142, v47, v47
	v_mul_f32_e32 v143, v49, v49
	v_pk_add_f32 v[44:45], v[44:45], v[144:145]
	v_fmac_f32_e32 v142, v46, v46
	v_fmac_f32_e32 v143, v48, v48
	v_add_f32_e32 v142, v142, v143
	v_mul_f32_e32 v143, v43, v43
	v_mul_f32_e32 v144, v45, v45
	v_fmac_f32_e32 v143, v42, v42
	v_fmac_f32_e32 v144, v44, v44
	v_add_f32_e32 v143, v143, v144
	v_add_f32_e32 v144, v142, v143
	v_lshlrev_b32_e32 v142, 16, v130
	v_and_b32_e32 v143, 0xffff0000, v130
	v_lshlrev_b32_e32 v130, 16, v131
	v_and_b32_e32 v131, 0xffff0000, v131
	v_pk_add_f32 v[40:41], v[40:41], v[130:131]
	v_pk_add_f32 v[38:39], v[38:39], v[142:143]
	v_lshlrev_b32_e32 v130, 16, v132
	v_and_b32_e32 v131, 0xffff0000, v132
	v_lshlrev_b32_e32 v132, 16, v133
	v_and_b32_e32 v133, 0xffff0000, v133
	v_pk_add_f32 v[34:35], v[34:35], v[130:131]
	v_mul_f32_e32 v130, v39, v39
	v_mul_f32_e32 v131, v41, v41
	v_pk_add_f32 v[36:37], v[36:37], v[132:133]
	v_fmac_f32_e32 v130, v38, v38
	v_fmac_f32_e32 v131, v40, v40
	v_add_f32_e32 v130, v130, v131
	v_mul_f32_e32 v131, v35, v35
	v_mul_f32_e32 v132, v37, v37
	v_fmac_f32_e32 v131, v34, v34
	v_fmac_f32_e32 v132, v36, v36
	v_add_f32_e32 v131, v131, v132
	v_add_f32_e32 v130, v130, v131
	v_add_f32_e32 v130, v144, v130
	v_mov_b32_e32 v131, v130
	s_nop 1
	v_permlane16_swap_b32_e32 v131, v130
	s_waitcnt lgkmcnt(0)
	v_add_f32_e32 v130, v130, v131
	ds_bpermute_b32 v131, v249, v130
	s_and_saveexec_b64 s[4:5], s[6:7]
	s_cbranch_execz .LBB0_216
	s_waitcnt lgkmcnt(0)
	v_add_f32_e32 v130, v130, v131
	ds_write_b32 v247, v130 offset:2304
;     __device__ __forceinline__ void operator()(f32x4 (&acc)[2][2][4][2], const Unit& u, int wr, int wc, int fr, int fq) const {
;     ...
;             for (int m = 0; m < 4; ++m) { float sq = 0.f;
; #pragma unroll
;                 for (int bj = 0; bj < 2; ++bj) { const u32x4 b = bb[ai][m][bj];
;                     const f32x4 v0 = acc[ai][bj][m][0] + (f32x4){bflo(b.x), bfhi(b.x), bflo(b.y), bfhi(b.y)}, v1 = acc[ai][bj][m][1] + (f32x4){bflo(b.z), bfhi(b.z), bflo(b.w), bfhi(b.w)};
;                     acc[ai][bj][m][0] = v0; acc[ai][bj][m][1] = v1;
;                     sq += ((v0[0] * v0[0] + v0[1] * v0[1]) + (v0[2] * v0[2] + v0[3] * v0[3])) + ((v1[0] * v1[0] + v1[1] * v1[1]) + (v1[2] * v1[2] + v1[3] * v1[3])); }
;                 sq += __shfl_xor(sq, 16); sq += __shfl_xor(sq, 32);
;                 if (fq == 0) part[(ai * HALF + wr * 64 + m * 16 + fr) * 4 + wc] = sq; }
.LBB0_216:
	s_or_b64 exec, exec, s[4:5]
	v_lshlrev_b32_e32 v130, 16, v150
	s_waitcnt lgkmcnt(0)
	v_and_b32_e32 v131, 0xffff0000, v150
	v_lshlrev_b32_e32 v132, 16, v151
	v_and_b32_e32 v133, 0xffff0000, v151
	v_pk_add_f32 v[32:33], v[32:33], v[132:133]
	v_pk_add_f32 v[30:31], v[30:31], v[130:131]
	v_lshlrev_b32_e32 v130, 16, v152
	v_and_b32_e32 v131, 0xffff0000, v152
	v_lshlrev_b32_e32 v132, 16, v153
	v_and_b32_e32 v133, 0xffff0000, v153
	v_pk_add_f32 v[26:27], v[26:27], v[130:131]
	v_mul_f32_e32 v130, v31, v31
	v_mul_f32_e32 v131, v33, v33
	v_pk_add_f32 v[28:29], v[28:29], v[132:133]
	v_fmac_f32_e32 v130, v30, v30
	v_fmac_f32_e32 v131, v32, v32
	v_add_f32_e32 v130, v130, v131
	v_mul_f32_e32 v131, v27, v27
	v_mul_f32_e32 v132, v29, v29
	v_fmac_f32_e32 v131, v26, v26
	v_fmac_f32_e32 v132, v28, v28
	v_add_f32_e32 v131, v131, v132
	v_add_f32_e32 v142, v130, v131
	v_lshlrev_b32_e32 v130, 16, v134
	v_and_b32_e32 v131, 0xffff0000, v134
	v_lshlrev_b32_e32 v132, 16, v135
	v_and_b32_e32 v133, 0xffff0000, v135
	v_pk_add_f32 v[24:25], v[24:25], v[132:133]
	v_pk_add_f32 v[22:23], v[22:23], v[130:131]
	v_lshlrev_b32_e32 v130, 16, v136
	v_and_b32_e32 v131, 0xffff0000, v136
	v_lshlrev_b32_e32 v132, 16, v137
	v_and_b32_e32 v133, 0xffff0000, v137
	v_pk_add_f32 v[18:19], v[18:19], v[130:131]
	v_mul_f32_e32 v130, v23, v23
	v_mul_f32_e32 v131, v25, v25
	v_pk_add_f32 v[20:21], v[20:21], v[132:133]
	v_fmac_f32_e32 v130, v22, v22
	v_fmac_f32_e32 v131, v24, v24
	v_add_f32_e32 v130, v130, v131
	v_mul_f32_e32 v131, v19, v19
	v_mul_f32_e32 v132, v21, v21
	v_fmac_f32_e32 v131, v18, v18
	v_fmac_f32_e32 v132, v20, v20
	v_add_f32_e32 v131, v131, v132
	v_add_f32_e32 v130, v130, v131
	v_add_f32_e32 v130, v142, v130
	v_mov_b32_e32 v131, v130
	s_nop 1
	v_permlane16_swap_b32_e32 v131, v130
	s_waitcnt lgkmcnt(0)
	v_add_f32_e32 v130, v130, v131
	ds_bpermute_b32 v131, v249, v130
	s_and_saveexec_b64 s[4:5], s[6:7]
	s_cbranch_execz .LBB0_218
	s_waitcnt lgkmcnt(0)
	v_add_f32_e32 v130, v130, v131
	ds_write_b32 v247, v130 offset:2560
.LBB0_218:
	s_or_b64 exec, exec, s[4:5]
	v_lshlrev_b32_e32 v130, 16, v146
	s_waitcnt lgkmcnt(0)
	v_and_b32_e32 v131, 0xffff0000, v146
	v_lshlrev_b32_e32 v132, 16, v147
	v_and_b32_e32 v133, 0xffff0000, v147
	v_pk_add_f32 v[132:133], v[16:17], v[132:133]
	v_pk_add_f32 v[136:137], v[14:15], v[130:131]
	v_lshlrev_b32_e32 v14, 16, v148
	v_and_b32_e32 v15, 0xffff0000, v148
	v_lshlrev_b32_e32 v16, 16, v149
	v_and_b32_e32 v17, 0xffff0000, v149
	v_pk_add_f32 v[134:135], v[10:11], v[14:15]
	v_mul_f32_e32 v10, v137, v137
	v_mul_f32_e32 v11, v133, v133
	v_pk_add_f32 v[130:131], v[12:13], v[16:17]
	v_fmac_f32_e32 v10, v136, v136
	v_fmac_f32_e32 v11, v132, v132
	v_add_f32_e32 v10, v10, v11
	v_mul_f32_e32 v11, v135, v135
	v_mul_f32_e32 v12, v131, v131
	v_fmac_f32_e32 v11, v134, v134
	v_fmac_f32_e32 v12, v130, v130
	v_add_f32_e32 v11, v11, v12
	v_add_f32_e32 v14, v10, v11
	v_lshlrev_b32_e32 v10, 16, v138
	v_and_b32_e32 v11, 0xffff0000, v138
	v_lshlrev_b32_e32 v12, 16, v139
	v_and_b32_e32 v13, 0xffff0000, v139
	v_pk_add_f32 v[138:139], v[8:9], v[12:13]
	v_pk_add_f32 v[142:143], v[6:7], v[10:11]
	v_lshlrev_b32_e32 v6, 16, v140
	v_and_b32_e32 v7, 0xffff0000, v140
	v_lshlrev_b32_e32 v8, 16, v141
	v_and_b32_e32 v9, 0xffff0000, v141
	v_pk_add_f32 v[144:145], v[2:3], v[6:7]
	v_mul_f32_e32 v2, v143, v143
	v_mul_f32_e32 v3, v139, v139
	v_pk_add_f32 v[140:141], v[4:5], v[8:9]
	v_fmac_f32_e32 v2, v142, v142
	v_fmac_f32_e32 v3, v138, v138
	v_add_f32_e32 v2, v2, v3
	v_mul_f32_e32 v3, v145, v145
	v_mul_f32_e32 v4, v141, v141
	v_fmac_f32_e32 v3, v144, v144
	v_fmac_f32_e32 v4, v140, v140
	v_add_f32_e32 v3, v3, v4
	v_add_f32_e32 v2, v2, v3
	v_add_f32_e32 v2, v14, v2
	v_mov_b32_e32 v3, v2
	s_nop 1
	v_permlane16_swap_b32_e32 v3, v2
	s_waitcnt lgkmcnt(0)
	v_add_f32_e32 v2, v2, v3
	ds_bpermute_b32 v3, v249, v2
	s_and_saveexec_b64 s[4:5], s[6:7]
	s_cbranch_execz .LBB0_220
	s_waitcnt lgkmcnt(0)
	v_add_f32_e32 v2, v2, v3
	ds_write_b32 v247, v2 offset:2816

; #define LAS __attribute__((address_space(3)))
; __device__ __forceinline__ unsigned cvt_pk_bf16(float lo, float hi) { unsigned r; asm volatile("v_cvt_pk_bf16_f32 %0, %1, %2" : "=v"(r) : "v"(lo), "v"(hi)); return r; }
; __device__ __forceinline__ f32x2 gelu_pk(f32x2 v) {
;     const f32x2 av = __builtin_elementwise_abs(v), d = av * 0.2316418882f + 1.0f;
;     f32x2 t; t.x = __builtin_amdgcn_rcpf(d.x); t.y = __builtin_amdgcn_rcpf(d.y);
;     f32x2 q = t * 0.5307027145f + (-0.7265760135f); q = q * t + 0.7107068705f; q = q * t + (-0.142248368f); q = q * t + 0.127414796f; q = q * t;
;     const f32x2 s = (v * v) * (-0.72134752044f);
;     f32x2 e; e.x = __builtin_amdgcn_exp2f(s.x); e.y = __builtin_amdgcn_exp2f(s.y);
;     const f32x2 m = v * (q * e), r = v - m;
;     f32x2 o; o.x = v.x < 0.f ? m.x : r.x; o.y = v.y < 0.f ? m.y : r.y; return o;
; }
;     __device__ __forceinline__ void operator()(const f32x4 (&acc)[2][2][4][2], const Unit& u, int wr, int wc, int fr, int fq) const {
;         const int row0 = u.pm * BM + wr * 64 + fr, col0 = u.pn * BM + wc * 32 + 8 * fq; const bool isv = u.pn >= 4;
;         LAS float* part = (LAS float*)(lds + PART_OFF);
;         float rsv[2][4]; rstd8(ss, row0, rsv);
; #pragma unroll
;         for (int ai = 0; ai < 2; ++ai)
; #pragma unroll
;             for (int m = 0; m < 4; ++m) { const int row = row0 + ai * HALF + m * 16; const float rs = rsv[ai][m]; bf16_t* rowp = O + (size_t)row * ldc + col0; float s1 = 0.f, s2 = 0.f;
; #pragma unroll
;                 for (int bj = 0; bj < 2; ++bj) { f32x4 v0 = acc[ai][bj][m][0] * rs, v1 = acc[ai][bj][m][1] * rs;
;                     const f32x2 a = gelu_pk((f32x2){v0[0], v0[1]}), b = gelu_pk((f32x2){v0[2], v0[3]}), c = gelu_pk((f32x2){v1[0], v1[1]}), d = gelu_pk((f32x2){v1[2], v1[3]});
;                     s1 += ((a.x + a.y) + (b.x + b.y)) + ((c.x + c.y) + (d.x + d.y));
;                     s2 += ((a.x * a.x + a.y * a.y) + (b.x * b.x + b.y * b.y)) + ((c.x * c.x + c.y * c.y) + (d.x * d.x + d.y * d.y));
;                     u32x4 w; w.x = cvt_pk_bf16(a.x, a.y); w.y = cvt_pk_bf16(b.x, b.y); w.z = cvt_pk_bf16(c.x, c.y); w.w = cvt_pk_bf16(d.x, d.y);
;                     *(u32x4*)(rowp + bj * HALF) = w; }
.LBB0_352:
	s_lshl_b32 s27, s10, 8
	v_add_u32_e32 v190, s27, v184
	v_ashrrev_i32_e32 v191, 31, v190
	v_lshl_add_u64 v[34:35], v[190:191], 4, s[22:23]
	global_load_dwordx4 v[176:179], v[34:35], off
	v_or_b32_e32 v174, 16, v190
	v_or_b32_e32 v172, 32, v190
	v_or_b32_e32 v170, 48, v190
	v_add_u32_e32 v168, 0x80, v190
	v_add_u32_e32 v166, 0x90, v190
	v_add_u32_e32 v164, 0xa0, v190
	v_add_u32_e32 v162, 0xb0, v190
	s_mov_b32 s4, 0xbf3a00e3
	v_ashrrev_i32_e32 v175, 31, v174
	v_lshl_add_u64 v[34:35], v[174:175], 4, s[22:23]
	v_ashrrev_i32_e32 v173, 31, v172
	global_load_dwordx4 v[146:149], v[34:35], off
	v_lshl_add_u64 v[34:35], v[172:173], 4, s[22:23]
	v_ashrrev_i32_e32 v171, 31, v170
	global_load_dwordx4 v[126:129], v[34:35], off
	v_lshl_add_u64 v[34:35], v[170:171], 4, s[22:23]
	v_ashrrev_i32_e32 v169, 31, v168
	global_load_dwordx4 v[110:113], v[34:35], off
	v_lshl_add_u64 v[34:35], v[168:169], 4, s[22:23]
	v_ashrrev_i32_e32 v167, 31, v166
	global_load_dwordx4 v[94:97], v[34:35], off
	v_lshl_add_u64 v[34:35], v[166:167], 4, s[22:23]
	v_ashrrev_i32_e32 v165, 31, v164
	global_load_dwordx4 v[74:77], v[34:35], off
	v_lshl_add_u64 v[34:35], v[164:165], 4, s[22:23]
	v_ashrrev_i32_e32 v163, 31, v162
	global_load_dwordx4 v[54:57], v[34:35], off
	v_lshl_add_u64 v[34:35], v[162:163], 4, s[22:23]
	global_load_dwordx4 v[34:37], v[34:35], off
	v_lshl_or_b32 v160, s46, 8, v185
	v_ashrrev_i32_e32 v161, 31, v160
	s_cmp_gt_i32 s46, 3
	s_cselect_b64 s[36:37], -1, 0
	s_cmp_lt_i32 s46, 4
	s_waitcnt vmcnt(0) lgkmcnt(0)
	v_mov_b32_e32 v192, v177
	v_mov_b32_e32 v193, v178
	v_mov_b32_e32 v177, v179
	v_pk_add_f32 v[176:177], v[192:193], v[176:177]
	s_nop 0
	v_add_f32_e32 v0, v176, v177
	v_fmamk_f32 v0, v0, 0x3a800000, v224
	v_rsq_f32_e32 v0, v0
	v_lshlrev_b64 v[176:177], 12, v[190:191]
	v_lshl_add_u64 v[176:177], s[20:21], 0, v[176:177]
	v_lshl_add_u64 v[176:177], v[160:161], 1, v[176:177]
	v_pk_mul_f32 v[178:179], v[154:155], v[0:1] op_sel_hi:[1,0]
	v_pk_mul_f32 v[154:155], v[150:151], v[0:1] op_sel_hi:[1,0]
	v_and_b32_e32 v151, 0x7fffffff, v179
	v_and_b32_e32 v150, 0x7fffffff, v178
	v_pk_fma_f32 v[150:151], v[150:151], s[64:65], 1.0 op_sel_hi:[1,0,0]
	v_pk_mul_f32 v[202:203], v[178:179], v[178:179]
	v_rcp_f32_e32 v190, v150
	v_rcp_f32_e32 v191, v151
	v_mov_b64_e32 v[150:151], s[4:5]
	v_pk_mul_f32 v[202:203], v[202:203], s[76:77] op_sel_hi:[1,0]
	v_cmp_gt_f32_e32 vcc, 0, v178
	v_pk_fma_f32 v[192:193], v[190:191], s[66:67], v[150:151] op_sel_hi:[1,0,0]
	v_exp_f32_e32 v202, v202
	v_pk_fma_f32 v[192:193], v[190:191], v[192:193], s[70:71] op_sel_hi:[1,1,0]
	v_exp_f32_e32 v203, v203
	v_pk_fma_f32 v[192:193], v[190:191], v[192:193], s[72:73] op_sel_hi:[1,1,0]
	v_pk_mul_f32 v[156:157], v[156:157], v[0:1] op_sel_hi:[1,0]
	v_pk_fma_f32 v[192:193], v[190:191], v[192:193], s[74:75] op_sel_hi:[1,1,0]
	v_pk_mul_f32 v[152:153], v[152:153], v[0:1] op_sel_hi:[1,0]
	v_pk_mul_f32 v[190:191], v[190:191], v[192:193]
	v_pk_mul_f32 v[192:193], v[156:157], v[156:157]
	v_pk_mul_f32 v[190:191], v[202:203], v[190:191]
	v_pk_mul_f32 v[192:193], v[192:193], s[76:77] op_sel_hi:[1,0]
	v_pk_mul_f32 v[202:203], v[178:179], v[190:191]
	v_pk_fma_f32 v[190:191], v[178:179], v[190:191], v[178:179] neg_lo:[1,0,0] neg_hi:[1,0,0]
	v_exp_f32_e32 v192, v192
	v_cndmask_b32_e32 v178, v190, v202, vcc
	v_cmp_gt_f32_e32 vcc, 0, v179
	v_and_b32_e32 v190, 0x7fffffff, v156
	v_exp_f32_e32 v193, v193
	v_cndmask_b32_e32 v179, v191, v203, vcc
	v_and_b32_e32 v191, 0x7fffffff, v157
	v_pk_fma_f32 v[190:191], v[190:191], s[64:65], 1.0 op_sel_hi:[1,0,0]
	v_cmp_gt_f32_e32 vcc, 0, v156
	v_rcp_f32_e32 v190, v190
	v_rcp_f32_e32 v191, v191
	v_pk_mul_f32 v[142:143], v[142:143], v[0:1] op_sel_hi:[1,0]
	v_pk_mul_f32 v[144:145], v[144:145], v[0:1] op_sel_hi:[1,0]
	v_pk_mul_f32 v[140:141], v[140:141], v[0:1] op_sel_hi:[1,0]
	v_pk_fma_f32 v[202:203], v[190:191], s[66:67], v[150:151] op_sel_hi:[1,0,0]
	s_nop 0
	v_pk_fma_f32 v[202:203], v[190:191], v[202:203], s[70:71] op_sel_hi:[1,1,0]
	s_nop 0
	v_pk_fma_f32 v[202:203], v[190:191], v[202:203], s[72:73] op_sel_hi:[1,1,0]
	s_nop 0
	v_pk_fma_f32 v[202:203], v[190:191], v[202:203], s[74:75] op_sel_hi:[1,1,0]
	s_nop 0
	v_pk_mul_f32 v[190:191], v[190:191], v[202:203]
	v_pk_mul_f32 v[202:203], v[154:155], v[154:155]
	v_pk_mul_f32 v[190:191], v[192:193], v[190:191]
	v_pk_mul_f32 v[202:203], v[202:203], s[76:77] op_sel_hi:[1,0]
	v_pk_mul_f32 v[192:193], v[156:157], v[190:191]
	v_pk_fma_f32 v[190:191], v[156:157], v[190:191], v[156:157] neg_lo:[1,0,0] neg_hi:[1,0,0]
	v_and_b32_e32 v156, 0x7fffffff, v154
	v_cndmask_b32_e32 v189, v190, v192, vcc
	v_cmp_gt_f32_e32 vcc, 0, v157
	v_and_b32_e32 v157, 0x7fffffff, v155
	v_pk_fma_f32 v[156:157], v[156:157], s[64:65], 1.0 op_sel_hi:[1,0,0]
	v_cndmask_b32_e32 v190, v191, v193, vcc
	v_rcp_f32_e32 v156, v156
	v_rcp_f32_e32 v157, v157
	v_exp_f32_e32 v202, v202
	v_exp_f32_e32 v203, v203
	v_cmp_gt_f32_e32 vcc, 0, v154
	v_pk_fma_f32 v[192:193], v[156:157], s[66:67], v[150:151] op_sel_hi:[1,0,0]
	s_nop 0
	v_pk_fma_f32 v[192:193], v[156:157], v[192:193], s[70:71] op_sel_hi:[1,1,0]
	s_nop 0
	v_pk_fma_f32 v[192:193], v[156:157], v[192:193], s[72:73] op_sel_hi:[1,1,0]
	s_nop 0
	v_pk_fma_f32 v[192:193], v[156:157], v[192:193], s[74:75] op_sel_hi:[1,1,0]
	s_nop 0
	v_pk_mul_f32 v[192:193], v[156:157], v[192:193]
	v_pk_mul_f32 v[156:157], v[152:153], v[152:153]
	v_pk_mul_f32 v[192:193], v[202:203], v[192:193]
	v_pk_mul_f32 v[156:157], v[156:157], s[76:77] op_sel_hi:[1,0]
	v_pk_mul_f32 v[202:203], v[154:155], v[192:193]
	v_pk_fma_f32 v[192:193], v[154:155], v[192:193], v[154:155] neg_lo:[1,0,0] neg_hi:[1,0,0]
	v_exp_f32_e32 v156, v156
	v_cndmask_b32_e32 v154, v192, v202, vcc
; __device__ __forceinline__ unsigned cvt_pk_bf16(float lo, float hi) { unsigned r; asm volatile("v_cvt_pk_bf16_f32 %0, %1, %2" : "=v"(r) : "v"(lo), "v"(hi)); return r; }
; __device__ __forceinline__ f32x2 gelu_pk(f32x2 v) {
;     const f32x2 av = __builtin_elementwise_abs(v), d = av * 0.2316418882f + 1.0f;
;     f32x2 t; t.x = __builtin_amdgcn_rcpf(d.x); t.y = __builtin_amdgcn_rcpf(d.y);
;     f32x2 q = t * 0.5307027145f + (-0.7265760135f); q = q * t + 0.7107068705f; q = q * t + (-0.142248368f); q = q * t + 0.127414796f; q = q * t;
;     const f32x2 s = (v * v) * (-0.72134752044f);
;     f32x2 e; e.x = __builtin_amdgcn_exp2f(s.x); e.y = __builtin_amdgcn_exp2f(s.y);
;     const f32x2 m = v * (q * e), r = v - m;
;     f32x2 o; o.x = v.x < 0.f ? m.x : r.x; o.y = v.y < 0.f ? m.y : r.y; return o;
; }
;     __device__ __forceinline__ void operator()(const f32x4 (&acc)[2][2][4][2], const Unit& u, int wr, int wc, int fr, int fq) const {
;     ...
;             for (int m = 0; m < 4; ++m) { const int row = row0 + ai * HALF + m * 16; const float rs = rsv[ai][m]; bf16_t* rowp = O + (size_t)row * ldc + col0; float s1 = 0.f, s2 = 0.f;
; #pragma unroll
;                 for (int bj = 0; bj < 2; ++bj) { f32x4 v0 = acc[ai][bj][m][0] * rs, v1 = acc[ai][bj][m][1] * rs;
;                     const f32x2 a = gelu_pk((f32x2){v0[0], v0[1]}), b = gelu_pk((f32x2){v0[2], v0[3]}), c = gelu_pk((f32x2){v1[0], v1[1]}), d = gelu_pk((f32x2){v1[2], v1[3]});
;                     s1 += ((a.x + a.y) + (b.x + b.y)) + ((c.x + c.y) + (d.x + d.y));
;                     s2 += ((a.x * a.x + a.y * a.y) + (b.x * b.x + b.y * b.y)) + ((c.x * c.x + c.y * c.y) + (d.x * d.x + d.y * d.y));
;                     u32x4 w; w.x = cvt_pk_bf16(a.x, a.y); w.y = cvt_pk_bf16(b.x, b.y); w.z = cvt_pk_bf16(c.x, c.y); w.w = cvt_pk_bf16(d.x, d.y);
;                     *(u32x4*)(rowp + bj * HALF) = w; }
	v_cmp_gt_f32_e32 vcc, 0, v155
	v_and_b32_e32 v192, 0x7fffffff, v152
	v_exp_f32_e32 v157, v157
	v_cndmask_b32_e32 v155, v193, v203, vcc
	v_and_b32_e32 v193, 0x7fffffff, v153
	v_pk_fma_f32 v[192:193], v[192:193], s[64:65], 1.0 op_sel_hi:[1,0,0]
	v_cmp_gt_f32_e32 vcc, 0, v152
	v_rcp_f32_e32 v192, v192
	v_rcp_f32_e32 v193, v193
	s_nop 0
	v_pk_fma_f32 v[202:203], v[192:193], s[66:67], v[150:151] op_sel_hi:[1,0,0]
	s_nop 0
	v_pk_fma_f32 v[202:203], v[192:193], v[202:203], s[70:71] op_sel_hi:[1,1,0]
	s_nop 0
	v_pk_fma_f32 v[202:203], v[192:193], v[202:203], s[72:73] op_sel_hi:[1,1,0]
	s_nop 0
	v_pk_fma_f32 v[202:203], v[192:193], v[202:203], s[74:75] op_sel_hi:[1,1,0]
	s_nop 0
	v_pk_mul_f32 v[192:193], v[192:193], v[202:203]
	v_cvt_pk_bf16_f32 v202, v178, v179
	v_cvt_pk_bf16_f32 v203, v189, v190
	v_cvt_pk_bf16_f32 v204, v154, v155
	s_nop 0
	v_pk_mul_f32 v[156:157], v[156:157], v[192:193]
	s_nop 0
	v_pk_mul_f32 v[192:193], v[152:153], v[156:157]
	v_pk_fma_f32 v[156:157], v[152:153], v[156:157], v[152:153] neg_lo:[1,0,0] neg_hi:[1,0,0]
	s_nop 0
	v_cndmask_b32_e32 v152, v156, v192, vcc
	v_cmp_gt_f32_e32 vcc, 0, v153
	s_nop 1
	v_cndmask_b32_e32 v153, v157, v193, vcc
	v_pk_mul_f32 v[156:157], v[138:139], v[0:1] op_sel_hi:[1,0]
	v_and_b32_e32 v139, 0x7fffffff, v143
	v_and_b32_e32 v138, 0x7fffffff, v142
	v_pk_fma_f32 v[138:139], v[138:139], s[64:65], 1.0 op_sel_hi:[1,0,0]
	v_cvt_pk_bf16_f32 v205, v152, v153
	global_store_dwordx4 v[176:177], v[202:205], off
	v_rcp_f32_e32 v138, v138
	v_rcp_f32_e32 v139, v139
	v_pk_mul_f32 v[202:203], v[142:143], v[142:143]
	v_cmp_gt_f32_e32 vcc, 0, v142
	v_pk_mul_f32 v[202:203], v[202:203], s[76:77] op_sel_hi:[1,0]
	v_pk_fma_f32 v[192:193], v[138:139], s[66:67], v[150:151] op_sel_hi:[1,0,0]
	v_exp_f32_e32 v202, v202
	v_pk_fma_f32 v[192:193], v[138:139], v[192:193], s[70:71] op_sel_hi:[1,1,0]
	v_exp_f32_e32 v203, v203
	v_pk_fma_f32 v[192:193], v[138:139], v[192:193], s[72:73] op_sel_hi:[1,1,0]
	s_nop 0
	v_pk_fma_f32 v[192:193], v[138:139], v[192:193], s[74:75] op_sel_hi:[1,1,0]
	s_nop 0
	v_pk_mul_f32 v[138:139], v[138:139], v[192:193]
	v_pk_mul_f32 v[192:193], v[144:145], v[144:145]
	v_pk_mul_f32 v[138:139], v[202:203], v[138:139]
	v_pk_mul_f32 v[192:193], v[192:193], s[76:77] op_sel_hi:[1,0]
	v_pk_mul_f32 v[202:203], v[142:143], v[138:139]
	v_pk_fma_f32 v[138:139], v[142:143], v[138:139], v[142:143] neg_lo:[1,0,0] neg_hi:[1,0,0]
	v_and_b32_e32 v142, 0x7fffffff, v144
	v_cndmask_b32_e32 v0, v138, v202, vcc
	v_cmp_gt_f32_e32 vcc, 0, v143
	v_and_b32_e32 v143, 0x7fffffff, v145
	v_pk_fma_f32 v[142:143], v[142:143], s[64:65], 1.0 op_sel_hi:[1,0,0]
	v_cndmask_b32_e32 v138, v139, v203, vcc
	v_rcp_f32_e32 v142, v142
	v_rcp_f32_e32 v143, v143
	v_exp_f32_e32 v192, v192
	v_exp_f32_e32 v193, v193
	v_cmp_gt_f32_e32 vcc, 0, v144
	v_pk_fma_f32 v[202:203], v[142:143], s[66:67], v[150:151] op_sel_hi:[1,0,0]
	s_nop 0
	v_pk_fma_f32 v[202:203], v[142:143], v[202:203], s[70:71] op_sel_hi:[1,1,0]
	s_nop 0
	v_pk_fma_f32 v[202:203], v[142:143], v[202:203], s[72:73] op_sel_hi:[1,1,0]
	s_nop 0
	v_pk_fma_f32 v[202:203], v[142:143], v[202:203], s[74:75] op_sel_hi:[1,1,0]
	s_nop 0
	v_pk_mul_f32 v[142:143], v[142:143], v[202:203]
	v_pk_mul_f32 v[202:203], v[156:157], v[156:157]
	v_pk_mul_f32 v[142:143], v[192:193], v[142:143]
	v_pk_mul_f32 v[202:203], v[202:203], s[76:77] op_sel_hi:[1,0]
	v_pk_mul_f32 v[192:193], v[144:145], v[142:143]
	v_pk_fma_f32 v[142:143], v[144:145], v[142:143], v[144:145] neg_lo:[1,0,0] neg_hi:[1,0,0]
	v_and_b32_e32 v144, 0x7fffffff, v156
	v_cndmask_b32_e32 v139, v142, v192, vcc
	v_cmp_gt_f32_e32 vcc, 0, v145
	v_and_b32_e32 v145, 0x7fffffff, v157
	v_pk_fma_f32 v[144:145], v[144:145], s[64:65], 1.0 op_sel_hi:[1,0,0]
	v_cndmask_b32_e32 v142, v143, v193, vcc
	v_rcp_f32_e32 v144, v144
	v_rcp_f32_e32 v145, v145
	v_exp_f32_e32 v202, v202
	v_exp_f32_e32 v203, v203
	v_cmp_gt_f32_e32 vcc, 0, v156
	v_pk_fma_f32 v[192:193], v[144:145], s[66:67], v[150:151] op_sel_hi:[1,0,0]
	s_nop 0
	v_pk_fma_f32 v[192:193], v[144:145], v[192:193], s[70:71] op_sel_hi:[1,1,0]
	s_nop 0
	v_pk_fma_f32 v[192:193], v[144:145], v[192:193], s[72:73] op_sel_hi:[1,1,0]
	s_nop 0
	v_pk_fma_f32 v[192:193], v[144:145], v[192:193], s[74:75] op_sel_hi:[1,1,0]
	s_nop 0
	v_pk_mul_f32 v[144:145], v[144:145], v[192:193]
	v_pk_mul_f32 v[192:193], v[140:141], v[140:141]
	v_pk_mul_f32 v[144:145], v[202:203], v[144:145]
	s_nop 0
	v_pk_mul_f32 v[202:203], v[156:157], v[144:145]
	v_pk_fma_f32 v[144:145], v[156:157], v[144:145], v[156:157] neg_lo:[1,0,0] neg_hi:[1,0,0]
	v_and_b32_e32 v156, 0x7fffffff, v140
	v_cndmask_b32_e32 v143, v144, v202, vcc
	v_cmp_gt_f32_e32 vcc, 0, v157
	v_and_b32_e32 v157, 0x7fffffff, v141
	v_pk_fma_f32 v[156:157], v[156:157], s[64:65], 1.0 op_sel_hi:[1,0,0]
	v_cndmask_b32_e32 v144, v145, v203, vcc
	v_rcp_f32_e32 v156, v156
	v_rcp_f32_e32 v157, v157
	v_cmp_gt_f32_e32 vcc, 0, v140
	v_cvt_pk_bf16_f32 v202, v0, v138
	v_cvt_pk_bf16_f32 v203, v139, v142
	v_pk_fma_f32 v[150:151], v[156:157], s[66:67], v[150:151] op_sel_hi:[1,0,0]
	v_cvt_pk_bf16_f32 v204, v143, v144
	s_nop 0
	v_pk_fma_f32 v[150:151], v[156:157], v[150:151], s[70:71] op_sel_hi:[1,1,0]
	s_nop 0
	v_pk_fma_f32 v[150:151], v[156:157], v[150:151], s[72:73] op_sel_hi:[1,1,0]
	s_nop 0
	v_pk_fma_f32 v[150:151], v[156:157], v[150:151], s[74:75] op_sel_hi:[1,1,0]
	s_nop 0
	v_pk_mul_f32 v[150:151], v[156:157], v[150:151]
	v_pk_mul_f32 v[156:157], v[192:193], s[76:77] op_sel_hi:[1,0]
	s_nop 0
	v_exp_f32_e32 v156, v156
	v_exp_f32_e32 v157, v157
	s_nop 0
	v_pk_mul_f32 v[150:151], v[156:157], v[150:151]
	s_nop 0
	v_pk_mul_f32 v[156:157], v[140:141], v[150:151]
	v_pk_fma_f32 v[150:151], v[140:141], v[150:151], v[140:141] neg_lo:[1,0,0] neg_hi:[1,0,0]
	s_nop 0
	v_cndmask_b32_e32 v140, v150, v156, vcc
	v_cmp_gt_f32_e32 vcc, 0, v141
	s_nop 1
	v_cndmask_b32_e32 v141, v151, v157, vcc
	v_cvt_pk_bf16_f32 v205, v140, v141
	global_store_dwordx4 v[176:177], v[202:205], off offset:256
	s_cbranch_scc1 .LBB0_356
; __device__ __forceinline__ unsigned cvt_pk_bf16(float lo, float hi) { unsigned r; asm volatile("v_cvt_pk_bf16_f32 %0, %1, %2" : "=v"(r) : "v"(lo), "v"(hi)); return r; }
;     __device__ __forceinline__ void operator()(const f32x4 (&acc)[2][2][4][2], const Unit& u, int wr, int wc, int fr, int fq) const {
;     ...
;                     s1 += ((a.x + a.y) + (b.x + b.y)) + ((c.x + c.y) + (d.x + d.y));
;                     s2 += ((a.x * a.x + a.y * a.y) + (b.x * b.x + b.y * b.y)) + ((c.x * c.x + c.y * c.y) + (d.x * d.x + d.y * d.y));
;                     u32x4 w; w.x = cvt_pk_bf16(a.x, a.y); w.y = cvt_pk_bf16(b.x, b.y); w.z = cvt_pk_bf16(c.x, c.y); w.w = cvt_pk_bf16(d.x, d.y);
;                     *(u32x4*)(rowp + bj * HALF) = w; }
;                 if (isv) { s1 += __shfl_xor(s1, 16); s1 += __shfl_xor(s1, 32); s2 += __shfl_xor(s2, 16); s2 += __shfl_xor(s2, 32);
;                     if (fq == 0) { const int rl = ai * HALF + wr * 64 + m * 16 + fr; part[rl * 4 + wc] = s1; part[1024 + rl * 4 + wc] = s2; } } }
	v_mul_f32_e32 v145, v179, v179
	v_mul_f32_e32 v150, v190, v190
	v_fmac_f32_e32 v145, v178, v178
	v_fmac_f32_e32 v150, v189, v189
	v_add_f32_e32 v145, v145, v150
	v_mul_f32_e32 v150, v155, v155
	v_mul_f32_e32 v151, v153, v153
	v_fmac_f32_e32 v150, v154, v154
	v_fmac_f32_e32 v151, v152, v152
	v_add_f32_e32 v150, v150, v151
	v_add_f32_e32 v145, v145, v150
	v_mul_f32_e32 v150, v138, v138
	v_fmac_f32_e32 v150, v0, v0
	v_mul_f32_e32 v151, v142, v142
	v_add_f32_e32 v0, v0, v138
	v_add_f32_e32 v138, v139, v142
	v_fmac_f32_e32 v151, v139, v139
	v_add_f32_e32 v0, v0, v138
	v_add_f32_e32 v138, v143, v144
	v_add_f32_e32 v139, v140, v141
	v_add_f32_e32 v157, v178, v179
	v_add_f32_e32 v176, v189, v190
	v_add_f32_e32 v154, v154, v155
	v_add_f32_e32 v152, v152, v153
	v_add_f32_e32 v138, v138, v139
	v_and_b32_e32 v139, 64, v226
	v_add_f32_e32 v157, v157, v176
	v_add_f32_e32 v152, v154, v152
	v_add_f32_e32 v0, v0, v138
	v_xor_b32_e32 v138, 16, v226
	v_add_u32_e32 v139, 64, v139
	v_add_f32_e32 v152, v157, v152
	v_cmp_lt_i32_e32 vcc, v138, v139
	v_add_f32_e32 v150, v150, v151
	v_mul_f32_e32 v151, v144, v144
	v_mul_f32_e32 v156, v141, v141
	v_add_f32_e32 v152, 0, v152
	v_cndmask_b32_e32 v138, v226, v138, vcc
	v_fmac_f32_e32 v151, v143, v143
	v_add_f32_e32 v0, v0, v152
	v_lshlrev_b32_e32 v138, 2, v138
	v_fmac_f32_e32 v156, v140, v140
	v_mov_b32_e32 v141, v0
	s_nop 1
	v_permlane16_swap_b32_e32 v141, v0
	v_add_f32_e32 v140, v151, v156
	v_add_f32_e32 v140, v150, v140
	v_add_f32_e32 v140, v145, v140
	v_mov_b32_e32 v142, v140
	s_nop 1
	v_permlane16_swap_b32_e32 v142, v140
	s_waitcnt lgkmcnt(0)
	v_add_f32_e32 v0, v0, v141
	v_xor_b32_e32 v141, 32, v226
	v_cmp_lt_i32_e32 vcc, v141, v139
	v_add_f32_e32 v139, v140, v142
	s_nop 0
	v_cndmask_b32_e32 v138, v226, v141, vcc
	v_lshlrev_b32_e32 v141, 2, v138
	v_mov_b32_e32 v138, v0
	s_nop 1
	v_permlane32_swap_b32_e32 v138, v0
	v_mov_b32_e32 v140, v139
	s_nop 1
	v_permlane32_swap_b32_e32 v140, v139
	s_and_saveexec_b64 s[4:5], s[6:7]
	s_cbranch_execz .LBB0_355
	s_waitcnt lgkmcnt(0)
	v_add_f32_e32 v139, v139, v140
	v_add_f32_e32 v0, v0, v138
	ds_write2st64_b32 v186, v0, v139 offset1:16

; __device__ __forceinline__ unsigned cvt_pk_bf16(float lo, float hi) { unsigned r; asm volatile("v_cvt_pk_bf16_f32 %0, %1, %2" : "=v"(r) : "v"(lo), "v"(hi)); return r; }
; __device__ __forceinline__ f32x2 gelu_pk(f32x2 v) {
;     const f32x2 av = __builtin_elementwise_abs(v), d = av * 0.2316418882f + 1.0f;
;     f32x2 t; t.x = __builtin_amdgcn_rcpf(d.x); t.y = __builtin_amdgcn_rcpf(d.y);
;     f32x2 q = t * 0.5307027145f + (-0.7265760135f); q = q * t + 0.7107068705f; q = q * t + (-0.142248368f); q = q * t + 0.127414796f; q = q * t;
;     const f32x2 s = (v * v) * (-0.72134752044f);
;     f32x2 e; e.x = __builtin_amdgcn_exp2f(s.x); e.y = __builtin_amdgcn_exp2f(s.y);
;     const f32x2 m = v * (q * e), r = v - m;
;     f32x2 o; o.x = v.x < 0.f ? m.x : r.x; o.y = v.y < 0.f ? m.y : r.y; return o;
; }
; __device__ __forceinline__ void rstd8(const float* ss, int row0, float (&rs)[2][4]) {
;     ...
;         for (int m = 0; m < 4; ++m) p[ai][m] = *(const f32x4*)(ss + 4 * (size_t)(row0 + ai * HALF + m * 16));
; #pragma unroll
;     for (int ai = 0; ai < 2; ++ai)
; #pragma unroll
;         for (int m = 0; m < 4; ++m) rs[ai][m] = __builtin_amdgcn_rsqf(((p[ai][m].x + p[ai][m].y) + (p[ai][m].z + p[ai][m].w)) * (1.0f / D) + EPS);
;     __device__ __forceinline__ void operator()(const f32x4 (&acc)[2][2][4][2], const Unit& u, int wr, int wc, int fr, int fq) const {
;     ...
;             for (int m = 0; m < 4; ++m) { const int row = row0 + ai * HALF + m * 16; const float rs = rsv[ai][m]; bf16_t* rowp = O + (size_t)row * ldc + col0; float s1 = 0.f, s2 = 0.f;
; #pragma unroll
;                 for (int bj = 0; bj < 2; ++bj) { f32x4 v0 = acc[ai][bj][m][0] * rs, v1 = acc[ai][bj][m][1] * rs;
;                     const f32x2 a = gelu_pk((f32x2){v0[0], v0[1]}), b = gelu_pk((f32x2){v0[2], v0[3]}), c = gelu_pk((f32x2){v1[0], v1[1]}), d = gelu_pk((f32x2){v1[2], v1[3]});
;                     s1 += ((a.x + a.y) + (b.x + b.y)) + ((c.x + c.y) + (d.x + d.y));
;                     s2 += ((a.x * a.x + a.y * a.y) + (b.x * b.x + b.y * b.y)) + ((c.x * c.x + c.y * c.y) + (d.x * d.x + d.y * d.y));
;                     u32x4 w; w.x = cvt_pk_bf16(a.x, a.y); w.y = cvt_pk_bf16(b.x, b.y); w.z = cvt_pk_bf16(c.x, c.y); w.w = cvt_pk_bf16(d.x, d.y);
;                     *(u32x4*)(rowp + bj * HALF) = w; }
.LBB0_356:
	v_add_f32_e32 v0, v146, v147
	s_waitcnt lgkmcnt(0)
	v_add_f32_e32 v138, v148, v149
	v_add_f32_e32 v0, v0, v138
	v_fmamk_f32 v0, v0, 0x3a800000, v224
	v_rsq_f32_e32 v0, v0
	s_mov_b32 s4, 0xbf3a00e3
	v_lshlrev_b64 v[138:139], 12, v[174:175]
	v_lshl_add_u64 v[138:139], s[20:21], 0, v[138:139]
	v_pk_mul_f32 v[134:135], v[134:135], v[0:1] op_sel_hi:[1,0]
	v_pk_mul_f32 v[140:141], v[130:131], v[0:1] op_sel_hi:[1,0]
	v_and_b32_e32 v131, 0x7fffffff, v135
	v_and_b32_e32 v130, 0x7fffffff, v134
	v_pk_fma_f32 v[130:131], v[130:131], s[64:65], 1.0 op_sel_hi:[1,0,0]
	v_pk_mul_f32 v[146:147], v[134:135], v[134:135]
	v_rcp_f32_e32 v142, v130
	v_rcp_f32_e32 v143, v131
	v_mov_b64_e32 v[130:131], s[4:5]
	v_pk_mul_f32 v[146:147], v[146:147], s[76:77] op_sel_hi:[1,0]
	v_cmp_gt_f32_e32 vcc, 0, v134
	v_pk_fma_f32 v[144:145], v[142:143], s[66:67], v[130:131] op_sel_hi:[1,0,0]
	v_exp_f32_e32 v146, v146
	v_pk_fma_f32 v[144:145], v[142:143], v[144:145], s[70:71] op_sel_hi:[1,1,0]
	v_exp_f32_e32 v147, v147
	v_pk_fma_f32 v[144:145], v[142:143], v[144:145], s[72:73] op_sel_hi:[1,1,0]
	v_pk_mul_f32 v[136:137], v[136:137], v[0:1] op_sel_hi:[1,0]
	v_pk_fma_f32 v[144:145], v[142:143], v[144:145], s[74:75] op_sel_hi:[1,1,0]
	v_pk_mul_f32 v[132:133], v[132:133], v[0:1] op_sel_hi:[1,0]
	v_pk_mul_f32 v[142:143], v[142:143], v[144:145]
	v_pk_mul_f32 v[144:145], v[136:137], v[136:137]
	v_pk_mul_f32 v[142:143], v[146:147], v[142:143]
	v_pk_mul_f32 v[144:145], v[144:145], s[76:77] op_sel_hi:[1,0]
	v_pk_mul_f32 v[146:147], v[134:135], v[142:143]
	v_pk_fma_f32 v[142:143], v[134:135], v[142:143], v[134:135] neg_lo:[1,0,0] neg_hi:[1,0,0]
	v_exp_f32_e32 v144, v144
	v_cndmask_b32_e32 v134, v142, v146, vcc
	v_cmp_gt_f32_e32 vcc, 0, v135
	v_and_b32_e32 v142, 0x7fffffff, v136
	v_exp_f32_e32 v145, v145
	v_cndmask_b32_e32 v135, v143, v147, vcc
	v_and_b32_e32 v143, 0x7fffffff, v137
	v_pk_fma_f32 v[142:143], v[142:143], s[64:65], 1.0 op_sel_hi:[1,0,0]
	v_cmp_gt_f32_e32 vcc, 0, v136
	v_rcp_f32_e32 v142, v142
	v_rcp_f32_e32 v143, v143
	v_lshl_add_u64 v[138:139], v[160:161], 1, v[138:139]
	v_pk_mul_f32 v[122:123], v[122:123], v[0:1] op_sel_hi:[1,0]
	v_pk_mul_f32 v[124:125], v[124:125], v[0:1] op_sel_hi:[1,0]
	v_pk_fma_f32 v[146:147], v[142:143], s[66:67], v[130:131] op_sel_hi:[1,0,0]
	v_pk_mul_f32 v[120:121], v[120:121], v[0:1] op_sel_hi:[1,0]
	v_pk_fma_f32 v[146:147], v[142:143], v[146:147], s[70:71] op_sel_hi:[1,1,0]
	s_nop 0
	v_pk_fma_f32 v[146:147], v[142:143], v[146:147], s[72:73] op_sel_hi:[1,1,0]
	s_nop 0
	v_pk_fma_f32 v[146:147], v[142:143], v[146:147], s[74:75] op_sel_hi:[1,1,0]
	s_nop 0
	v_pk_mul_f32 v[142:143], v[142:143], v[146:147]
	v_pk_mul_f32 v[146:147], v[140:141], v[140:141]
	v_pk_mul_f32 v[142:143], v[144:145], v[142:143]
	v_pk_mul_f32 v[146:147], v[146:147], s[76:77] op_sel_hi:[1,0]
	v_pk_mul_f32 v[144:145], v[136:137], v[142:143]
	v_pk_fma_f32 v[142:143], v[136:137], v[142:143], v[136:137] neg_lo:[1,0,0] neg_hi:[1,0,0]
	v_exp_f32_e32 v146, v146
	v_cndmask_b32_e32 v136, v142, v144, vcc
	v_cmp_gt_f32_e32 vcc, 0, v137
	v_and_b32_e32 v142, 0x7fffffff, v140
	v_exp_f32_e32 v147, v147
	v_cndmask_b32_e32 v137, v143, v145, vcc
	v_and_b32_e32 v143, 0x7fffffff, v141
	v_pk_fma_f32 v[142:143], v[142:143], s[64:65], 1.0 op_sel_hi:[1,0,0]
	v_cmp_gt_f32_e32 vcc, 0, v140
	v_rcp_f32_e32 v142, v142
	v_rcp_f32_e32 v143, v143
	s_nop 0
	v_pk_fma_f32 v[144:145], v[142:143], s[66:67], v[130:131] op_sel_hi:[1,0,0]
	s_nop 0
	v_pk_fma_f32 v[144:145], v[142:143], v[144:145], s[70:71] op_sel_hi:[1,1,0]
	s_nop 0
	v_pk_fma_f32 v[144:145], v[142:143], v[144:145], s[72:73] op_sel_hi:[1,1,0]
	s_nop 0
	v_pk_fma_f32 v[144:145], v[142:143], v[144:145], s[74:75] op_sel_hi:[1,1,0]
	s_nop 0
	v_pk_mul_f32 v[142:143], v[142:143], v[144:145]
	v_pk_mul_f32 v[144:145], v[132:133], v[132:133]
	v_pk_mul_f32 v[142:143], v[146:147], v[142:143]
	v_pk_mul_f32 v[144:145], v[144:145], s[76:77] op_sel_hi:[1,0]
	v_pk_mul_f32 v[146:147], v[140:141], v[142:143]
	v_pk_fma_f32 v[142:143], v[140:141], v[142:143], v[140:141] neg_lo:[1,0,0] neg_hi:[1,0,0]
	v_exp_f32_e32 v144, v144
	v_cndmask_b32_e32 v140, v142, v146, vcc
	v_cmp_gt_f32_e32 vcc, 0, v141
	v_and_b32_e32 v142, 0x7fffffff, v132
	v_exp_f32_e32 v145, v145
	v_cndmask_b32_e32 v141, v143, v147, vcc
	v_and_b32_e32 v143, 0x7fffffff, v133
	v_pk_fma_f32 v[142:143], v[142:143], s[64:65], 1.0 op_sel_hi:[1,0,0]
	v_cmp_gt_f32_e32 vcc, 0, v132
	v_rcp_f32_e32 v142, v142
	v_rcp_f32_e32 v143, v143
	s_nop 0
	v_pk_fma_f32 v[146:147], v[142:143], s[66:67], v[130:131] op_sel_hi:[1,0,0]
	s_nop 0
	v_pk_fma_f32 v[146:147], v[142:143], v[146:147], s[70:71] op_sel_hi:[1,1,0]
	s_nop 0
	v_pk_fma_f32 v[146:147], v[142:143], v[146:147], s[72:73] op_sel_hi:[1,1,0]
	s_nop 0
	v_pk_fma_f32 v[146:147], v[142:143], v[146:147], s[74:75] op_sel_hi:[1,1,0]
	s_nop 0
	v_pk_mul_f32 v[142:143], v[142:143], v[146:147]
	v_pk_mul_f32 v[146:147], v[122:123], v[122:123]
	v_pk_mul_f32 v[142:143], v[144:145], v[142:143]
	v_pk_mul_f32 v[146:147], v[146:147], s[76:77] op_sel_hi:[1,0]
	v_pk_mul_f32 v[144:145], v[132:133], v[142:143]
	v_pk_fma_f32 v[142:143], v[132:133], v[142:143], v[132:133] neg_lo:[1,0,0] neg_hi:[1,0,0]
	v_exp_f32_e32 v146, v146
	v_cndmask_b32_e32 v132, v142, v144, vcc
	v_cmp_gt_f32_e32 vcc, 0, v133
	v_cvt_pk_bf16_f32 v142, v134, v135
	v_exp_f32_e32 v147, v147
	s_nop 0
	v_cndmask_b32_e32 v133, v143, v145, vcc
	v_cvt_pk_bf16_f32 v143, v136, v137
	v_cvt_pk_bf16_f32 v144, v140, v141
	v_cvt_pk_bf16_f32 v145, v132, v133
	global_store_dwordx4 v[138:139], v[142:145], off
	v_cmp_gt_f32_e32 vcc, 0, v122
	s_nop 0
	v_pk_mul_f32 v[142:143], v[118:119], v[0:1] op_sel_hi:[1,0]
	v_and_b32_e32 v119, 0x7fffffff, v123
; __device__ __forceinline__ unsigned cvt_pk_bf16(float lo, float hi) { unsigned r; asm volatile("v_cvt_pk_bf16_f32 %0, %1, %2" : "=v"(r) : "v"(lo), "v"(hi)); return r; }
; __device__ __forceinline__ f32x2 gelu_pk(f32x2 v) {
;     const f32x2 av = __builtin_elementwise_abs(v), d = av * 0.2316418882f + 1.0f;
;     f32x2 t; t.x = __builtin_amdgcn_rcpf(d.x); t.y = __builtin_amdgcn_rcpf(d.y);
;     f32x2 q = t * 0.5307027145f + (-0.7265760135f); q = q * t + 0.7107068705f; q = q * t + (-0.142248368f); q = q * t + 0.127414796f; q = q * t;
;     const f32x2 s = (v * v) * (-0.72134752044f);
;     f32x2 e; e.x = __builtin_amdgcn_exp2f(s.x); e.y = __builtin_amdgcn_exp2f(s.y);
;     const f32x2 m = v * (q * e), r = v - m;
;     f32x2 o; o.x = v.x < 0.f ? m.x : r.x; o.y = v.y < 0.f ? m.y : r.y; return o;
; }
;     __device__ __forceinline__ void operator()(const f32x4 (&acc)[2][2][4][2], const Unit& u, int wr, int wc, int fr, int fq) const {
;     ...
;             for (int m = 0; m < 4; ++m) { const int row = row0 + ai * HALF + m * 16; const float rs = rsv[ai][m]; bf16_t* rowp = O + (size_t)row * ldc + col0; float s1 = 0.f, s2 = 0.f;
; #pragma unroll
;                 for (int bj = 0; bj < 2; ++bj) { f32x4 v0 = acc[ai][bj][m][0] * rs, v1 = acc[ai][bj][m][1] * rs;
;                     const f32x2 a = gelu_pk((f32x2){v0[0], v0[1]}), b = gelu_pk((f32x2){v0[2], v0[3]}), c = gelu_pk((f32x2){v1[0], v1[1]}), d = gelu_pk((f32x2){v1[2], v1[3]});
;                     s1 += ((a.x + a.y) + (b.x + b.y)) + ((c.x + c.y) + (d.x + d.y));
;                     s2 += ((a.x * a.x + a.y * a.y) + (b.x * b.x + b.y * b.y)) + ((c.x * c.x + c.y * c.y) + (d.x * d.x + d.y * d.y));
;                     u32x4 w; w.x = cvt_pk_bf16(a.x, a.y); w.y = cvt_pk_bf16(b.x, b.y); w.z = cvt_pk_bf16(c.x, c.y); w.w = cvt_pk_bf16(d.x, d.y);
;                     *(u32x4*)(rowp + bj * HALF) = w; }
;                 if (isv) { s1 += __shfl_xor(s1, 16); s1 += __shfl_xor(s1, 32); s2 += __shfl_xor(s2, 16); s2 += __shfl_xor(s2, 32);
;                     if (fq == 0) { const int rl = ai * HALF + wr * 64 + m * 16 + fr; part[rl * 4 + wc] = s1; part[1024 + rl * 4 + wc] = s2; } } }
	v_and_b32_e32 v118, 0x7fffffff, v122
	v_pk_fma_f32 v[118:119], v[118:119], s[64:65], 1.0 op_sel_hi:[1,0,0]
	s_nop 0
	v_rcp_f32_e32 v118, v118
	v_rcp_f32_e32 v119, v119
	s_nop 0
	v_pk_fma_f32 v[144:145], v[118:119], s[66:67], v[130:131] op_sel_hi:[1,0,0]
	s_nop 0
	v_pk_fma_f32 v[144:145], v[118:119], v[144:145], s[70:71] op_sel_hi:[1,1,0]
	s_nop 0
	v_pk_fma_f32 v[144:145], v[118:119], v[144:145], s[72:73] op_sel_hi:[1,1,0]
	s_nop 0
	v_pk_fma_f32 v[144:145], v[118:119], v[144:145], s[74:75] op_sel_hi:[1,1,0]
	s_nop 0
	v_pk_mul_f32 v[118:119], v[118:119], v[144:145]
	v_pk_mul_f32 v[144:145], v[124:125], v[124:125]
	v_pk_mul_f32 v[118:119], v[146:147], v[118:119]
	v_pk_mul_f32 v[144:145], v[144:145], s[76:77] op_sel_hi:[1,0]
	v_pk_mul_f32 v[146:147], v[122:123], v[118:119]
	v_pk_fma_f32 v[118:119], v[122:123], v[118:119], v[122:123] neg_lo:[1,0,0] neg_hi:[1,0,0]
	v_and_b32_e32 v122, 0x7fffffff, v124
	v_cndmask_b32_e32 v0, v118, v146, vcc
	v_cmp_gt_f32_e32 vcc, 0, v123
	v_and_b32_e32 v123, 0x7fffffff, v125
	v_pk_fma_f32 v[122:123], v[122:123], s[64:65], 1.0 op_sel_hi:[1,0,0]
	v_cndmask_b32_e32 v118, v119, v147, vcc
	v_rcp_f32_e32 v122, v122
	v_rcp_f32_e32 v123, v123
	v_exp_f32_e32 v144, v144
	v_exp_f32_e32 v145, v145
	v_cmp_gt_f32_e32 vcc, 0, v124
	v_pk_fma_f32 v[146:147], v[122:123], s[66:67], v[130:131] op_sel_hi:[1,0,0]
	s_nop 0
	v_pk_fma_f32 v[146:147], v[122:123], v[146:147], s[70:71] op_sel_hi:[1,1,0]
	s_nop 0
	v_pk_fma_f32 v[146:147], v[122:123], v[146:147], s[72:73] op_sel_hi:[1,1,0]
	s_nop 0
	v_pk_fma_f32 v[146:147], v[122:123], v[146:147], s[74:75] op_sel_hi:[1,1,0]
	s_nop 0
	v_pk_mul_f32 v[122:123], v[122:123], v[146:147]
	v_pk_mul_f32 v[146:147], v[142:143], v[142:143]
	v_pk_mul_f32 v[122:123], v[144:145], v[122:123]
	v_pk_mul_f32 v[146:147], v[146:147], s[76:77] op_sel_hi:[1,0]
	v_pk_mul_f32 v[144:145], v[124:125], v[122:123]
	v_pk_fma_f32 v[122:123], v[124:125], v[122:123], v[124:125] neg_lo:[1,0,0] neg_hi:[1,0,0]
	v_and_b32_e32 v124, 0x7fffffff, v142
	v_cndmask_b32_e32 v119, v122, v144, vcc
	v_cmp_gt_f32_e32 vcc, 0, v125
	v_and_b32_e32 v125, 0x7fffffff, v143
	v_pk_fma_f32 v[124:125], v[124:125], s[64:65], 1.0 op_sel_hi:[1,0,0]
	v_cndmask_b32_e32 v122, v123, v145, vcc
	v_rcp_f32_e32 v124, v124
	v_rcp_f32_e32 v125, v125
	v_exp_f32_e32 v146, v146
	v_exp_f32_e32 v147, v147
	v_cmp_gt_f32_e32 vcc, 0, v142
	v_pk_fma_f32 v[144:145], v[124:125], s[66:67], v[130:131] op_sel_hi:[1,0,0]
	s_nop 0
	v_pk_fma_f32 v[144:145], v[124:125], v[144:145], s[70:71] op_sel_hi:[1,1,0]
	s_nop 0
	v_pk_fma_f32 v[144:145], v[124:125], v[144:145], s[72:73] op_sel_hi:[1,1,0]
	s_nop 0
	v_pk_fma_f32 v[144:145], v[124:125], v[144:145], s[74:75] op_sel_hi:[1,1,0]
	s_nop 0
	v_pk_mul_f32 v[124:125], v[124:125], v[144:145]
	v_pk_mul_f32 v[144:145], v[120:121], v[120:121]
	v_pk_mul_f32 v[124:125], v[146:147], v[124:125]
	s_nop 0
	v_pk_mul_f32 v[146:147], v[142:143], v[124:125]
	v_pk_fma_f32 v[124:125], v[142:143], v[124:125], v[142:143] neg_lo:[1,0,0] neg_hi:[1,0,0]
	v_and_b32_e32 v142, 0x7fffffff, v120
	v_cndmask_b32_e32 v123, v124, v146, vcc
	v_cmp_gt_f32_e32 vcc, 0, v143
	v_and_b32_e32 v143, 0x7fffffff, v121
	v_pk_fma_f32 v[142:143], v[142:143], s[64:65], 1.0 op_sel_hi:[1,0,0]
	v_cndmask_b32_e32 v124, v125, v147, vcc
	v_rcp_f32_e32 v142, v142
	v_rcp_f32_e32 v143, v143
	v_cmp_gt_f32_e32 vcc, 0, v120
	v_cndmask_b32_e64 v125, 0, 1, s[36:37]
	v_cmp_ne_u32_e64 s[10:11], 1, v125
	v_pk_fma_f32 v[130:131], v[142:143], s[66:67], v[130:131] op_sel_hi:[1,0,0]
	s_nop 0
	v_pk_fma_f32 v[130:131], v[142:143], v[130:131], s[70:71] op_sel_hi:[1,1,0]
	s_nop 0
	v_pk_fma_f32 v[130:131], v[142:143], v[130:131], s[72:73] op_sel_hi:[1,1,0]
	s_nop 0
	v_pk_fma_f32 v[130:131], v[142:143], v[130:131], s[74:75] op_sel_hi:[1,1,0]
	s_nop 0
	v_pk_mul_f32 v[130:131], v[142:143], v[130:131]
	v_pk_mul_f32 v[142:143], v[144:145], s[76:77] op_sel_hi:[1,0]
	s_nop 0
	v_exp_f32_e32 v142, v142
	v_exp_f32_e32 v143, v143
	s_nop 0
	v_pk_mul_f32 v[130:131], v[142:143], v[130:131]
	s_nop 0
	v_pk_mul_f32 v[142:143], v[120:121], v[130:131]
	v_pk_fma_f32 v[130:131], v[120:121], v[130:131], v[120:121] neg_lo:[1,0,0] neg_hi:[1,0,0]
	s_nop 0
	v_cndmask_b32_e32 v120, v130, v142, vcc
	v_cmp_gt_f32_e32 vcc, 0, v121
	v_cvt_pk_bf16_f32 v142, v0, v118
	s_nop 1
	v_cndmask_b32_e32 v121, v131, v143, vcc
	s_andn2_b64 vcc, exec, s[36:37]
	v_cvt_pk_bf16_f32 v143, v119, v122
	v_cvt_pk_bf16_f32 v144, v123, v124
	v_cvt_pk_bf16_f32 v145, v120, v121
	global_store_dwordx4 v[138:139], v[142:145], off offset:256
	s_cbranch_vccnz .LBB0_360
	v_mul_f32_e32 v125, v135, v135
	v_mul_f32_e32 v130, v137, v137
	v_fmac_f32_e32 v125, v134, v134
	v_fmac_f32_e32 v130, v136, v136
	v_add_f32_e32 v125, v125, v130
	v_mul_f32_e32 v130, v141, v141
	v_mul_f32_e32 v131, v133, v133
	v_fmac_f32_e32 v130, v140, v140
	v_fmac_f32_e32 v131, v132, v132
	v_add_f32_e32 v130, v130, v131
	v_add_f32_e32 v125, v125, v130
	v_mul_f32_e32 v130, v118, v118
	v_fmac_f32_e32 v130, v0, v0
	v_mul_f32_e32 v131, v122, v122
	v_add_f32_e32 v0, v0, v118
	v_add_f32_e32 v118, v119, v122
	v_fmac_f32_e32 v131, v119, v119
	v_add_f32_e32 v134, v134, v135
	v_add_f32_e32 v135, v136, v137
	v_add_f32_e32 v0, v0, v118
	v_add_f32_e32 v118, v123, v124
	v_add_f32_e32 v119, v120, v121
	v_add_f32_e32 v134, v134, v135
	v_add_f32_e32 v135, v140, v141
	v_add_f32_e32 v132, v132, v133
	v_add_f32_e32 v118, v118, v119
	v_and_b32_e32 v119, 64, v226
	v_add_f32_e32 v132, v135, v132
	v_add_f32_e32 v0, v0, v118
	v_xor_b32_e32 v118, 16, v226
	v_add_u32_e32 v119, 64, v119
	v_add_f32_e32 v132, v134, v132
	v_cmp_lt_i32_e32 vcc, v118, v119
	v_add_f32_e32 v130, v130, v131
	v_mul_f32_e32 v131, v124, v124
	v_mul_f32_e32 v138, v121, v121
	v_add_f32_e32 v132, 0, v132
	v_cndmask_b32_e32 v118, v226, v118, vcc
	v_fmac_f32_e32 v131, v123, v123
	v_add_f32_e32 v0, v0, v132
	v_lshlrev_b32_e32 v118, 2, v118
	v_fmac_f32_e32 v138, v120, v120
	v_mov_b32_e32 v121, v0
	s_nop 1
	v_permlane16_swap_b32_e32 v121, v0
	v_add_f32_e32 v120, v131, v138
	v_add_f32_e32 v120, v130, v120
	v_add_f32_e32 v120, v125, v120
	v_mov_b32_e32 v122, v120
	s_nop 1
	v_permlane16_swap_b32_e32 v122, v120
	s_waitcnt lgkmcnt(0)
	v_add_f32_e32 v0, v0, v121
	v_xor_b32_e32 v121, 32, v226
	v_cmp_lt_i32_e32 vcc, v121, v119
	v_add_f32_e32 v119, v120, v122
	s_nop 0
	v_cndmask_b32_e32 v118, v226, v121, vcc
	v_lshlrev_b32_e32 v121, 2, v118
	v_mov_b32_e32 v118, v0
	s_nop 1
	v_permlane32_swap_b32_e32 v118, v0
	v_mov_b32_e32 v120, v119
	s_nop 1
	v_permlane32_swap_b32_e32 v120, v119
	s_and_saveexec_b64 s[4:5], s[6:7]
	s_cbranch_execz .LBB0_359
	s_waitcnt lgkmcnt(0)
	v_add_f32_e32 v119, v119, v120
	v_add_f32_e32 v0, v0, v118
	ds_write2st64_b32 v186, v0, v119 offset0:1 offset1:17

; __device__ __forceinline__ unsigned cvt_pk_bf16(float lo, float hi) { unsigned r; asm volatile("v_cvt_pk_bf16_f32 %0, %1, %2" : "=v"(r) : "v"(lo), "v"(hi)); return r; }
; __device__ __forceinline__ f32x2 gelu_pk(f32x2 v) {
;     const f32x2 av = __builtin_elementwise_abs(v), d = av * 0.2316418882f + 1.0f;
;     f32x2 t; t.x = __builtin_amdgcn_rcpf(d.x); t.y = __builtin_amdgcn_rcpf(d.y);
;     f32x2 q = t * 0.5307027145f + (-0.7265760135f); q = q * t + 0.7107068705f; q = q * t + (-0.142248368f); q = q * t + 0.127414796f; q = q * t;
;     const f32x2 s = (v * v) * (-0.72134752044f);
;     f32x2 e; e.x = __builtin_amdgcn_exp2f(s.x); e.y = __builtin_amdgcn_exp2f(s.y);
;     const f32x2 m = v * (q * e), r = v - m;
;     f32x2 o; o.x = v.x < 0.f ? m.x : r.x; o.y = v.y < 0.f ? m.y : r.y; return o;
; }
; __device__ __forceinline__ void rstd8(const float* ss, int row0, float (&rs)[2][4]) {
;     ...
;         for (int m = 0; m < 4; ++m) p[ai][m] = *(const f32x4*)(ss + 4 * (size_t)(row0 + ai * HALF + m * 16));
; #pragma unroll
;     for (int ai = 0; ai < 2; ++ai)
; #pragma unroll
;         for (int m = 0; m < 4; ++m) rs[ai][m] = __builtin_amdgcn_rsqf(((p[ai][m].x + p[ai][m].y) + (p[ai][m].z + p[ai][m].w)) * (1.0f / D) + EPS);
;     __device__ __forceinline__ void operator()(const f32x4 (&acc)[2][2][4][2], const Unit& u, int wr, int wc, int fr, int fq) const {
;     ...
;             for (int m = 0; m < 4; ++m) { const int row = row0 + ai * HALF + m * 16; const float rs = rsv[ai][m]; bf16_t* rowp = O + (size_t)row * ldc + col0; float s1 = 0.f, s2 = 0.f;
; #pragma unroll
;                 for (int bj = 0; bj < 2; ++bj) { f32x4 v0 = acc[ai][bj][m][0] * rs, v1 = acc[ai][bj][m][1] * rs;
;                     const f32x2 a = gelu_pk((f32x2){v0[0], v0[1]}), b = gelu_pk((f32x2){v0[2], v0[3]}), c = gelu_pk((f32x2){v1[0], v1[1]}), d = gelu_pk((f32x2){v1[2], v1[3]});
;                     s1 += ((a.x + a.y) + (b.x + b.y)) + ((c.x + c.y) + (d.x + d.y));
;                     s2 += ((a.x * a.x + a.y * a.y) + (b.x * b.x + b.y * b.y)) + ((c.x * c.x + c.y * c.y) + (d.x * d.x + d.y * d.y));
;                     u32x4 w; w.x = cvt_pk_bf16(a.x, a.y); w.y = cvt_pk_bf16(b.x, b.y); w.z = cvt_pk_bf16(c.x, c.y); w.w = cvt_pk_bf16(d.x, d.y);
;                     *(u32x4*)(rowp + bj * HALF) = w; }
.LBB0_360:
	v_add_f32_e32 v0, v126, v127
	s_waitcnt lgkmcnt(0)
	v_add_f32_e32 v118, v128, v129
	v_add_f32_e32 v0, v0, v118
	v_fmamk_f32 v0, v0, 0x3a800000, v224
	v_rsq_f32_e32 v0, v0
	s_mov_b32 s4, 0xbf3a00e3
	v_lshlrev_b64 v[118:119], 12, v[172:173]
	v_lshl_add_u64 v[118:119], s[20:21], 0, v[118:119]
	v_pk_mul_f32 v[114:115], v[114:115], v[0:1] op_sel_hi:[1,0]
	v_pk_mul_f32 v[120:121], v[106:107], v[0:1] op_sel_hi:[1,0]
	v_and_b32_e32 v107, 0x7fffffff, v115
	v_and_b32_e32 v106, 0x7fffffff, v114
	v_pk_fma_f32 v[106:107], v[106:107], s[64:65], 1.0 op_sel_hi:[1,0,0]
	v_pk_mul_f32 v[126:127], v[114:115], v[114:115]
	v_rcp_f32_e32 v122, v106
	v_rcp_f32_e32 v123, v107
	v_mov_b64_e32 v[106:107], s[4:5]
	v_pk_mul_f32 v[126:127], v[126:127], s[76:77] op_sel_hi:[1,0]
	v_cmp_gt_f32_e32 vcc, 0, v114
	v_pk_fma_f32 v[124:125], v[122:123], s[66:67], v[106:107] op_sel_hi:[1,0,0]
	v_exp_f32_e32 v126, v126
	v_pk_fma_f32 v[124:125], v[122:123], v[124:125], s[70:71] op_sel_hi:[1,1,0]
	v_exp_f32_e32 v127, v127
	v_pk_fma_f32 v[124:125], v[122:123], v[124:125], s[72:73] op_sel_hi:[1,1,0]
	v_pk_mul_f32 v[116:117], v[116:117], v[0:1] op_sel_hi:[1,0]
	v_pk_fma_f32 v[124:125], v[122:123], v[124:125], s[74:75] op_sel_hi:[1,1,0]
	v_pk_mul_f32 v[108:109], v[108:109], v[0:1] op_sel_hi:[1,0]
	v_pk_mul_f32 v[122:123], v[122:123], v[124:125]
	v_pk_mul_f32 v[124:125], v[116:117], v[116:117]
	v_pk_mul_f32 v[122:123], v[126:127], v[122:123]
	v_pk_mul_f32 v[124:125], v[124:125], s[76:77] op_sel_hi:[1,0]
	v_pk_mul_f32 v[126:127], v[114:115], v[122:123]
	v_pk_fma_f32 v[122:123], v[114:115], v[122:123], v[114:115] neg_lo:[1,0,0] neg_hi:[1,0,0]
	v_exp_f32_e32 v124, v124
	v_cndmask_b32_e32 v114, v122, v126, vcc
	v_cmp_gt_f32_e32 vcc, 0, v115
	v_and_b32_e32 v122, 0x7fffffff, v116
	v_exp_f32_e32 v125, v125
	v_cndmask_b32_e32 v115, v123, v127, vcc
	v_and_b32_e32 v123, 0x7fffffff, v117
	v_pk_fma_f32 v[122:123], v[122:123], s[64:65], 1.0 op_sel_hi:[1,0,0]
	v_cmp_gt_f32_e32 vcc, 0, v116
	v_rcp_f32_e32 v122, v122
	v_rcp_f32_e32 v123, v123
	v_lshl_add_u64 v[118:119], v[160:161], 1, v[118:119]
	v_pk_mul_f32 v[102:103], v[102:103], v[0:1] op_sel_hi:[1,0]
	v_pk_mul_f32 v[104:105], v[104:105], v[0:1] op_sel_hi:[1,0]
	v_pk_fma_f32 v[126:127], v[122:123], s[66:67], v[106:107] op_sel_hi:[1,0,0]
	v_pk_mul_f32 v[100:101], v[100:101], v[0:1] op_sel_hi:[1,0]
	v_pk_fma_f32 v[126:127], v[122:123], v[126:127], s[70:71] op_sel_hi:[1,1,0]
	s_nop 0
	v_pk_fma_f32 v[126:127], v[122:123], v[126:127], s[72:73] op_sel_hi:[1,1,0]
	s_nop 0
	v_pk_fma_f32 v[126:127], v[122:123], v[126:127], s[74:75] op_sel_hi:[1,1,0]
	s_nop 0
	v_pk_mul_f32 v[122:123], v[122:123], v[126:127]
	v_pk_mul_f32 v[126:127], v[120:121], v[120:121]
	v_pk_mul_f32 v[122:123], v[124:125], v[122:123]
	v_pk_mul_f32 v[126:127], v[126:127], s[76:77] op_sel_hi:[1,0]
	v_pk_mul_f32 v[124:125], v[116:117], v[122:123]
	v_pk_fma_f32 v[122:123], v[116:117], v[122:123], v[116:117] neg_lo:[1,0,0] neg_hi:[1,0,0]
	v_exp_f32_e32 v126, v126
	v_cndmask_b32_e32 v116, v122, v124, vcc
	v_cmp_gt_f32_e32 vcc, 0, v117
	v_and_b32_e32 v122, 0x7fffffff, v120
	v_exp_f32_e32 v127, v127
	v_cndmask_b32_e32 v117, v123, v125, vcc
	v_and_b32_e32 v123, 0x7fffffff, v121
	v_pk_fma_f32 v[122:123], v[122:123], s[64:65], 1.0 op_sel_hi:[1,0,0]
	v_cmp_gt_f32_e32 vcc, 0, v120
	v_rcp_f32_e32 v122, v122
	v_rcp_f32_e32 v123, v123
	s_nop 0
	v_pk_fma_f32 v[124:125], v[122:123], s[66:67], v[106:107] op_sel_hi:[1,0,0]
	s_nop 0
	v_pk_fma_f32 v[124:125], v[122:123], v[124:125], s[70:71] op_sel_hi:[1,1,0]
	s_nop 0
	v_pk_fma_f32 v[124:125], v[122:123], v[124:125], s[72:73] op_sel_hi:[1,1,0]
	s_nop 0
	v_pk_fma_f32 v[124:125], v[122:123], v[124:125], s[74:75] op_sel_hi:[1,1,0]
	s_nop 0
	v_pk_mul_f32 v[122:123], v[122:123], v[124:125]
	v_pk_mul_f32 v[124:125], v[108:109], v[108:109]
	v_pk_mul_f32 v[122:123], v[126:127], v[122:123]
	v_pk_mul_f32 v[124:125], v[124:125], s[76:77] op_sel_hi:[1,0]
	v_pk_mul_f32 v[126:127], v[120:121], v[122:123]
	v_pk_fma_f32 v[122:123], v[120:121], v[122:123], v[120:121] neg_lo:[1,0,0] neg_hi:[1,0,0]
	v_exp_f32_e32 v124, v124
	v_cndmask_b32_e32 v120, v122, v126, vcc
	v_cmp_gt_f32_e32 vcc, 0, v121
	v_and_b32_e32 v122, 0x7fffffff, v108
	v_exp_f32_e32 v125, v125
	v_cndmask_b32_e32 v121, v123, v127, vcc
	v_and_b32_e32 v123, 0x7fffffff, v109
	v_pk_fma_f32 v[122:123], v[122:123], s[64:65], 1.0 op_sel_hi:[1,0,0]
	v_cmp_gt_f32_e32 vcc, 0, v108
	v_rcp_f32_e32 v122, v122
	v_rcp_f32_e32 v123, v123
	s_nop 0
	v_pk_fma_f32 v[126:127], v[122:123], s[66:67], v[106:107] op_sel_hi:[1,0,0]
	s_nop 0
	v_pk_fma_f32 v[126:127], v[122:123], v[126:127], s[70:71] op_sel_hi:[1,1,0]
	s_nop 0
	v_pk_fma_f32 v[126:127], v[122:123], v[126:127], s[72:73] op_sel_hi:[1,1,0]
	s_nop 0
	v_pk_fma_f32 v[126:127], v[122:123], v[126:127], s[74:75] op_sel_hi:[1,1,0]
	s_nop 0
	v_pk_mul_f32 v[122:123], v[122:123], v[126:127]
	v_pk_mul_f32 v[126:127], v[102:103], v[102:103]
	v_pk_mul_f32 v[122:123], v[124:125], v[122:123]
	v_pk_mul_f32 v[126:127], v[126:127], s[76:77] op_sel_hi:[1,0]
	v_pk_mul_f32 v[124:125], v[108:109], v[122:123]
	v_pk_fma_f32 v[122:123], v[108:109], v[122:123], v[108:109] neg_lo:[1,0,0] neg_hi:[1,0,0]
	v_exp_f32_e32 v126, v126
	v_cndmask_b32_e32 v108, v122, v124, vcc
	v_cmp_gt_f32_e32 vcc, 0, v109
	v_cvt_pk_bf16_f32 v122, v114, v115
	v_exp_f32_e32 v127, v127
	s_nop 0
	v_cndmask_b32_e32 v109, v123, v125, vcc
	v_cvt_pk_bf16_f32 v123, v116, v117
	v_cvt_pk_bf16_f32 v124, v120, v121
	v_cvt_pk_bf16_f32 v125, v108, v109
	global_store_dwordx4 v[118:119], v[122:125], off
	v_cmp_gt_f32_e32 vcc, 0, v102
	s_nop 0
	v_pk_mul_f32 v[122:123], v[98:99], v[0:1] op_sel_hi:[1,0]
	v_and_b32_e32 v99, 0x7fffffff, v103
; __device__ __forceinline__ unsigned cvt_pk_bf16(float lo, float hi) { unsigned r; asm volatile("v_cvt_pk_bf16_f32 %0, %1, %2" : "=v"(r) : "v"(lo), "v"(hi)); return r; }
; __device__ __forceinline__ f32x2 gelu_pk(f32x2 v) {
;     const f32x2 av = __builtin_elementwise_abs(v), d = av * 0.2316418882f + 1.0f;
;     f32x2 t; t.x = __builtin_amdgcn_rcpf(d.x); t.y = __builtin_amdgcn_rcpf(d.y);
;     f32x2 q = t * 0.5307027145f + (-0.7265760135f); q = q * t + 0.7107068705f; q = q * t + (-0.142248368f); q = q * t + 0.127414796f; q = q * t;
;     const f32x2 s = (v * v) * (-0.72134752044f);
;     f32x2 e; e.x = __builtin_amdgcn_exp2f(s.x); e.y = __builtin_amdgcn_exp2f(s.y);
;     const f32x2 m = v * (q * e), r = v - m;
;     f32x2 o; o.x = v.x < 0.f ? m.x : r.x; o.y = v.y < 0.f ? m.y : r.y; return o;
; }
;     __device__ __forceinline__ void operator()(const f32x4 (&acc)[2][2][4][2], const Unit& u, int wr, int wc, int fr, int fq) const {
;     ...
;             for (int m = 0; m < 4; ++m) { const int row = row0 + ai * HALF + m * 16; const float rs = rsv[ai][m]; bf16_t* rowp = O + (size_t)row * ldc + col0; float s1 = 0.f, s2 = 0.f;
; #pragma unroll
;                 for (int bj = 0; bj < 2; ++bj) { f32x4 v0 = acc[ai][bj][m][0] * rs, v1 = acc[ai][bj][m][1] * rs;
;                     const f32x2 a = gelu_pk((f32x2){v0[0], v0[1]}), b = gelu_pk((f32x2){v0[2], v0[3]}), c = gelu_pk((f32x2){v1[0], v1[1]}), d = gelu_pk((f32x2){v1[2], v1[3]});
;                     s1 += ((a.x + a.y) + (b.x + b.y)) + ((c.x + c.y) + (d.x + d.y));
;                     s2 += ((a.x * a.x + a.y * a.y) + (b.x * b.x + b.y * b.y)) + ((c.x * c.x + c.y * c.y) + (d.x * d.x + d.y * d.y));
;                     u32x4 w; w.x = cvt_pk_bf16(a.x, a.y); w.y = cvt_pk_bf16(b.x, b.y); w.z = cvt_pk_bf16(c.x, c.y); w.w = cvt_pk_bf16(d.x, d.y);
;                     *(u32x4*)(rowp + bj * HALF) = w; }
;                 if (isv) { s1 += __shfl_xor(s1, 16); s1 += __shfl_xor(s1, 32); s2 += __shfl_xor(s2, 16); s2 += __shfl_xor(s2, 32);
;                     if (fq == 0) { const int rl = ai * HALF + wr * 64 + m * 16 + fr; part[rl * 4 + wc] = s1; part[1024 + rl * 4 + wc] = s2; } } }
	v_and_b32_e32 v98, 0x7fffffff, v102
	v_pk_fma_f32 v[98:99], v[98:99], s[64:65], 1.0 op_sel_hi:[1,0,0]
	s_nop 0
	v_rcp_f32_e32 v98, v98
	v_rcp_f32_e32 v99, v99
	s_nop 0
	v_pk_fma_f32 v[124:125], v[98:99], s[66:67], v[106:107] op_sel_hi:[1,0,0]
	s_nop 0
	v_pk_fma_f32 v[124:125], v[98:99], v[124:125], s[70:71] op_sel_hi:[1,1,0]
	s_nop 0
	v_pk_fma_f32 v[124:125], v[98:99], v[124:125], s[72:73] op_sel_hi:[1,1,0]
	s_nop 0
	v_pk_fma_f32 v[124:125], v[98:99], v[124:125], s[74:75] op_sel_hi:[1,1,0]
	s_nop 0
	v_pk_mul_f32 v[98:99], v[98:99], v[124:125]
	v_pk_mul_f32 v[124:125], v[104:105], v[104:105]
	v_pk_mul_f32 v[98:99], v[126:127], v[98:99]
	v_pk_mul_f32 v[124:125], v[124:125], s[76:77] op_sel_hi:[1,0]
	v_pk_mul_f32 v[126:127], v[102:103], v[98:99]
	v_pk_fma_f32 v[98:99], v[102:103], v[98:99], v[102:103] neg_lo:[1,0,0] neg_hi:[1,0,0]
	v_and_b32_e32 v102, 0x7fffffff, v104
	v_cndmask_b32_e32 v0, v98, v126, vcc
	v_cmp_gt_f32_e32 vcc, 0, v103
	v_and_b32_e32 v103, 0x7fffffff, v105
	v_pk_fma_f32 v[102:103], v[102:103], s[64:65], 1.0 op_sel_hi:[1,0,0]
	v_cndmask_b32_e32 v98, v99, v127, vcc
	v_rcp_f32_e32 v102, v102
	v_rcp_f32_e32 v103, v103
	v_exp_f32_e32 v124, v124
	v_exp_f32_e32 v125, v125
	v_cmp_gt_f32_e32 vcc, 0, v104
	v_pk_fma_f32 v[126:127], v[102:103], s[66:67], v[106:107] op_sel_hi:[1,0,0]
	s_nop 0
	v_pk_fma_f32 v[126:127], v[102:103], v[126:127], s[70:71] op_sel_hi:[1,1,0]
	s_nop 0
	v_pk_fma_f32 v[126:127], v[102:103], v[126:127], s[72:73] op_sel_hi:[1,1,0]
	s_nop 0
	v_pk_fma_f32 v[126:127], v[102:103], v[126:127], s[74:75] op_sel_hi:[1,1,0]
	s_nop 0
	v_pk_mul_f32 v[102:103], v[102:103], v[126:127]
	v_pk_mul_f32 v[126:127], v[122:123], v[122:123]
	v_pk_mul_f32 v[102:103], v[124:125], v[102:103]
	v_pk_mul_f32 v[126:127], v[126:127], s[76:77] op_sel_hi:[1,0]
	v_pk_mul_f32 v[124:125], v[104:105], v[102:103]
	v_pk_fma_f32 v[102:103], v[104:105], v[102:103], v[104:105] neg_lo:[1,0,0] neg_hi:[1,0,0]
	v_and_b32_e32 v104, 0x7fffffff, v122
	v_cndmask_b32_e32 v99, v102, v124, vcc
	v_cmp_gt_f32_e32 vcc, 0, v105
	v_and_b32_e32 v105, 0x7fffffff, v123
	v_pk_fma_f32 v[104:105], v[104:105], s[64:65], 1.0 op_sel_hi:[1,0,0]
	v_cndmask_b32_e32 v102, v103, v125, vcc
	v_rcp_f32_e32 v104, v104
	v_rcp_f32_e32 v105, v105
	v_exp_f32_e32 v126, v126
	v_exp_f32_e32 v127, v127
	v_cmp_gt_f32_e32 vcc, 0, v122
	v_pk_fma_f32 v[124:125], v[104:105], s[66:67], v[106:107] op_sel_hi:[1,0,0]
	s_nop 0
	v_pk_fma_f32 v[124:125], v[104:105], v[124:125], s[70:71] op_sel_hi:[1,1,0]
	s_nop 0
	v_pk_fma_f32 v[124:125], v[104:105], v[124:125], s[72:73] op_sel_hi:[1,1,0]
	s_nop 0
	v_pk_fma_f32 v[124:125], v[104:105], v[124:125], s[74:75] op_sel_hi:[1,1,0]
	s_nop 0
	v_pk_mul_f32 v[104:105], v[104:105], v[124:125]
	v_pk_mul_f32 v[124:125], v[100:101], v[100:101]
	v_pk_mul_f32 v[104:105], v[126:127], v[104:105]
	s_nop 0
	v_pk_mul_f32 v[126:127], v[122:123], v[104:105]
	v_pk_fma_f32 v[104:105], v[122:123], v[104:105], v[122:123] neg_lo:[1,0,0] neg_hi:[1,0,0]
	v_and_b32_e32 v122, 0x7fffffff, v100
	v_cndmask_b32_e32 v103, v104, v126, vcc
	v_cmp_gt_f32_e32 vcc, 0, v123
	v_and_b32_e32 v123, 0x7fffffff, v101
	v_pk_fma_f32 v[122:123], v[122:123], s[64:65], 1.0 op_sel_hi:[1,0,0]
	v_cndmask_b32_e32 v104, v105, v127, vcc
	v_rcp_f32_e32 v122, v122
	v_rcp_f32_e32 v123, v123
	v_cmp_gt_f32_e32 vcc, 0, v100
	v_pk_fma_f32 v[106:107], v[122:123], s[66:67], v[106:107] op_sel_hi:[1,0,0]
	s_nop 0
	v_pk_fma_f32 v[106:107], v[122:123], v[106:107], s[70:71] op_sel_hi:[1,1,0]
	s_nop 0
	v_pk_fma_f32 v[106:107], v[122:123], v[106:107], s[72:73] op_sel_hi:[1,1,0]
	s_nop 0
	v_pk_fma_f32 v[106:107], v[122:123], v[106:107], s[74:75] op_sel_hi:[1,1,0]
	s_nop 0
	v_pk_mul_f32 v[106:107], v[122:123], v[106:107]
	v_pk_mul_f32 v[122:123], v[124:125], s[76:77] op_sel_hi:[1,0]
	s_nop 0
	v_exp_f32_e32 v122, v122
	v_exp_f32_e32 v123, v123
	s_nop 0
	v_pk_mul_f32 v[106:107], v[122:123], v[106:107]
	s_nop 0
	v_pk_mul_f32 v[122:123], v[100:101], v[106:107]
	v_pk_fma_f32 v[106:107], v[100:101], v[106:107], v[100:101] neg_lo:[1,0,0] neg_hi:[1,0,0]
	s_nop 0
	v_cndmask_b32_e32 v100, v106, v122, vcc
	v_cmp_gt_f32_e32 vcc, 0, v101
	v_cvt_pk_bf16_f32 v122, v0, v98
	s_nop 1
	v_cndmask_b32_e32 v101, v107, v123, vcc
	s_and_b64 vcc, exec, s[10:11]
	v_cvt_pk_bf16_f32 v123, v99, v102
	v_cvt_pk_bf16_f32 v124, v103, v104
	v_cvt_pk_bf16_f32 v125, v100, v101
	global_store_dwordx4 v[118:119], v[122:125], off offset:256
	s_cbranch_vccnz .LBB0_364
	v_mul_f32_e32 v105, v115, v115
	v_mul_f32_e32 v106, v117, v117
	v_fmac_f32_e32 v105, v114, v114
	v_fmac_f32_e32 v106, v116, v116
	v_add_f32_e32 v105, v105, v106
	v_mul_f32_e32 v106, v121, v121
	v_mul_f32_e32 v107, v109, v109
	v_fmac_f32_e32 v106, v120, v120
	v_fmac_f32_e32 v107, v108, v108
	v_add_f32_e32 v106, v106, v107
	v_add_f32_e32 v105, v105, v106
	v_mul_f32_e32 v106, v98, v98
	v_fmac_f32_e32 v106, v0, v0
	v_mul_f32_e32 v107, v102, v102
	v_add_f32_e32 v0, v0, v98
	v_add_f32_e32 v98, v99, v102
	v_fmac_f32_e32 v107, v99, v99
	v_add_f32_e32 v114, v114, v115
	v_add_f32_e32 v115, v116, v117
	v_add_f32_e32 v0, v0, v98
	v_add_f32_e32 v98, v103, v104
	v_add_f32_e32 v99, v100, v101
	v_add_f32_e32 v114, v114, v115
	v_add_f32_e32 v115, v120, v121
	v_add_f32_e32 v108, v108, v109
	v_add_f32_e32 v98, v98, v99
	v_and_b32_e32 v99, 64, v226
	v_add_f32_e32 v108, v115, v108
	v_add_f32_e32 v0, v0, v98
	v_xor_b32_e32 v98, 16, v226
	v_add_u32_e32 v99, 64, v99
	v_add_f32_e32 v108, v114, v108
	v_cmp_lt_i32_e32 vcc, v98, v99
	v_add_f32_e32 v106, v106, v107
	v_mul_f32_e32 v107, v104, v104
	v_mul_f32_e32 v118, v101, v101
	v_add_f32_e32 v108, 0, v108
	v_cndmask_b32_e32 v98, v226, v98, vcc
	v_fmac_f32_e32 v107, v103, v103
	v_add_f32_e32 v0, v0, v108
	v_lshlrev_b32_e32 v98, 2, v98
	v_fmac_f32_e32 v118, v100, v100
	v_mov_b32_e32 v101, v0
	s_nop 1
	v_permlane16_swap_b32_e32 v101, v0
	v_add_f32_e32 v100, v107, v118
	v_add_f32_e32 v100, v106, v100
	v_add_f32_e32 v100, v105, v100
	v_mov_b32_e32 v102, v100
	s_nop 1
	v_permlane16_swap_b32_e32 v102, v100
	s_waitcnt lgkmcnt(0)
	v_add_f32_e32 v0, v0, v101
	v_xor_b32_e32 v101, 32, v226
	v_cmp_lt_i32_e32 vcc, v101, v99
	v_add_f32_e32 v99, v100, v102
	s_nop 0
	v_cndmask_b32_e32 v98, v226, v101, vcc
	v_lshlrev_b32_e32 v101, 2, v98
	v_mov_b32_e32 v98, v0
	s_nop 1
	v_permlane32_swap_b32_e32 v98, v0
	v_mov_b32_e32 v100, v99
	s_nop 1
	v_permlane32_swap_b32_e32 v100, v99
	s_and_saveexec_b64 s[4:5], s[6:7]
	s_cbranch_execz .LBB0_363
	s_waitcnt lgkmcnt(0)
	v_add_f32_e32 v99, v99, v100
	v_add_f32_e32 v0, v0, v98
	ds_write2st64_b32 v186, v0, v99 offset0:2 offset1:18

; __device__ __forceinline__ unsigned cvt_pk_bf16(float lo, float hi) { unsigned r; asm volatile("v_cvt_pk_bf16_f32 %0, %1, %2" : "=v"(r) : "v"(lo), "v"(hi)); return r; }
; __device__ __forceinline__ f32x2 gelu_pk(f32x2 v) {
;     const f32x2 av = __builtin_elementwise_abs(v), d = av * 0.2316418882f + 1.0f;
;     f32x2 t; t.x = __builtin_amdgcn_rcpf(d.x); t.y = __builtin_amdgcn_rcpf(d.y);
;     f32x2 q = t * 0.5307027145f + (-0.7265760135f); q = q * t + 0.7107068705f; q = q * t + (-0.142248368f); q = q * t + 0.127414796f; q = q * t;
;     const f32x2 s = (v * v) * (-0.72134752044f);
;     f32x2 e; e.x = __builtin_amdgcn_exp2f(s.x); e.y = __builtin_amdgcn_exp2f(s.y);
;     const f32x2 m = v * (q * e), r = v - m;
;     f32x2 o; o.x = v.x < 0.f ? m.x : r.x; o.y = v.y < 0.f ? m.y : r.y; return o;
; }
; __device__ __forceinline__ void rstd8(const float* ss, int row0, float (&rs)[2][4]) {
;     ...
;         for (int m = 0; m < 4; ++m) p[ai][m] = *(const f32x4*)(ss + 4 * (size_t)(row0 + ai * HALF + m * 16));
; #pragma unroll
;     for (int ai = 0; ai < 2; ++ai)
; #pragma unroll
;         for (int m = 0; m < 4; ++m) rs[ai][m] = __builtin_amdgcn_rsqf(((p[ai][m].x + p[ai][m].y) + (p[ai][m].z + p[ai][m].w)) * (1.0f / D) + EPS);
;     __device__ __forceinline__ void operator()(const f32x4 (&acc)[2][2][4][2], const Unit& u, int wr, int wc, int fr, int fq) const {
;     ...
;             for (int m = 0; m < 4; ++m) { const int row = row0 + ai * HALF + m * 16; const float rs = rsv[ai][m]; bf16_t* rowp = O + (size_t)row * ldc + col0; float s1 = 0.f, s2 = 0.f;
; #pragma unroll
;                 for (int bj = 0; bj < 2; ++bj) { f32x4 v0 = acc[ai][bj][m][0] * rs, v1 = acc[ai][bj][m][1] * rs;
;                     const f32x2 a = gelu_pk((f32x2){v0[0], v0[1]}), b = gelu_pk((f32x2){v0[2], v0[3]}), c = gelu_pk((f32x2){v1[0], v1[1]}), d = gelu_pk((f32x2){v1[2], v1[3]});
;                     s1 += ((a.x + a.y) + (b.x + b.y)) + ((c.x + c.y) + (d.x + d.y));
;                     s2 += ((a.x * a.x + a.y * a.y) + (b.x * b.x + b.y * b.y)) + ((c.x * c.x + c.y * c.y) + (d.x * d.x + d.y * d.y));
;                     u32x4 w; w.x = cvt_pk_bf16(a.x, a.y); w.y = cvt_pk_bf16(b.x, b.y); w.z = cvt_pk_bf16(c.x, c.y); w.w = cvt_pk_bf16(d.x, d.y);
;                     *(u32x4*)(rowp + bj * HALF) = w; }
.LBB0_364:
	v_add_f32_e32 v0, v110, v111
	s_waitcnt lgkmcnt(0)
	v_add_f32_e32 v98, v112, v113
	v_add_f32_e32 v0, v0, v98
	v_fmamk_f32 v0, v0, 0x3a800000, v224
	v_rsq_f32_e32 v0, v0
	s_mov_b32 s4, 0xbf3a00e3
	v_lshlrev_b64 v[98:99], 12, v[170:171]
	v_lshl_add_u64 v[98:99], s[20:21], 0, v[98:99]
	v_pk_mul_f32 v[90:91], v[90:91], v[0:1] op_sel_hi:[1,0]
	v_pk_mul_f32 v[100:101], v[86:87], v[0:1] op_sel_hi:[1,0]
	v_and_b32_e32 v87, 0x7fffffff, v91
	v_and_b32_e32 v86, 0x7fffffff, v90
	v_pk_fma_f32 v[86:87], v[86:87], s[64:65], 1.0 op_sel_hi:[1,0,0]
	v_pk_mul_f32 v[106:107], v[90:91], v[90:91]
	v_rcp_f32_e32 v102, v86
	v_rcp_f32_e32 v103, v87
	v_mov_b64_e32 v[86:87], s[4:5]
	v_pk_mul_f32 v[106:107], v[106:107], s[76:77] op_sel_hi:[1,0]
	v_cmp_gt_f32_e32 vcc, 0, v90
	v_pk_fma_f32 v[104:105], v[102:103], s[66:67], v[86:87] op_sel_hi:[1,0,0]
	v_exp_f32_e32 v106, v106
	v_pk_fma_f32 v[104:105], v[102:103], v[104:105], s[70:71] op_sel_hi:[1,1,0]
	v_exp_f32_e32 v107, v107
	v_pk_fma_f32 v[104:105], v[102:103], v[104:105], s[72:73] op_sel_hi:[1,1,0]
	v_pk_mul_f32 v[92:93], v[92:93], v[0:1] op_sel_hi:[1,0]
	v_pk_fma_f32 v[104:105], v[102:103], v[104:105], s[74:75] op_sel_hi:[1,1,0]
	v_pk_mul_f32 v[88:89], v[88:89], v[0:1] op_sel_hi:[1,0]
	v_pk_mul_f32 v[102:103], v[102:103], v[104:105]
	v_pk_mul_f32 v[104:105], v[92:93], v[92:93]
	v_pk_mul_f32 v[102:103], v[106:107], v[102:103]
	v_pk_mul_f32 v[104:105], v[104:105], s[76:77] op_sel_hi:[1,0]
	v_pk_mul_f32 v[106:107], v[90:91], v[102:103]
	v_pk_fma_f32 v[102:103], v[90:91], v[102:103], v[90:91] neg_lo:[1,0,0] neg_hi:[1,0,0]
	v_exp_f32_e32 v104, v104
	v_cndmask_b32_e32 v90, v102, v106, vcc
	v_cmp_gt_f32_e32 vcc, 0, v91
	v_and_b32_e32 v102, 0x7fffffff, v92
	v_exp_f32_e32 v105, v105
	v_cndmask_b32_e32 v91, v103, v107, vcc
	v_and_b32_e32 v103, 0x7fffffff, v93
	v_pk_fma_f32 v[102:103], v[102:103], s[64:65], 1.0 op_sel_hi:[1,0,0]
	v_cmp_gt_f32_e32 vcc, 0, v92
	v_rcp_f32_e32 v102, v102
	v_rcp_f32_e32 v103, v103
	v_lshl_add_u64 v[98:99], v[160:161], 1, v[98:99]
	v_pk_mul_f32 v[82:83], v[82:83], v[0:1] op_sel_hi:[1,0]
	v_pk_mul_f32 v[84:85], v[84:85], v[0:1] op_sel_hi:[1,0]
	v_pk_fma_f32 v[106:107], v[102:103], s[66:67], v[86:87] op_sel_hi:[1,0,0]
	v_pk_mul_f32 v[80:81], v[80:81], v[0:1] op_sel_hi:[1,0]
	v_pk_fma_f32 v[106:107], v[102:103], v[106:107], s[70:71] op_sel_hi:[1,1,0]
	s_nop 0
	v_pk_fma_f32 v[106:107], v[102:103], v[106:107], s[72:73] op_sel_hi:[1,1,0]
	s_nop 0
	v_pk_fma_f32 v[106:107], v[102:103], v[106:107], s[74:75] op_sel_hi:[1,1,0]
	s_nop 0
	v_pk_mul_f32 v[102:103], v[102:103], v[106:107]
	v_pk_mul_f32 v[106:107], v[100:101], v[100:101]
	v_pk_mul_f32 v[102:103], v[104:105], v[102:103]
	v_pk_mul_f32 v[106:107], v[106:107], s[76:77] op_sel_hi:[1,0]
	v_pk_mul_f32 v[104:105], v[92:93], v[102:103]
	v_pk_fma_f32 v[102:103], v[92:93], v[102:103], v[92:93] neg_lo:[1,0,0] neg_hi:[1,0,0]
	v_exp_f32_e32 v106, v106
	v_cndmask_b32_e32 v92, v102, v104, vcc
	v_cmp_gt_f32_e32 vcc, 0, v93
	v_and_b32_e32 v102, 0x7fffffff, v100
	v_exp_f32_e32 v107, v107
	v_cndmask_b32_e32 v93, v103, v105, vcc
	v_and_b32_e32 v103, 0x7fffffff, v101
	v_pk_fma_f32 v[102:103], v[102:103], s[64:65], 1.0 op_sel_hi:[1,0,0]
	v_cmp_gt_f32_e32 vcc, 0, v100
	v_rcp_f32_e32 v102, v102
	v_rcp_f32_e32 v103, v103
	s_nop 0
	v_pk_fma_f32 v[104:105], v[102:103], s[66:67], v[86:87] op_sel_hi:[1,0,0]
	s_nop 0
	v_pk_fma_f32 v[104:105], v[102:103], v[104:105], s[70:71] op_sel_hi:[1,1,0]
	s_nop 0
	v_pk_fma_f32 v[104:105], v[102:103], v[104:105], s[72:73] op_sel_hi:[1,1,0]
	s_nop 0
	v_pk_fma_f32 v[104:105], v[102:103], v[104:105], s[74:75] op_sel_hi:[1,1,0]
	s_nop 0
	v_pk_mul_f32 v[102:103], v[102:103], v[104:105]
	v_pk_mul_f32 v[104:105], v[88:89], v[88:89]
	v_pk_mul_f32 v[102:103], v[106:107], v[102:103]
	v_pk_mul_f32 v[104:105], v[104:105], s[76:77] op_sel_hi:[1,0]
	v_pk_mul_f32 v[106:107], v[100:101], v[102:103]
	v_pk_fma_f32 v[102:103], v[100:101], v[102:103], v[100:101] neg_lo:[1,0,0] neg_hi:[1,0,0]
	v_exp_f32_e32 v104, v104
	v_cndmask_b32_e32 v100, v102, v106, vcc
	v_cmp_gt_f32_e32 vcc, 0, v101
	v_and_b32_e32 v102, 0x7fffffff, v88
	v_exp_f32_e32 v105, v105
	v_cndmask_b32_e32 v101, v103, v107, vcc
	v_and_b32_e32 v103, 0x7fffffff, v89
	v_pk_fma_f32 v[102:103], v[102:103], s[64:65], 1.0 op_sel_hi:[1,0,0]
	v_cmp_gt_f32_e32 vcc, 0, v88
	v_rcp_f32_e32 v102, v102
	v_rcp_f32_e32 v103, v103
	s_nop 0
	v_pk_fma_f32 v[106:107], v[102:103], s[66:67], v[86:87] op_sel_hi:[1,0,0]
	s_nop 0
	v_pk_fma_f32 v[106:107], v[102:103], v[106:107], s[70:71] op_sel_hi:[1,1,0]
	s_nop 0
	v_pk_fma_f32 v[106:107], v[102:103], v[106:107], s[72:73] op_sel_hi:[1,1,0]
	s_nop 0
	v_pk_fma_f32 v[106:107], v[102:103], v[106:107], s[74:75] op_sel_hi:[1,1,0]
	s_nop 0
	v_pk_mul_f32 v[102:103], v[102:103], v[106:107]
	v_pk_mul_f32 v[106:107], v[82:83], v[82:83]
	v_pk_mul_f32 v[102:103], v[104:105], v[102:103]
	v_pk_mul_f32 v[106:107], v[106:107], s[76:77] op_sel_hi:[1,0]
	v_pk_mul_f32 v[104:105], v[88:89], v[102:103]
	v_pk_fma_f32 v[102:103], v[88:89], v[102:103], v[88:89] neg_lo:[1,0,0] neg_hi:[1,0,0]
	v_exp_f32_e32 v106, v106
	v_cndmask_b32_e32 v88, v102, v104, vcc
	v_cmp_gt_f32_e32 vcc, 0, v89
	v_cvt_pk_bf16_f32 v102, v90, v91
	v_exp_f32_e32 v107, v107
	s_nop 0
	v_cndmask_b32_e32 v89, v103, v105, vcc
	v_cvt_pk_bf16_f32 v103, v92, v93
	v_cvt_pk_bf16_f32 v104, v100, v101
	v_cvt_pk_bf16_f32 v105, v88, v89
	global_store_dwordx4 v[98:99], v[102:105], off
	v_cmp_gt_f32_e32 vcc, 0, v82
	s_nop 0
	v_pk_mul_f32 v[102:103], v[78:79], v[0:1] op_sel_hi:[1,0]
	v_and_b32_e32 v79, 0x7fffffff, v83
	v_and_b32_e32 v78, 0x7fffffff, v82
	v_pk_fma_f32 v[78:79], v[78:79], s[64:65], 1.0 op_sel_hi:[1,0,0]
	s_nop 0
; __device__ __forceinline__ unsigned cvt_pk_bf16(float lo, float hi) { unsigned r; asm volatile("v_cvt_pk_bf16_f32 %0, %1, %2" : "=v"(r) : "v"(lo), "v"(hi)); return r; }
; __device__ __forceinline__ f32x2 gelu_pk(f32x2 v) {
;     const f32x2 av = __builtin_elementwise_abs(v), d = av * 0.2316418882f + 1.0f;
;     f32x2 t; t.x = __builtin_amdgcn_rcpf(d.x); t.y = __builtin_amdgcn_rcpf(d.y);
;     f32x2 q = t * 0.5307027145f + (-0.7265760135f); q = q * t + 0.7107068705f; q = q * t + (-0.142248368f); q = q * t + 0.127414796f; q = q * t;
;     const f32x2 s = (v * v) * (-0.72134752044f);
;     f32x2 e; e.x = __builtin_amdgcn_exp2f(s.x); e.y = __builtin_amdgcn_exp2f(s.y);
;     const f32x2 m = v * (q * e), r = v - m;
;     f32x2 o; o.x = v.x < 0.f ? m.x : r.x; o.y = v.y < 0.f ? m.y : r.y; return o;
;     __device__ __forceinline__ void operator()(const f32x4 (&acc)[2][2][4][2], const Unit& u, int wr, int wc, int fr, int fq) const {
;     ...
;                 for (int bj = 0; bj < 2; ++bj) { f32x4 v0 = acc[ai][bj][m][0] * rs, v1 = acc[ai][bj][m][1] * rs;
;                     const f32x2 a = gelu_pk((f32x2){v0[0], v0[1]}), b = gelu_pk((f32x2){v0[2], v0[3]}), c = gelu_pk((f32x2){v1[0], v1[1]}), d = gelu_pk((f32x2){v1[2], v1[3]});
;                     s1 += ((a.x + a.y) + (b.x + b.y)) + ((c.x + c.y) + (d.x + d.y));
;                     s2 += ((a.x * a.x + a.y * a.y) + (b.x * b.x + b.y * b.y)) + ((c.x * c.x + c.y * c.y) + (d.x * d.x + d.y * d.y));
;                     u32x4 w; w.x = cvt_pk_bf16(a.x, a.y); w.y = cvt_pk_bf16(b.x, b.y); w.z = cvt_pk_bf16(c.x, c.y); w.w = cvt_pk_bf16(d.x, d.y);
;                     *(u32x4*)(rowp + bj * HALF) = w; }
;                 if (isv) { s1 += __shfl_xor(s1, 16); s1 += __shfl_xor(s1, 32); s2 += __shfl_xor(s2, 16); s2 += __shfl_xor(s2, 32);
;                     if (fq == 0) { const int rl = ai * HALF + wr * 64 + m * 16 + fr; part[rl * 4 + wc] = s1; part[1024 + rl * 4 + wc] = s2; } } }
	v_rcp_f32_e32 v78, v78
	v_rcp_f32_e32 v79, v79
	s_nop 0
	v_pk_fma_f32 v[104:105], v[78:79], s[66:67], v[86:87] op_sel_hi:[1,0,0]
	s_nop 0
	v_pk_fma_f32 v[104:105], v[78:79], v[104:105], s[70:71] op_sel_hi:[1,1,0]
	s_nop 0
	v_pk_fma_f32 v[104:105], v[78:79], v[104:105], s[72:73] op_sel_hi:[1,1,0]
	s_nop 0
	v_pk_fma_f32 v[104:105], v[78:79], v[104:105], s[74:75] op_sel_hi:[1,1,0]
	s_nop 0
	v_pk_mul_f32 v[78:79], v[78:79], v[104:105]
	v_pk_mul_f32 v[104:105], v[84:85], v[84:85]
	v_pk_mul_f32 v[78:79], v[106:107], v[78:79]
	v_pk_mul_f32 v[104:105], v[104:105], s[76:77] op_sel_hi:[1,0]
	v_pk_mul_f32 v[106:107], v[82:83], v[78:79]
	v_pk_fma_f32 v[78:79], v[82:83], v[78:79], v[82:83] neg_lo:[1,0,0] neg_hi:[1,0,0]
	v_and_b32_e32 v82, 0x7fffffff, v84
	v_cndmask_b32_e32 v0, v78, v106, vcc
	v_cmp_gt_f32_e32 vcc, 0, v83
	v_and_b32_e32 v83, 0x7fffffff, v85
	v_pk_fma_f32 v[82:83], v[82:83], s[64:65], 1.0 op_sel_hi:[1,0,0]
	v_cndmask_b32_e32 v78, v79, v107, vcc
	v_rcp_f32_e32 v82, v82
	v_rcp_f32_e32 v83, v83
	v_exp_f32_e32 v104, v104
	v_exp_f32_e32 v105, v105
	v_cmp_gt_f32_e32 vcc, 0, v84
	v_pk_fma_f32 v[106:107], v[82:83], s[66:67], v[86:87] op_sel_hi:[1,0,0]
	s_nop 0
	v_pk_fma_f32 v[106:107], v[82:83], v[106:107], s[70:71] op_sel_hi:[1,1,0]
	s_nop 0
	v_pk_fma_f32 v[106:107], v[82:83], v[106:107], s[72:73] op_sel_hi:[1,1,0]
	s_nop 0
	v_pk_fma_f32 v[106:107], v[82:83], v[106:107], s[74:75] op_sel_hi:[1,1,0]
	s_nop 0
	v_pk_mul_f32 v[82:83], v[82:83], v[106:107]
	v_pk_mul_f32 v[106:107], v[102:103], v[102:103]
	v_pk_mul_f32 v[82:83], v[104:105], v[82:83]
	v_pk_mul_f32 v[106:107], v[106:107], s[76:77] op_sel_hi:[1,0]
	v_pk_mul_f32 v[104:105], v[84:85], v[82:83]
	v_pk_fma_f32 v[82:83], v[84:85], v[82:83], v[84:85] neg_lo:[1,0,0] neg_hi:[1,0,0]
	v_and_b32_e32 v84, 0x7fffffff, v102
	v_cndmask_b32_e32 v79, v82, v104, vcc
	v_cmp_gt_f32_e32 vcc, 0, v85
	v_and_b32_e32 v85, 0x7fffffff, v103
	v_pk_fma_f32 v[84:85], v[84:85], s[64:65], 1.0 op_sel_hi:[1,0,0]
	v_cndmask_b32_e32 v82, v83, v105, vcc
	v_rcp_f32_e32 v84, v84
	v_rcp_f32_e32 v85, v85
	v_exp_f32_e32 v106, v106
	v_exp_f32_e32 v107, v107
	v_cmp_gt_f32_e32 vcc, 0, v102
	v_pk_fma_f32 v[104:105], v[84:85], s[66:67], v[86:87] op_sel_hi:[1,0,0]
	s_nop 0
	v_pk_fma_f32 v[104:105], v[84:85], v[104:105], s[70:71] op_sel_hi:[1,1,0]
	s_nop 0
	v_pk_fma_f32 v[104:105], v[84:85], v[104:105], s[72:73] op_sel_hi:[1,1,0]
	s_nop 0
	v_pk_fma_f32 v[104:105], v[84:85], v[104:105], s[74:75] op_sel_hi:[1,1,0]
	s_nop 0
	v_pk_mul_f32 v[84:85], v[84:85], v[104:105]
	v_pk_mul_f32 v[104:105], v[80:81], v[80:81]
	v_pk_mul_f32 v[84:85], v[106:107], v[84:85]
	s_nop 0
	v_pk_mul_f32 v[106:107], v[102:103], v[84:85]
	v_pk_fma_f32 v[84:85], v[102:103], v[84:85], v[102:103] neg_lo:[1,0,0] neg_hi:[1,0,0]
	v_and_b32_e32 v102, 0x7fffffff, v80
	v_cndmask_b32_e32 v83, v84, v106, vcc
	v_cmp_gt_f32_e32 vcc, 0, v103
	v_and_b32_e32 v103, 0x7fffffff, v81
	v_pk_fma_f32 v[102:103], v[102:103], s[64:65], 1.0 op_sel_hi:[1,0,0]
	v_cndmask_b32_e32 v84, v85, v107, vcc
	v_rcp_f32_e32 v102, v102
	v_rcp_f32_e32 v103, v103
	v_cmp_gt_f32_e32 vcc, 0, v80
	v_pk_fma_f32 v[86:87], v[102:103], s[66:67], v[86:87] op_sel_hi:[1,0,0]
	s_nop 0
	v_pk_fma_f32 v[86:87], v[102:103], v[86:87], s[70:71] op_sel_hi:[1,1,0]
	s_nop 0
	v_pk_fma_f32 v[86:87], v[102:103], v[86:87], s[72:73] op_sel_hi:[1,1,0]
	s_nop 0
	v_pk_fma_f32 v[86:87], v[102:103], v[86:87], s[74:75] op_sel_hi:[1,1,0]
	s_nop 0
	v_pk_mul_f32 v[86:87], v[102:103], v[86:87]
	v_pk_mul_f32 v[102:103], v[104:105], s[76:77] op_sel_hi:[1,0]
	s_nop 0
	v_exp_f32_e32 v102, v102
	v_exp_f32_e32 v103, v103
	s_nop 0
	v_pk_mul_f32 v[86:87], v[102:103], v[86:87]
	s_nop 0
	v_pk_mul_f32 v[102:103], v[80:81], v[86:87]
	v_pk_fma_f32 v[86:87], v[80:81], v[86:87], v[80:81] neg_lo:[1,0,0] neg_hi:[1,0,0]
	s_nop 0
	v_cndmask_b32_e32 v80, v86, v102, vcc
	v_cmp_gt_f32_e32 vcc, 0, v81
	v_cvt_pk_bf16_f32 v102, v0, v78
	s_nop 1
	v_cndmask_b32_e32 v81, v87, v103, vcc
	s_and_b64 vcc, exec, s[10:11]
	v_cvt_pk_bf16_f32 v103, v79, v82
	v_cvt_pk_bf16_f32 v104, v83, v84
	v_cvt_pk_bf16_f32 v105, v80, v81
	global_store_dwordx4 v[98:99], v[102:105], off offset:256
	s_cbranch_vccnz .LBB0_368
	v_mul_f32_e32 v85, v91, v91
	v_mul_f32_e32 v86, v93, v93
	v_fmac_f32_e32 v85, v90, v90
	v_fmac_f32_e32 v86, v92, v92
	v_add_f32_e32 v85, v85, v86
	v_mul_f32_e32 v86, v101, v101
	v_mul_f32_e32 v87, v89, v89
	v_fmac_f32_e32 v86, v100, v100
	v_fmac_f32_e32 v87, v88, v88
	v_add_f32_e32 v86, v86, v87
	v_add_f32_e32 v85, v85, v86
	v_mul_f32_e32 v86, v78, v78
	v_fmac_f32_e32 v86, v0, v0
	v_mul_f32_e32 v87, v82, v82
	v_add_f32_e32 v0, v0, v78
	v_add_f32_e32 v78, v79, v82
	v_fmac_f32_e32 v87, v79, v79
	v_add_f32_e32 v90, v90, v91
	v_add_f32_e32 v91, v92, v93
	v_add_f32_e32 v0, v0, v78
	v_add_f32_e32 v78, v83, v84
	v_add_f32_e32 v79, v80, v81
	v_add_f32_e32 v90, v90, v91
	v_add_f32_e32 v91, v100, v101
	v_add_f32_e32 v88, v88, v89
	v_add_f32_e32 v78, v78, v79
	v_and_b32_e32 v79, 64, v226
	v_add_f32_e32 v88, v91, v88
	v_add_f32_e32 v0, v0, v78
	v_xor_b32_e32 v78, 16, v226
	v_add_u32_e32 v79, 64, v79
	v_add_f32_e32 v88, v90, v88
	v_cmp_lt_i32_e32 vcc, v78, v79
	v_add_f32_e32 v86, v86, v87
	v_mul_f32_e32 v87, v84, v84
	v_mul_f32_e32 v98, v81, v81
	v_add_f32_e32 v88, 0, v88
	v_cndmask_b32_e32 v78, v226, v78, vcc
	v_fmac_f32_e32 v87, v83, v83
	v_add_f32_e32 v0, v0, v88
	v_lshlrev_b32_e32 v78, 2, v78
	v_fmac_f32_e32 v98, v80, v80
	v_mov_b32_e32 v81, v0
	s_nop 1
	v_permlane16_swap_b32_e32 v81, v0
	v_add_f32_e32 v80, v87, v98
	v_add_f32_e32 v80, v86, v80
	v_add_f32_e32 v80, v85, v80
	v_mov_b32_e32 v82, v80
	s_nop 1
	v_permlane16_swap_b32_e32 v82, v80
	s_waitcnt lgkmcnt(0)
	v_add_f32_e32 v0, v0, v81
	v_xor_b32_e32 v81, 32, v226
	v_cmp_lt_i32_e32 vcc, v81, v79
	v_add_f32_e32 v79, v80, v82
	s_nop 0
	v_cndmask_b32_e32 v78, v226, v81, vcc
	v_lshlrev_b32_e32 v81, 2, v78
	v_mov_b32_e32 v78, v0
	s_nop 1
	v_permlane32_swap_b32_e32 v78, v0
	v_mov_b32_e32 v80, v79
	s_nop 1
	v_permlane32_swap_b32_e32 v80, v79
	s_and_saveexec_b64 s[4:5], s[6:7]
	s_cbranch_execz .LBB0_367
	s_waitcnt lgkmcnt(0)
	v_add_f32_e32 v79, v79, v80
	v_add_f32_e32 v0, v0, v78
	ds_write2st64_b32 v186, v0, v79 offset0:3 offset1:19

; __device__ __forceinline__ unsigned cvt_pk_bf16(float lo, float hi) { unsigned r; asm volatile("v_cvt_pk_bf16_f32 %0, %1, %2" : "=v"(r) : "v"(lo), "v"(hi)); return r; }
; __device__ __forceinline__ f32x2 gelu_pk(f32x2 v) {
;     const f32x2 av = __builtin_elementwise_abs(v), d = av * 0.2316418882f + 1.0f;
;     f32x2 t; t.x = __builtin_amdgcn_rcpf(d.x); t.y = __builtin_amdgcn_rcpf(d.y);
;     f32x2 q = t * 0.5307027145f + (-0.7265760135f); q = q * t + 0.7107068705f; q = q * t + (-0.142248368f); q = q * t + 0.127414796f; q = q * t;
;     const f32x2 s = (v * v) * (-0.72134752044f);
;     f32x2 e; e.x = __builtin_amdgcn_exp2f(s.x); e.y = __builtin_amdgcn_exp2f(s.y);
;     const f32x2 m = v * (q * e), r = v - m;
;     f32x2 o; o.x = v.x < 0.f ? m.x : r.x; o.y = v.y < 0.f ? m.y : r.y; return o;
;     __device__ __forceinline__ void operator()(const f32x4 (&acc)[2][2][4][2], const Unit& u, int wr, int wc, int fr, int fq) const {
;     ...
;             for (int m = 0; m < 4; ++m) { const int row = row0 + ai * HALF + m * 16; const float rs = rsv[ai][m]; bf16_t* rowp = O + (size_t)row * ldc + col0; float s1 = 0.f, s2 = 0.f;
; #pragma unroll
;                 for (int bj = 0; bj < 2; ++bj) { f32x4 v0 = acc[ai][bj][m][0] * rs, v1 = acc[ai][bj][m][1] * rs;
;                     const f32x2 a = gelu_pk((f32x2){v0[0], v0[1]}), b = gelu_pk((f32x2){v0[2], v0[3]}), c = gelu_pk((f32x2){v1[0], v1[1]}), d = gelu_pk((f32x2){v1[2], v1[3]});
;                     s1 += ((a.x + a.y) + (b.x + b.y)) + ((c.x + c.y) + (d.x + d.y));
;                     s2 += ((a.x * a.x + a.y * a.y) + (b.x * b.x + b.y * b.y)) + ((c.x * c.x + c.y * c.y) + (d.x * d.x + d.y * d.y));
;                     u32x4 w; w.x = cvt_pk_bf16(a.x, a.y); w.y = cvt_pk_bf16(b.x, b.y); w.z = cvt_pk_bf16(c.x, c.y); w.w = cvt_pk_bf16(d.x, d.y);
;                     *(u32x4*)(rowp + bj * HALF) = w; }
.LBB0_368:
	v_add_f32_e32 v0, v94, v95
	s_waitcnt lgkmcnt(0)
	v_add_f32_e32 v78, v96, v97
	v_add_f32_e32 v0, v0, v78
	v_fmamk_f32 v0, v0, 0x3a800000, v224
	v_rsq_f32_e32 v0, v0
	s_mov_b32 s4, 0xbf3a00e3
	v_lshlrev_b64 v[78:79], 12, v[168:169]
	v_lshl_add_u64 v[78:79], s[20:21], 0, v[78:79]
	v_pk_mul_f32 v[70:71], v[70:71], v[0:1] op_sel_hi:[1,0]
	v_pk_mul_f32 v[80:81], v[66:67], v[0:1] op_sel_hi:[1,0]
	v_and_b32_e32 v67, 0x7fffffff, v71
	v_and_b32_e32 v66, 0x7fffffff, v70
	v_pk_fma_f32 v[66:67], v[66:67], s[64:65], 1.0 op_sel_hi:[1,0,0]
	v_pk_mul_f32 v[86:87], v[70:71], v[70:71]
	v_rcp_f32_e32 v82, v66
	v_rcp_f32_e32 v83, v67
	v_mov_b64_e32 v[66:67], s[4:5]
	v_pk_mul_f32 v[86:87], v[86:87], s[76:77] op_sel_hi:[1,0]
	v_cmp_gt_f32_e32 vcc, 0, v70
	v_pk_fma_f32 v[84:85], v[82:83], s[66:67], v[66:67] op_sel_hi:[1,0,0]
	v_exp_f32_e32 v86, v86
	v_pk_fma_f32 v[84:85], v[82:83], v[84:85], s[70:71] op_sel_hi:[1,1,0]
	v_exp_f32_e32 v87, v87
	v_pk_fma_f32 v[84:85], v[82:83], v[84:85], s[72:73] op_sel_hi:[1,1,0]
	v_pk_mul_f32 v[72:73], v[72:73], v[0:1] op_sel_hi:[1,0]
	v_pk_fma_f32 v[84:85], v[82:83], v[84:85], s[74:75] op_sel_hi:[1,1,0]
	v_pk_mul_f32 v[68:69], v[68:69], v[0:1] op_sel_hi:[1,0]
	v_pk_mul_f32 v[82:83], v[82:83], v[84:85]
	v_pk_mul_f32 v[84:85], v[72:73], v[72:73]
	v_pk_mul_f32 v[82:83], v[86:87], v[82:83]
	v_pk_mul_f32 v[84:85], v[84:85], s[76:77] op_sel_hi:[1,0]
	v_pk_mul_f32 v[86:87], v[70:71], v[82:83]
	v_pk_fma_f32 v[82:83], v[70:71], v[82:83], v[70:71] neg_lo:[1,0,0] neg_hi:[1,0,0]
	v_exp_f32_e32 v84, v84
	v_cndmask_b32_e32 v70, v82, v86, vcc
	v_cmp_gt_f32_e32 vcc, 0, v71
	v_and_b32_e32 v82, 0x7fffffff, v72
	v_exp_f32_e32 v85, v85
	v_cndmask_b32_e32 v71, v83, v87, vcc
	v_and_b32_e32 v83, 0x7fffffff, v73
	v_pk_fma_f32 v[82:83], v[82:83], s[64:65], 1.0 op_sel_hi:[1,0,0]
	v_cmp_gt_f32_e32 vcc, 0, v72
	v_rcp_f32_e32 v82, v82
	v_rcp_f32_e32 v83, v83
	v_lshl_add_u64 v[78:79], v[160:161], 1, v[78:79]
	v_pk_mul_f32 v[62:63], v[62:63], v[0:1] op_sel_hi:[1,0]
	v_pk_mul_f32 v[64:65], v[64:65], v[0:1] op_sel_hi:[1,0]
	v_pk_fma_f32 v[86:87], v[82:83], s[66:67], v[66:67] op_sel_hi:[1,0,0]
	v_pk_mul_f32 v[60:61], v[60:61], v[0:1] op_sel_hi:[1,0]
	v_pk_fma_f32 v[86:87], v[82:83], v[86:87], s[70:71] op_sel_hi:[1,1,0]
	s_nop 0
	v_pk_fma_f32 v[86:87], v[82:83], v[86:87], s[72:73] op_sel_hi:[1,1,0]
	s_nop 0
	v_pk_fma_f32 v[86:87], v[82:83], v[86:87], s[74:75] op_sel_hi:[1,1,0]
	s_nop 0
	v_pk_mul_f32 v[82:83], v[82:83], v[86:87]
	v_pk_mul_f32 v[86:87], v[80:81], v[80:81]
	v_pk_mul_f32 v[82:83], v[84:85], v[82:83]
	v_pk_mul_f32 v[86:87], v[86:87], s[76:77] op_sel_hi:[1,0]
	v_pk_mul_f32 v[84:85], v[72:73], v[82:83]
	v_pk_fma_f32 v[82:83], v[72:73], v[82:83], v[72:73] neg_lo:[1,0,0] neg_hi:[1,0,0]
	v_exp_f32_e32 v86, v86
	v_cndmask_b32_e32 v72, v82, v84, vcc
	v_cmp_gt_f32_e32 vcc, 0, v73
	v_and_b32_e32 v82, 0x7fffffff, v80
	v_exp_f32_e32 v87, v87
	v_cndmask_b32_e32 v73, v83, v85, vcc
	v_and_b32_e32 v83, 0x7fffffff, v81
	v_pk_fma_f32 v[82:83], v[82:83], s[64:65], 1.0 op_sel_hi:[1,0,0]
	v_cmp_gt_f32_e32 vcc, 0, v80
	v_rcp_f32_e32 v82, v82
	v_rcp_f32_e32 v83, v83
	s_nop 0
	v_pk_fma_f32 v[84:85], v[82:83], s[66:67], v[66:67] op_sel_hi:[1,0,0]
	s_nop 0
	v_pk_fma_f32 v[84:85], v[82:83], v[84:85], s[70:71] op_sel_hi:[1,1,0]
	s_nop 0
	v_pk_fma_f32 v[84:85], v[82:83], v[84:85], s[72:73] op_sel_hi:[1,1,0]
	s_nop 0
	v_pk_fma_f32 v[84:85], v[82:83], v[84:85], s[74:75] op_sel_hi:[1,1,0]
	s_nop 0
	v_pk_mul_f32 v[82:83], v[82:83], v[84:85]
	v_pk_mul_f32 v[84:85], v[68:69], v[68:69]
	v_pk_mul_f32 v[82:83], v[86:87], v[82:83]
	v_pk_mul_f32 v[84:85], v[84:85], s[76:77] op_sel_hi:[1,0]
	v_pk_mul_f32 v[86:87], v[80:81], v[82:83]
	v_pk_fma_f32 v[82:83], v[80:81], v[82:83], v[80:81] neg_lo:[1,0,0] neg_hi:[1,0,0]
	v_exp_f32_e32 v84, v84
	v_cndmask_b32_e32 v80, v82, v86, vcc
	v_cmp_gt_f32_e32 vcc, 0, v81
	v_and_b32_e32 v82, 0x7fffffff, v68
	v_exp_f32_e32 v85, v85
	v_cndmask_b32_e32 v81, v83, v87, vcc
	v_and_b32_e32 v83, 0x7fffffff, v69
	v_pk_fma_f32 v[82:83], v[82:83], s[64:65], 1.0 op_sel_hi:[1,0,0]
	v_cmp_gt_f32_e32 vcc, 0, v68
	v_rcp_f32_e32 v82, v82
	v_rcp_f32_e32 v83, v83
	s_nop 0
	v_pk_fma_f32 v[86:87], v[82:83], s[66:67], v[66:67] op_sel_hi:[1,0,0]
	s_nop 0
	v_pk_fma_f32 v[86:87], v[82:83], v[86:87], s[70:71] op_sel_hi:[1,1,0]
	s_nop 0
	v_pk_fma_f32 v[86:87], v[82:83], v[86:87], s[72:73] op_sel_hi:[1,1,0]
	s_nop 0
	v_pk_fma_f32 v[86:87], v[82:83], v[86:87], s[74:75] op_sel_hi:[1,1,0]
	s_nop 0
	v_pk_mul_f32 v[82:83], v[82:83], v[86:87]
	v_pk_mul_f32 v[86:87], v[62:63], v[62:63]
	v_pk_mul_f32 v[82:83], v[84:85], v[82:83]
	v_pk_mul_f32 v[86:87], v[86:87], s[76:77] op_sel_hi:[1,0]
	v_pk_mul_f32 v[84:85], v[68:69], v[82:83]
	v_pk_fma_f32 v[82:83], v[68:69], v[82:83], v[68:69] neg_lo:[1,0,0] neg_hi:[1,0,0]
	v_exp_f32_e32 v86, v86
	v_cndmask_b32_e32 v68, v82, v84, vcc
	v_cmp_gt_f32_e32 vcc, 0, v69
	v_cvt_pk_bf16_f32 v82, v70, v71
	v_exp_f32_e32 v87, v87
	s_nop 0
	v_cndmask_b32_e32 v69, v83, v85, vcc
	v_cvt_pk_bf16_f32 v83, v72, v73
	v_cvt_pk_bf16_f32 v84, v80, v81
	v_cvt_pk_bf16_f32 v85, v68, v69
	global_store_dwordx4 v[78:79], v[82:85], off
	v_cmp_gt_f32_e32 vcc, 0, v62
	s_nop 0
	v_pk_mul_f32 v[82:83], v[58:59], v[0:1] op_sel_hi:[1,0]
	v_and_b32_e32 v59, 0x7fffffff, v63
	v_and_b32_e32 v58, 0x7fffffff, v62
	v_pk_fma_f32 v[58:59], v[58:59], s[64:65], 1.0 op_sel_hi:[1,0,0]
	s_nop 0
	v_rcp_f32_e32 v58, v58
	v_rcp_f32_e32 v59, v59
	s_nop 0
	v_pk_fma_f32 v[84:85], v[58:59], s[66:67], v[66:67] op_sel_hi:[1,0,0]
	s_nop 0
	v_pk_fma_f32 v[84:85], v[58:59], v[84:85], s[70:71] op_sel_hi:[1,1,0]
	s_nop 0
	v_pk_fma_f32 v[84:85], v[58:59], v[84:85], s[72:73] op_sel_hi:[1,1,0]
	s_nop 0
; __device__ __forceinline__ unsigned cvt_pk_bf16(float lo, float hi) { unsigned r; asm volatile("v_cvt_pk_bf16_f32 %0, %1, %2" : "=v"(r) : "v"(lo), "v"(hi)); return r; }
; __device__ __forceinline__ f32x2 gelu_pk(f32x2 v) {
;     const f32x2 av = __builtin_elementwise_abs(v), d = av * 0.2316418882f + 1.0f;
;     f32x2 t; t.x = __builtin_amdgcn_rcpf(d.x); t.y = __builtin_amdgcn_rcpf(d.y);
;     f32x2 q = t * 0.5307027145f + (-0.7265760135f); q = q * t + 0.7107068705f; q = q * t + (-0.142248368f); q = q * t + 0.127414796f; q = q * t;
;     const f32x2 s = (v * v) * (-0.72134752044f);
;     f32x2 e; e.x = __builtin_amdgcn_exp2f(s.x); e.y = __builtin_amdgcn_exp2f(s.y);
;     const f32x2 m = v * (q * e), r = v - m;
;     f32x2 o; o.x = v.x < 0.f ? m.x : r.x; o.y = v.y < 0.f ? m.y : r.y; return o;
;     __device__ __forceinline__ void operator()(const f32x4 (&acc)[2][2][4][2], const Unit& u, int wr, int wc, int fr, int fq) const {
;     ...
;                 for (int bj = 0; bj < 2; ++bj) { f32x4 v0 = acc[ai][bj][m][0] * rs, v1 = acc[ai][bj][m][1] * rs;
;                     const f32x2 a = gelu_pk((f32x2){v0[0], v0[1]}), b = gelu_pk((f32x2){v0[2], v0[3]}), c = gelu_pk((f32x2){v1[0], v1[1]}), d = gelu_pk((f32x2){v1[2], v1[3]});
;                     s1 += ((a.x + a.y) + (b.x + b.y)) + ((c.x + c.y) + (d.x + d.y));
;                     s2 += ((a.x * a.x + a.y * a.y) + (b.x * b.x + b.y * b.y)) + ((c.x * c.x + c.y * c.y) + (d.x * d.x + d.y * d.y));
;                     u32x4 w; w.x = cvt_pk_bf16(a.x, a.y); w.y = cvt_pk_bf16(b.x, b.y); w.z = cvt_pk_bf16(c.x, c.y); w.w = cvt_pk_bf16(d.x, d.y);
;                     *(u32x4*)(rowp + bj * HALF) = w; }
;                 if (isv) { s1 += __shfl_xor(s1, 16); s1 += __shfl_xor(s1, 32); s2 += __shfl_xor(s2, 16); s2 += __shfl_xor(s2, 32);
;                     if (fq == 0) { const int rl = ai * HALF + wr * 64 + m * 16 + fr; part[rl * 4 + wc] = s1; part[1024 + rl * 4 + wc] = s2; } } }
	v_pk_fma_f32 v[84:85], v[58:59], v[84:85], s[74:75] op_sel_hi:[1,1,0]
	s_nop 0
	v_pk_mul_f32 v[58:59], v[58:59], v[84:85]
	v_pk_mul_f32 v[84:85], v[64:65], v[64:65]
	v_pk_mul_f32 v[58:59], v[86:87], v[58:59]
	v_pk_mul_f32 v[84:85], v[84:85], s[76:77] op_sel_hi:[1,0]
	v_pk_mul_f32 v[86:87], v[62:63], v[58:59]
	v_pk_fma_f32 v[58:59], v[62:63], v[58:59], v[62:63] neg_lo:[1,0,0] neg_hi:[1,0,0]
	v_and_b32_e32 v62, 0x7fffffff, v64
	v_cndmask_b32_e32 v0, v58, v86, vcc
	v_cmp_gt_f32_e32 vcc, 0, v63
	v_and_b32_e32 v63, 0x7fffffff, v65
	v_pk_fma_f32 v[62:63], v[62:63], s[64:65], 1.0 op_sel_hi:[1,0,0]
	v_cndmask_b32_e32 v58, v59, v87, vcc
	v_rcp_f32_e32 v62, v62
	v_rcp_f32_e32 v63, v63
	v_exp_f32_e32 v84, v84
	v_exp_f32_e32 v85, v85
	v_cmp_gt_f32_e32 vcc, 0, v64
	v_pk_fma_f32 v[86:87], v[62:63], s[66:67], v[66:67] op_sel_hi:[1,0,0]
	s_nop 0
	v_pk_fma_f32 v[86:87], v[62:63], v[86:87], s[70:71] op_sel_hi:[1,1,0]
	s_nop 0
	v_pk_fma_f32 v[86:87], v[62:63], v[86:87], s[72:73] op_sel_hi:[1,1,0]
	s_nop 0
	v_pk_fma_f32 v[86:87], v[62:63], v[86:87], s[74:75] op_sel_hi:[1,1,0]
	s_nop 0
	v_pk_mul_f32 v[62:63], v[62:63], v[86:87]
	v_pk_mul_f32 v[86:87], v[82:83], v[82:83]
	v_pk_mul_f32 v[62:63], v[84:85], v[62:63]
	v_pk_mul_f32 v[86:87], v[86:87], s[76:77] op_sel_hi:[1,0]
	v_pk_mul_f32 v[84:85], v[64:65], v[62:63]
	v_pk_fma_f32 v[62:63], v[64:65], v[62:63], v[64:65] neg_lo:[1,0,0] neg_hi:[1,0,0]
	v_and_b32_e32 v64, 0x7fffffff, v82
	v_cndmask_b32_e32 v59, v62, v84, vcc
	v_cmp_gt_f32_e32 vcc, 0, v65
	v_and_b32_e32 v65, 0x7fffffff, v83
	v_pk_fma_f32 v[64:65], v[64:65], s[64:65], 1.0 op_sel_hi:[1,0,0]
	v_cndmask_b32_e32 v62, v63, v85, vcc
	v_rcp_f32_e32 v64, v64
	v_rcp_f32_e32 v65, v65
	v_exp_f32_e32 v86, v86
	v_exp_f32_e32 v87, v87
	v_cmp_gt_f32_e32 vcc, 0, v82
	v_pk_fma_f32 v[84:85], v[64:65], s[66:67], v[66:67] op_sel_hi:[1,0,0]
	s_nop 0
	v_pk_fma_f32 v[84:85], v[64:65], v[84:85], s[70:71] op_sel_hi:[1,1,0]
	s_nop 0
	v_pk_fma_f32 v[84:85], v[64:65], v[84:85], s[72:73] op_sel_hi:[1,1,0]
	s_nop 0
	v_pk_fma_f32 v[84:85], v[64:65], v[84:85], s[74:75] op_sel_hi:[1,1,0]
	s_nop 0
	v_pk_mul_f32 v[64:65], v[64:65], v[84:85]
	v_pk_mul_f32 v[84:85], v[60:61], v[60:61]
	v_pk_mul_f32 v[64:65], v[86:87], v[64:65]
	s_nop 0
	v_pk_mul_f32 v[86:87], v[82:83], v[64:65]
	v_pk_fma_f32 v[64:65], v[82:83], v[64:65], v[82:83] neg_lo:[1,0,0] neg_hi:[1,0,0]
	v_and_b32_e32 v82, 0x7fffffff, v60
	v_cndmask_b32_e32 v63, v64, v86, vcc
	v_cmp_gt_f32_e32 vcc, 0, v83
	v_and_b32_e32 v83, 0x7fffffff, v61
	v_pk_fma_f32 v[82:83], v[82:83], s[64:65], 1.0 op_sel_hi:[1,0,0]
	v_cndmask_b32_e32 v64, v65, v87, vcc
	v_rcp_f32_e32 v82, v82
	v_rcp_f32_e32 v83, v83
	v_cmp_gt_f32_e32 vcc, 0, v60
	v_pk_fma_f32 v[66:67], v[82:83], s[66:67], v[66:67] op_sel_hi:[1,0,0]
	s_nop 0
	v_pk_fma_f32 v[66:67], v[82:83], v[66:67], s[70:71] op_sel_hi:[1,1,0]
	s_nop 0
	v_pk_fma_f32 v[66:67], v[82:83], v[66:67], s[72:73] op_sel_hi:[1,1,0]
	s_nop 0
	v_pk_fma_f32 v[66:67], v[82:83], v[66:67], s[74:75] op_sel_hi:[1,1,0]
	s_nop 0
	v_pk_mul_f32 v[66:67], v[82:83], v[66:67]
	v_pk_mul_f32 v[82:83], v[84:85], s[76:77] op_sel_hi:[1,0]
	s_nop 0
	v_exp_f32_e32 v82, v82
	v_exp_f32_e32 v83, v83
	s_nop 0
	v_pk_mul_f32 v[66:67], v[82:83], v[66:67]
	s_nop 0
	v_pk_mul_f32 v[82:83], v[60:61], v[66:67]
	v_pk_fma_f32 v[66:67], v[60:61], v[66:67], v[60:61] neg_lo:[1,0,0] neg_hi:[1,0,0]
	s_nop 0
	v_cndmask_b32_e32 v60, v66, v82, vcc
	v_cmp_gt_f32_e32 vcc, 0, v61
	v_cvt_pk_bf16_f32 v82, v0, v58
	s_nop 1
	v_cndmask_b32_e32 v61, v67, v83, vcc
	s_and_b64 vcc, exec, s[10:11]
	v_cvt_pk_bf16_f32 v83, v59, v62
	v_cvt_pk_bf16_f32 v84, v63, v64
	v_cvt_pk_bf16_f32 v85, v60, v61
	global_store_dwordx4 v[78:79], v[82:85], off offset:256
	s_cbranch_vccnz .LBB0_372
	v_mul_f32_e32 v65, v71, v71
	v_mul_f32_e32 v66, v73, v73
	v_fmac_f32_e32 v65, v70, v70
	v_fmac_f32_e32 v66, v72, v72
	v_add_f32_e32 v65, v65, v66
	v_mul_f32_e32 v66, v81, v81
	v_mul_f32_e32 v67, v69, v69
	v_fmac_f32_e32 v66, v80, v80
	v_fmac_f32_e32 v67, v68, v68
	v_add_f32_e32 v66, v66, v67
	v_add_f32_e32 v65, v65, v66
	v_mul_f32_e32 v66, v58, v58
	v_fmac_f32_e32 v66, v0, v0
	v_mul_f32_e32 v67, v62, v62
	v_add_f32_e32 v0, v0, v58
	v_add_f32_e32 v58, v59, v62
	v_fmac_f32_e32 v67, v59, v59
	v_add_f32_e32 v70, v70, v71
	v_add_f32_e32 v71, v72, v73
	v_add_f32_e32 v0, v0, v58
	v_add_f32_e32 v58, v63, v64
	v_add_f32_e32 v59, v60, v61
	v_add_f32_e32 v70, v70, v71
	v_add_f32_e32 v71, v80, v81
	v_add_f32_e32 v68, v68, v69
	v_add_f32_e32 v58, v58, v59
	v_and_b32_e32 v59, 64, v226
	v_add_f32_e32 v68, v71, v68
	v_add_f32_e32 v0, v0, v58
	v_xor_b32_e32 v58, 16, v226
	v_add_u32_e32 v59, 64, v59
	v_add_f32_e32 v68, v70, v68
	v_cmp_lt_i32_e32 vcc, v58, v59
	v_add_f32_e32 v66, v66, v67
	v_mul_f32_e32 v67, v64, v64
	v_mul_f32_e32 v78, v61, v61
	v_add_f32_e32 v68, 0, v68
	v_cndmask_b32_e32 v58, v226, v58, vcc
	v_fmac_f32_e32 v67, v63, v63
	v_add_f32_e32 v0, v0, v68
	v_lshlrev_b32_e32 v58, 2, v58
	v_fmac_f32_e32 v78, v60, v60
	v_mov_b32_e32 v61, v0
	s_nop 1
	v_permlane16_swap_b32_e32 v61, v0
	v_add_f32_e32 v60, v67, v78
	v_add_f32_e32 v60, v66, v60
	v_add_f32_e32 v60, v65, v60
	v_mov_b32_e32 v62, v60
	s_nop 1
	v_permlane16_swap_b32_e32 v62, v60
	s_waitcnt lgkmcnt(0)
	v_add_f32_e32 v0, v0, v61
	v_xor_b32_e32 v61, 32, v226
	v_cmp_lt_i32_e32 vcc, v61, v59
	v_add_f32_e32 v59, v60, v62
	s_nop 0
	v_cndmask_b32_e32 v58, v226, v61, vcc
	v_lshlrev_b32_e32 v61, 2, v58
	v_mov_b32_e32 v58, v0
	s_nop 1
	v_permlane32_swap_b32_e32 v58, v0
	v_mov_b32_e32 v60, v59
	s_nop 1
	v_permlane32_swap_b32_e32 v60, v59
	s_and_saveexec_b64 s[4:5], s[6:7]
	s_cbranch_execz .LBB0_371
	s_waitcnt lgkmcnt(0)
	v_add_f32_e32 v59, v59, v60
	v_add_f32_e32 v0, v0, v58
	ds_write2st64_b32 v186, v0, v59 offset0:8 offset1:24

; __device__ __forceinline__ unsigned cvt_pk_bf16(float lo, float hi) { unsigned r; asm volatile("v_cvt_pk_bf16_f32 %0, %1, %2" : "=v"(r) : "v"(lo), "v"(hi)); return r; }
; __device__ __forceinline__ f32x2 gelu_pk(f32x2 v) {
;     const f32x2 av = __builtin_elementwise_abs(v), d = av * 0.2316418882f + 1.0f;
;     f32x2 t; t.x = __builtin_amdgcn_rcpf(d.x); t.y = __builtin_amdgcn_rcpf(d.y);
;     f32x2 q = t * 0.5307027145f + (-0.7265760135f); q = q * t + 0.7107068705f; q = q * t + (-0.142248368f); q = q * t + 0.127414796f; q = q * t;
;     const f32x2 s = (v * v) * (-0.72134752044f);
;     f32x2 e; e.x = __builtin_amdgcn_exp2f(s.x); e.y = __builtin_amdgcn_exp2f(s.y);
;     const f32x2 m = v * (q * e), r = v - m;
;     f32x2 o; o.x = v.x < 0.f ? m.x : r.x; o.y = v.y < 0.f ? m.y : r.y; return o;
;     __device__ __forceinline__ void operator()(const f32x4 (&acc)[2][2][4][2], const Unit& u, int wr, int wc, int fr, int fq) const {
;     ...
;             for (int m = 0; m < 4; ++m) { const int row = row0 + ai * HALF + m * 16; const float rs = rsv[ai][m]; bf16_t* rowp = O + (size_t)row * ldc + col0; float s1 = 0.f, s2 = 0.f;
; #pragma unroll
;                 for (int bj = 0; bj < 2; ++bj) { f32x4 v0 = acc[ai][bj][m][0] * rs, v1 = acc[ai][bj][m][1] * rs;
;                     const f32x2 a = gelu_pk((f32x2){v0[0], v0[1]}), b = gelu_pk((f32x2){v0[2], v0[3]}), c = gelu_pk((f32x2){v1[0], v1[1]}), d = gelu_pk((f32x2){v1[2], v1[3]});
;                     s1 += ((a.x + a.y) + (b.x + b.y)) + ((c.x + c.y) + (d.x + d.y));
;                     s2 += ((a.x * a.x + a.y * a.y) + (b.x * b.x + b.y * b.y)) + ((c.x * c.x + c.y * c.y) + (d.x * d.x + d.y * d.y));
;                     u32x4 w; w.x = cvt_pk_bf16(a.x, a.y); w.y = cvt_pk_bf16(b.x, b.y); w.z = cvt_pk_bf16(c.x, c.y); w.w = cvt_pk_bf16(d.x, d.y);
;                     *(u32x4*)(rowp + bj * HALF) = w; }
.LBB0_372:
	v_add_f32_e32 v0, v74, v75
	s_waitcnt lgkmcnt(0)
	v_add_f32_e32 v58, v76, v77
	v_add_f32_e32 v0, v0, v58
	v_fmamk_f32 v0, v0, 0x3a800000, v224
	v_rsq_f32_e32 v0, v0
	s_mov_b32 s4, 0xbf3a00e3
	v_lshlrev_b64 v[58:59], 12, v[166:167]
	v_lshl_add_u64 v[58:59], s[20:21], 0, v[58:59]
	v_pk_mul_f32 v[50:51], v[50:51], v[0:1] op_sel_hi:[1,0]
	v_pk_mul_f32 v[60:61], v[46:47], v[0:1] op_sel_hi:[1,0]
	v_and_b32_e32 v47, 0x7fffffff, v51
	v_and_b32_e32 v46, 0x7fffffff, v50
	v_pk_fma_f32 v[46:47], v[46:47], s[64:65], 1.0 op_sel_hi:[1,0,0]
	v_pk_mul_f32 v[66:67], v[50:51], v[50:51]
	v_rcp_f32_e32 v62, v46
	v_rcp_f32_e32 v63, v47
	v_mov_b64_e32 v[46:47], s[4:5]
	v_pk_mul_f32 v[66:67], v[66:67], s[76:77] op_sel_hi:[1,0]
	v_cmp_gt_f32_e32 vcc, 0, v50
	v_pk_fma_f32 v[64:65], v[62:63], s[66:67], v[46:47] op_sel_hi:[1,0,0]
	v_exp_f32_e32 v66, v66
	v_pk_fma_f32 v[64:65], v[62:63], v[64:65], s[70:71] op_sel_hi:[1,1,0]
	v_exp_f32_e32 v67, v67
	v_pk_fma_f32 v[64:65], v[62:63], v[64:65], s[72:73] op_sel_hi:[1,1,0]
	v_pk_mul_f32 v[52:53], v[52:53], v[0:1] op_sel_hi:[1,0]
	v_pk_fma_f32 v[64:65], v[62:63], v[64:65], s[74:75] op_sel_hi:[1,1,0]
	v_pk_mul_f32 v[48:49], v[48:49], v[0:1] op_sel_hi:[1,0]
	v_pk_mul_f32 v[62:63], v[62:63], v[64:65]
	v_pk_mul_f32 v[64:65], v[52:53], v[52:53]
	v_pk_mul_f32 v[62:63], v[66:67], v[62:63]
	v_pk_mul_f32 v[64:65], v[64:65], s[76:77] op_sel_hi:[1,0]
	v_pk_mul_f32 v[66:67], v[50:51], v[62:63]
	v_pk_fma_f32 v[62:63], v[50:51], v[62:63], v[50:51] neg_lo:[1,0,0] neg_hi:[1,0,0]
	v_exp_f32_e32 v64, v64
	v_cndmask_b32_e32 v50, v62, v66, vcc
	v_cmp_gt_f32_e32 vcc, 0, v51
	v_and_b32_e32 v62, 0x7fffffff, v52
	v_exp_f32_e32 v65, v65
	v_cndmask_b32_e32 v51, v63, v67, vcc
	v_and_b32_e32 v63, 0x7fffffff, v53
	v_pk_fma_f32 v[62:63], v[62:63], s[64:65], 1.0 op_sel_hi:[1,0,0]
	v_cmp_gt_f32_e32 vcc, 0, v52
	v_rcp_f32_e32 v62, v62
	v_rcp_f32_e32 v63, v63
	v_lshl_add_u64 v[58:59], v[160:161], 1, v[58:59]
	v_pk_mul_f32 v[42:43], v[42:43], v[0:1] op_sel_hi:[1,0]
	v_pk_mul_f32 v[44:45], v[44:45], v[0:1] op_sel_hi:[1,0]
	v_pk_fma_f32 v[66:67], v[62:63], s[66:67], v[46:47] op_sel_hi:[1,0,0]
	v_pk_mul_f32 v[40:41], v[40:41], v[0:1] op_sel_hi:[1,0]
	v_pk_fma_f32 v[66:67], v[62:63], v[66:67], s[70:71] op_sel_hi:[1,1,0]
	s_nop 0
	v_pk_fma_f32 v[66:67], v[62:63], v[66:67], s[72:73] op_sel_hi:[1,1,0]
	s_nop 0
	v_pk_fma_f32 v[66:67], v[62:63], v[66:67], s[74:75] op_sel_hi:[1,1,0]
	s_nop 0
	v_pk_mul_f32 v[62:63], v[62:63], v[66:67]
	v_pk_mul_f32 v[66:67], v[60:61], v[60:61]
	v_pk_mul_f32 v[62:63], v[64:65], v[62:63]
	v_pk_mul_f32 v[66:67], v[66:67], s[76:77] op_sel_hi:[1,0]
	v_pk_mul_f32 v[64:65], v[52:53], v[62:63]
	v_pk_fma_f32 v[62:63], v[52:53], v[62:63], v[52:53] neg_lo:[1,0,0] neg_hi:[1,0,0]
	v_exp_f32_e32 v66, v66
	v_cndmask_b32_e32 v52, v62, v64, vcc
	v_cmp_gt_f32_e32 vcc, 0, v53
	v_and_b32_e32 v62, 0x7fffffff, v60
	v_exp_f32_e32 v67, v67
	v_cndmask_b32_e32 v53, v63, v65, vcc
	v_and_b32_e32 v63, 0x7fffffff, v61
	v_pk_fma_f32 v[62:63], v[62:63], s[64:65], 1.0 op_sel_hi:[1,0,0]
	v_cmp_gt_f32_e32 vcc, 0, v60
	v_rcp_f32_e32 v62, v62
	v_rcp_f32_e32 v63, v63
	s_nop 0
	v_pk_fma_f32 v[64:65], v[62:63], s[66:67], v[46:47] op_sel_hi:[1,0,0]
	s_nop 0
	v_pk_fma_f32 v[64:65], v[62:63], v[64:65], s[70:71] op_sel_hi:[1,1,0]
	s_nop 0
	v_pk_fma_f32 v[64:65], v[62:63], v[64:65], s[72:73] op_sel_hi:[1,1,0]
	s_nop 0
	v_pk_fma_f32 v[64:65], v[62:63], v[64:65], s[74:75] op_sel_hi:[1,1,0]
	s_nop 0
	v_pk_mul_f32 v[62:63], v[62:63], v[64:65]
	v_pk_mul_f32 v[64:65], v[48:49], v[48:49]
	v_pk_mul_f32 v[62:63], v[66:67], v[62:63]
	v_pk_mul_f32 v[64:65], v[64:65], s[76:77] op_sel_hi:[1,0]
	v_pk_mul_f32 v[66:67], v[60:61], v[62:63]
	v_pk_fma_f32 v[62:63], v[60:61], v[62:63], v[60:61] neg_lo:[1,0,0] neg_hi:[1,0,0]
	v_exp_f32_e32 v64, v64
	v_cndmask_b32_e32 v60, v62, v66, vcc
	v_cmp_gt_f32_e32 vcc, 0, v61
	v_and_b32_e32 v62, 0x7fffffff, v48
	v_exp_f32_e32 v65, v65
	v_cndmask_b32_e32 v61, v63, v67, vcc
	v_and_b32_e32 v63, 0x7fffffff, v49
	v_pk_fma_f32 v[62:63], v[62:63], s[64:65], 1.0 op_sel_hi:[1,0,0]
	v_cmp_gt_f32_e32 vcc, 0, v48
	v_rcp_f32_e32 v62, v62
	v_rcp_f32_e32 v63, v63
	s_nop 0
	v_pk_fma_f32 v[66:67], v[62:63], s[66:67], v[46:47] op_sel_hi:[1,0,0]
	s_nop 0
	v_pk_fma_f32 v[66:67], v[62:63], v[66:67], s[70:71] op_sel_hi:[1,1,0]
	s_nop 0
	v_pk_fma_f32 v[66:67], v[62:63], v[66:67], s[72:73] op_sel_hi:[1,1,0]
	s_nop 0
	v_pk_fma_f32 v[66:67], v[62:63], v[66:67], s[74:75] op_sel_hi:[1,1,0]
	s_nop 0
	v_pk_mul_f32 v[62:63], v[62:63], v[66:67]
	v_pk_mul_f32 v[66:67], v[42:43], v[42:43]
	v_pk_mul_f32 v[62:63], v[64:65], v[62:63]
	v_pk_mul_f32 v[66:67], v[66:67], s[76:77] op_sel_hi:[1,0]
	v_pk_mul_f32 v[64:65], v[48:49], v[62:63]
	v_pk_fma_f32 v[62:63], v[48:49], v[62:63], v[48:49] neg_lo:[1,0,0] neg_hi:[1,0,0]
	v_exp_f32_e32 v66, v66
	v_cndmask_b32_e32 v48, v62, v64, vcc
	v_cmp_gt_f32_e32 vcc, 0, v49
	v_cvt_pk_bf16_f32 v62, v50, v51
	v_exp_f32_e32 v67, v67
	s_nop 0
	v_cndmask_b32_e32 v49, v63, v65, vcc
	v_cvt_pk_bf16_f32 v63, v52, v53
	v_cvt_pk_bf16_f32 v64, v60, v61
	v_cvt_pk_bf16_f32 v65, v48, v49
	global_store_dwordx4 v[58:59], v[62:65], off
	v_cmp_gt_f32_e32 vcc, 0, v42
	s_nop 0
	v_pk_mul_f32 v[62:63], v[38:39], v[0:1] op_sel_hi:[1,0]
	v_and_b32_e32 v39, 0x7fffffff, v43
	v_and_b32_e32 v38, 0x7fffffff, v42
	v_pk_fma_f32 v[38:39], v[38:39], s[64:65], 1.0 op_sel_hi:[1,0,0]
	s_nop 0
	v_rcp_f32_e32 v38, v38
	v_rcp_f32_e32 v39, v39
	s_nop 0
	v_pk_fma_f32 v[64:65], v[38:39], s[66:67], v[46:47] op_sel_hi:[1,0,0]
	s_nop 0
	v_pk_fma_f32 v[64:65], v[38:39], v[64:65], s[70:71] op_sel_hi:[1,1,0]
	s_nop 0
	v_pk_fma_f32 v[64:65], v[38:39], v[64:65], s[72:73] op_sel_hi:[1,1,0]
	s_nop 0
; __device__ __forceinline__ unsigned cvt_pk_bf16(float lo, float hi) { unsigned r; asm volatile("v_cvt_pk_bf16_f32 %0, %1, %2" : "=v"(r) : "v"(lo), "v"(hi)); return r; }
; __device__ __forceinline__ f32x2 gelu_pk(f32x2 v) {
;     const f32x2 av = __builtin_elementwise_abs(v), d = av * 0.2316418882f + 1.0f;
;     f32x2 t; t.x = __builtin_amdgcn_rcpf(d.x); t.y = __builtin_amdgcn_rcpf(d.y);
;     f32x2 q = t * 0.5307027145f + (-0.7265760135f); q = q * t + 0.7107068705f; q = q * t + (-0.142248368f); q = q * t + 0.127414796f; q = q * t;
;     const f32x2 s = (v * v) * (-0.72134752044f);
;     f32x2 e; e.x = __builtin_amdgcn_exp2f(s.x); e.y = __builtin_amdgcn_exp2f(s.y);
;     const f32x2 m = v * (q * e), r = v - m;
;     f32x2 o; o.x = v.x < 0.f ? m.x : r.x; o.y = v.y < 0.f ? m.y : r.y; return o;
;     __device__ __forceinline__ void operator()(const f32x4 (&acc)[2][2][4][2], const Unit& u, int wr, int wc, int fr, int fq) const {
;     ...
;                 for (int bj = 0; bj < 2; ++bj) { f32x4 v0 = acc[ai][bj][m][0] * rs, v1 = acc[ai][bj][m][1] * rs;
;                     const f32x2 a = gelu_pk((f32x2){v0[0], v0[1]}), b = gelu_pk((f32x2){v0[2], v0[3]}), c = gelu_pk((f32x2){v1[0], v1[1]}), d = gelu_pk((f32x2){v1[2], v1[3]});
;                     s1 += ((a.x + a.y) + (b.x + b.y)) + ((c.x + c.y) + (d.x + d.y));
;                     s2 += ((a.x * a.x + a.y * a.y) + (b.x * b.x + b.y * b.y)) + ((c.x * c.x + c.y * c.y) + (d.x * d.x + d.y * d.y));
;                     u32x4 w; w.x = cvt_pk_bf16(a.x, a.y); w.y = cvt_pk_bf16(b.x, b.y); w.z = cvt_pk_bf16(c.x, c.y); w.w = cvt_pk_bf16(d.x, d.y);
;                     *(u32x4*)(rowp + bj * HALF) = w; }
;                 if (isv) { s1 += __shfl_xor(s1, 16); s1 += __shfl_xor(s1, 32); s2 += __shfl_xor(s2, 16); s2 += __shfl_xor(s2, 32);
;                     if (fq == 0) { const int rl = ai * HALF + wr * 64 + m * 16 + fr; part[rl * 4 + wc] = s1; part[1024 + rl * 4 + wc] = s2; } } }
	v_pk_fma_f32 v[64:65], v[38:39], v[64:65], s[74:75] op_sel_hi:[1,1,0]
	s_nop 0
	v_pk_mul_f32 v[38:39], v[38:39], v[64:65]
	v_pk_mul_f32 v[64:65], v[44:45], v[44:45]
	v_pk_mul_f32 v[38:39], v[66:67], v[38:39]
	v_pk_mul_f32 v[64:65], v[64:65], s[76:77] op_sel_hi:[1,0]
	v_pk_mul_f32 v[66:67], v[42:43], v[38:39]
	v_pk_fma_f32 v[38:39], v[42:43], v[38:39], v[42:43] neg_lo:[1,0,0] neg_hi:[1,0,0]
	v_and_b32_e32 v42, 0x7fffffff, v44
	v_cndmask_b32_e32 v0, v38, v66, vcc
	v_cmp_gt_f32_e32 vcc, 0, v43
	v_and_b32_e32 v43, 0x7fffffff, v45
	v_pk_fma_f32 v[42:43], v[42:43], s[64:65], 1.0 op_sel_hi:[1,0,0]
	v_cndmask_b32_e32 v38, v39, v67, vcc
	v_rcp_f32_e32 v42, v42
	v_rcp_f32_e32 v43, v43
	v_exp_f32_e32 v64, v64
	v_exp_f32_e32 v65, v65
	v_cmp_gt_f32_e32 vcc, 0, v44
	v_pk_fma_f32 v[66:67], v[42:43], s[66:67], v[46:47] op_sel_hi:[1,0,0]
	s_nop 0
	v_pk_fma_f32 v[66:67], v[42:43], v[66:67], s[70:71] op_sel_hi:[1,1,0]
	s_nop 0
	v_pk_fma_f32 v[66:67], v[42:43], v[66:67], s[72:73] op_sel_hi:[1,1,0]
	s_nop 0
	v_pk_fma_f32 v[66:67], v[42:43], v[66:67], s[74:75] op_sel_hi:[1,1,0]
	s_nop 0
	v_pk_mul_f32 v[42:43], v[42:43], v[66:67]
	v_pk_mul_f32 v[66:67], v[62:63], v[62:63]
	v_pk_mul_f32 v[42:43], v[64:65], v[42:43]
	v_pk_mul_f32 v[66:67], v[66:67], s[76:77] op_sel_hi:[1,0]
	v_pk_mul_f32 v[64:65], v[44:45], v[42:43]
	v_pk_fma_f32 v[42:43], v[44:45], v[42:43], v[44:45] neg_lo:[1,0,0] neg_hi:[1,0,0]
	v_and_b32_e32 v44, 0x7fffffff, v62
	v_cndmask_b32_e32 v39, v42, v64, vcc
	v_cmp_gt_f32_e32 vcc, 0, v45
	v_and_b32_e32 v45, 0x7fffffff, v63
	v_pk_fma_f32 v[44:45], v[44:45], s[64:65], 1.0 op_sel_hi:[1,0,0]
	v_cndmask_b32_e32 v42, v43, v65, vcc
	v_rcp_f32_e32 v44, v44
	v_rcp_f32_e32 v45, v45
	v_exp_f32_e32 v66, v66
	v_exp_f32_e32 v67, v67
	v_cmp_gt_f32_e32 vcc, 0, v62
	v_pk_fma_f32 v[64:65], v[44:45], s[66:67], v[46:47] op_sel_hi:[1,0,0]
	s_nop 0
	v_pk_fma_f32 v[64:65], v[44:45], v[64:65], s[70:71] op_sel_hi:[1,1,0]
	s_nop 0
	v_pk_fma_f32 v[64:65], v[44:45], v[64:65], s[72:73] op_sel_hi:[1,1,0]
	s_nop 0
	v_pk_fma_f32 v[64:65], v[44:45], v[64:65], s[74:75] op_sel_hi:[1,1,0]
	s_nop 0
	v_pk_mul_f32 v[44:45], v[44:45], v[64:65]
	v_pk_mul_f32 v[64:65], v[40:41], v[40:41]
	v_pk_mul_f32 v[44:45], v[66:67], v[44:45]
	s_nop 0
	v_pk_mul_f32 v[66:67], v[62:63], v[44:45]
	v_pk_fma_f32 v[44:45], v[62:63], v[44:45], v[62:63] neg_lo:[1,0,0] neg_hi:[1,0,0]
	v_and_b32_e32 v62, 0x7fffffff, v40
	v_cndmask_b32_e32 v43, v44, v66, vcc
	v_cmp_gt_f32_e32 vcc, 0, v63
	v_and_b32_e32 v63, 0x7fffffff, v41
	v_pk_fma_f32 v[62:63], v[62:63], s[64:65], 1.0 op_sel_hi:[1,0,0]
	v_cndmask_b32_e32 v44, v45, v67, vcc
	v_rcp_f32_e32 v62, v62
	v_rcp_f32_e32 v63, v63
	v_cmp_gt_f32_e32 vcc, 0, v40
	v_pk_fma_f32 v[46:47], v[62:63], s[66:67], v[46:47] op_sel_hi:[1,0,0]
	s_nop 0
	v_pk_fma_f32 v[46:47], v[62:63], v[46:47], s[70:71] op_sel_hi:[1,1,0]
	s_nop 0
	v_pk_fma_f32 v[46:47], v[62:63], v[46:47], s[72:73] op_sel_hi:[1,1,0]
	s_nop 0
	v_pk_fma_f32 v[46:47], v[62:63], v[46:47], s[74:75] op_sel_hi:[1,1,0]
	s_nop 0
	v_pk_mul_f32 v[46:47], v[62:63], v[46:47]
	v_pk_mul_f32 v[62:63], v[64:65], s[76:77] op_sel_hi:[1,0]
	s_nop 0
	v_exp_f32_e32 v62, v62
	v_exp_f32_e32 v63, v63
	s_nop 0
	v_pk_mul_f32 v[46:47], v[62:63], v[46:47]
	s_nop 0
	v_pk_mul_f32 v[62:63], v[40:41], v[46:47]
	v_pk_fma_f32 v[46:47], v[40:41], v[46:47], v[40:41] neg_lo:[1,0,0] neg_hi:[1,0,0]
	s_nop 0
	v_cndmask_b32_e32 v40, v46, v62, vcc
	v_cmp_gt_f32_e32 vcc, 0, v41
	v_cvt_pk_bf16_f32 v62, v0, v38
	s_nop 1
	v_cndmask_b32_e32 v41, v47, v63, vcc
	s_and_b64 vcc, exec, s[10:11]
	v_cvt_pk_bf16_f32 v63, v39, v42
	v_cvt_pk_bf16_f32 v64, v43, v44
	v_cvt_pk_bf16_f32 v65, v40, v41
	global_store_dwordx4 v[58:59], v[62:65], off offset:256
	s_cbranch_vccnz .LBB0_376
	v_mul_f32_e32 v45, v51, v51
	v_mul_f32_e32 v46, v53, v53
	v_fmac_f32_e32 v45, v50, v50
	v_fmac_f32_e32 v46, v52, v52
	v_add_f32_e32 v45, v45, v46
	v_mul_f32_e32 v46, v61, v61
	v_mul_f32_e32 v47, v49, v49
	v_fmac_f32_e32 v46, v60, v60
	v_fmac_f32_e32 v47, v48, v48
	v_add_f32_e32 v46, v46, v47
	v_add_f32_e32 v45, v45, v46
	v_mul_f32_e32 v46, v38, v38
	v_fmac_f32_e32 v46, v0, v0
	v_mul_f32_e32 v47, v42, v42
	v_add_f32_e32 v0, v0, v38
	v_add_f32_e32 v38, v39, v42
	v_fmac_f32_e32 v47, v39, v39
	v_add_f32_e32 v50, v50, v51
	v_add_f32_e32 v51, v52, v53
	v_add_f32_e32 v0, v0, v38
	v_add_f32_e32 v38, v43, v44
	v_add_f32_e32 v39, v40, v41
	v_add_f32_e32 v50, v50, v51
	v_add_f32_e32 v51, v60, v61
	v_add_f32_e32 v48, v48, v49
	v_add_f32_e32 v38, v38, v39
	v_and_b32_e32 v39, 64, v226
	v_add_f32_e32 v48, v51, v48
	v_add_f32_e32 v0, v0, v38
	v_xor_b32_e32 v38, 16, v226
	v_add_u32_e32 v39, 64, v39
	v_add_f32_e32 v48, v50, v48
	v_cmp_lt_i32_e32 vcc, v38, v39
	v_add_f32_e32 v46, v46, v47
	v_mul_f32_e32 v47, v44, v44
	v_mul_f32_e32 v58, v41, v41
	v_add_f32_e32 v48, 0, v48
	v_cndmask_b32_e32 v38, v226, v38, vcc
	v_fmac_f32_e32 v47, v43, v43
	v_add_f32_e32 v0, v0, v48
	v_lshlrev_b32_e32 v38, 2, v38
	v_fmac_f32_e32 v58, v40, v40
	v_mov_b32_e32 v41, v0
	s_nop 1
	v_permlane16_swap_b32_e32 v41, v0
	v_add_f32_e32 v40, v47, v58
	v_add_f32_e32 v40, v46, v40
	v_add_f32_e32 v40, v45, v40
	v_mov_b32_e32 v42, v40
	s_nop 1
	v_permlane16_swap_b32_e32 v42, v40
	s_waitcnt lgkmcnt(0)
	v_add_f32_e32 v0, v0, v41
	v_xor_b32_e32 v41, 32, v226
	v_cmp_lt_i32_e32 vcc, v41, v39
	v_add_f32_e32 v39, v40, v42
	s_nop 0
	v_cndmask_b32_e32 v38, v226, v41, vcc
	v_lshlrev_b32_e32 v41, 2, v38
	v_mov_b32_e32 v38, v0
	s_nop 1
	v_permlane32_swap_b32_e32 v38, v0
	v_mov_b32_e32 v40, v39
	s_nop 1
	v_permlane32_swap_b32_e32 v40, v39
	s_and_saveexec_b64 s[4:5], s[6:7]
	s_cbranch_execz .LBB0_375
	s_waitcnt lgkmcnt(0)
	v_add_f32_e32 v39, v39, v40
	v_add_f32_e32 v0, v0, v38
	ds_write2st64_b32 v186, v0, v39 offset0:9 offset1:25

; __device__ __forceinline__ unsigned cvt_pk_bf16(float lo, float hi) { unsigned r; asm volatile("v_cvt_pk_bf16_f32 %0, %1, %2" : "=v"(r) : "v"(lo), "v"(hi)); return r; }
; __device__ __forceinline__ f32x2 gelu_pk(f32x2 v) {
;     const f32x2 av = __builtin_elementwise_abs(v), d = av * 0.2316418882f + 1.0f;
;     f32x2 t; t.x = __builtin_amdgcn_rcpf(d.x); t.y = __builtin_amdgcn_rcpf(d.y);
;     f32x2 q = t * 0.5307027145f + (-0.7265760135f); q = q * t + 0.7107068705f; q = q * t + (-0.142248368f); q = q * t + 0.127414796f; q = q * t;
;     const f32x2 s = (v * v) * (-0.72134752044f);
;     f32x2 e; e.x = __builtin_amdgcn_exp2f(s.x); e.y = __builtin_amdgcn_exp2f(s.y);
;     const f32x2 m = v * (q * e), r = v - m;
;     f32x2 o; o.x = v.x < 0.f ? m.x : r.x; o.y = v.y < 0.f ? m.y : r.y; return o;
;     __device__ __forceinline__ void operator()(const f32x4 (&acc)[2][2][4][2], const Unit& u, int wr, int wc, int fr, int fq) const {
;     ...
;             for (int m = 0; m < 4; ++m) { const int row = row0 + ai * HALF + m * 16; const float rs = rsv[ai][m]; bf16_t* rowp = O + (size_t)row * ldc + col0; float s1 = 0.f, s2 = 0.f;
; #pragma unroll
;                 for (int bj = 0; bj < 2; ++bj) { f32x4 v0 = acc[ai][bj][m][0] * rs, v1 = acc[ai][bj][m][1] * rs;
;                     const f32x2 a = gelu_pk((f32x2){v0[0], v0[1]}), b = gelu_pk((f32x2){v0[2], v0[3]}), c = gelu_pk((f32x2){v1[0], v1[1]}), d = gelu_pk((f32x2){v1[2], v1[3]});
;                     s1 += ((a.x + a.y) + (b.x + b.y)) + ((c.x + c.y) + (d.x + d.y));
;                     s2 += ((a.x * a.x + a.y * a.y) + (b.x * b.x + b.y * b.y)) + ((c.x * c.x + c.y * c.y) + (d.x * d.x + d.y * d.y));
;                     u32x4 w; w.x = cvt_pk_bf16(a.x, a.y); w.y = cvt_pk_bf16(b.x, b.y); w.z = cvt_pk_bf16(c.x, c.y); w.w = cvt_pk_bf16(d.x, d.y);
;                     *(u32x4*)(rowp + bj * HALF) = w; }
.LBB0_376:
	v_add_f32_e32 v0, v54, v55
	s_waitcnt lgkmcnt(0)
	v_add_f32_e32 v38, v56, v57
	v_add_f32_e32 v0, v0, v38
	v_fmamk_f32 v0, v0, 0x3a800000, v224
	v_rsq_f32_e32 v0, v0
	s_mov_b32 s4, 0xbf3a00e3
	v_lshlrev_b64 v[38:39], 12, v[164:165]
	v_lshl_add_u64 v[38:39], s[20:21], 0, v[38:39]
	v_pk_mul_f32 v[30:31], v[30:31], v[0:1] op_sel_hi:[1,0]
	v_pk_mul_f32 v[40:41], v[26:27], v[0:1] op_sel_hi:[1,0]
	v_and_b32_e32 v27, 0x7fffffff, v31
	v_and_b32_e32 v26, 0x7fffffff, v30
	v_pk_fma_f32 v[26:27], v[26:27], s[64:65], 1.0 op_sel_hi:[1,0,0]
	v_pk_mul_f32 v[46:47], v[30:31], v[30:31]
	v_rcp_f32_e32 v42, v26
	v_rcp_f32_e32 v43, v27
	v_mov_b64_e32 v[26:27], s[4:5]
	v_pk_mul_f32 v[46:47], v[46:47], s[76:77] op_sel_hi:[1,0]
	v_cmp_gt_f32_e32 vcc, 0, v30
	v_pk_fma_f32 v[44:45], v[42:43], s[66:67], v[26:27] op_sel_hi:[1,0,0]
	v_exp_f32_e32 v46, v46
	v_pk_fma_f32 v[44:45], v[42:43], v[44:45], s[70:71] op_sel_hi:[1,1,0]
	v_exp_f32_e32 v47, v47
	v_pk_fma_f32 v[44:45], v[42:43], v[44:45], s[72:73] op_sel_hi:[1,1,0]
	v_pk_mul_f32 v[32:33], v[32:33], v[0:1] op_sel_hi:[1,0]
	v_pk_fma_f32 v[44:45], v[42:43], v[44:45], s[74:75] op_sel_hi:[1,1,0]
	v_pk_mul_f32 v[28:29], v[28:29], v[0:1] op_sel_hi:[1,0]
	v_pk_mul_f32 v[42:43], v[42:43], v[44:45]
	v_pk_mul_f32 v[44:45], v[32:33], v[32:33]
	v_pk_mul_f32 v[42:43], v[46:47], v[42:43]
	v_pk_mul_f32 v[44:45], v[44:45], s[76:77] op_sel_hi:[1,0]
	v_pk_mul_f32 v[46:47], v[30:31], v[42:43]
	v_pk_fma_f32 v[42:43], v[30:31], v[42:43], v[30:31] neg_lo:[1,0,0] neg_hi:[1,0,0]
	v_exp_f32_e32 v44, v44
	v_cndmask_b32_e32 v30, v42, v46, vcc
	v_cmp_gt_f32_e32 vcc, 0, v31
	v_and_b32_e32 v42, 0x7fffffff, v32
	v_exp_f32_e32 v45, v45
	v_cndmask_b32_e32 v31, v43, v47, vcc
	v_and_b32_e32 v43, 0x7fffffff, v33
	v_pk_fma_f32 v[42:43], v[42:43], s[64:65], 1.0 op_sel_hi:[1,0,0]
	v_cmp_gt_f32_e32 vcc, 0, v32
	v_rcp_f32_e32 v42, v42
	v_rcp_f32_e32 v43, v43
	v_lshl_add_u64 v[38:39], v[160:161], 1, v[38:39]
	v_pk_mul_f32 v[22:23], v[22:23], v[0:1] op_sel_hi:[1,0]
	v_pk_mul_f32 v[24:25], v[24:25], v[0:1] op_sel_hi:[1,0]
	v_pk_fma_f32 v[46:47], v[42:43], s[66:67], v[26:27] op_sel_hi:[1,0,0]
	v_pk_mul_f32 v[20:21], v[20:21], v[0:1] op_sel_hi:[1,0]
	v_pk_fma_f32 v[46:47], v[42:43], v[46:47], s[70:71] op_sel_hi:[1,1,0]
	s_nop 0
	v_pk_fma_f32 v[46:47], v[42:43], v[46:47], s[72:73] op_sel_hi:[1,1,0]
	s_nop 0
	v_pk_fma_f32 v[46:47], v[42:43], v[46:47], s[74:75] op_sel_hi:[1,1,0]
	s_nop 0
	v_pk_mul_f32 v[42:43], v[42:43], v[46:47]
	v_pk_mul_f32 v[46:47], v[40:41], v[40:41]
	v_pk_mul_f32 v[42:43], v[44:45], v[42:43]
	v_pk_mul_f32 v[46:47], v[46:47], s[76:77] op_sel_hi:[1,0]
	v_pk_mul_f32 v[44:45], v[32:33], v[42:43]
	v_pk_fma_f32 v[42:43], v[32:33], v[42:43], v[32:33] neg_lo:[1,0,0] neg_hi:[1,0,0]
	v_exp_f32_e32 v46, v46
	v_cndmask_b32_e32 v32, v42, v44, vcc
	v_cmp_gt_f32_e32 vcc, 0, v33
	v_and_b32_e32 v42, 0x7fffffff, v40
	v_exp_f32_e32 v47, v47
	v_cndmask_b32_e32 v33, v43, v45, vcc
	v_and_b32_e32 v43, 0x7fffffff, v41
	v_pk_fma_f32 v[42:43], v[42:43], s[64:65], 1.0 op_sel_hi:[1,0,0]
	v_cmp_gt_f32_e32 vcc, 0, v40
	v_rcp_f32_e32 v42, v42
	v_rcp_f32_e32 v43, v43
	s_nop 0
	v_pk_fma_f32 v[44:45], v[42:43], s[66:67], v[26:27] op_sel_hi:[1,0,0]
	s_nop 0
	v_pk_fma_f32 v[44:45], v[42:43], v[44:45], s[70:71] op_sel_hi:[1,1,0]
	s_nop 0
	v_pk_fma_f32 v[44:45], v[42:43], v[44:45], s[72:73] op_sel_hi:[1,1,0]
	s_nop 0
	v_pk_fma_f32 v[44:45], v[42:43], v[44:45], s[74:75] op_sel_hi:[1,1,0]
	s_nop 0
	v_pk_mul_f32 v[42:43], v[42:43], v[44:45]
	v_pk_mul_f32 v[44:45], v[28:29], v[28:29]
	v_pk_mul_f32 v[42:43], v[46:47], v[42:43]
	v_pk_mul_f32 v[44:45], v[44:45], s[76:77] op_sel_hi:[1,0]
	v_pk_mul_f32 v[46:47], v[40:41], v[42:43]
	v_pk_fma_f32 v[42:43], v[40:41], v[42:43], v[40:41] neg_lo:[1,0,0] neg_hi:[1,0,0]
	v_exp_f32_e32 v44, v44
	v_cndmask_b32_e32 v40, v42, v46, vcc
	v_cmp_gt_f32_e32 vcc, 0, v41
	v_and_b32_e32 v42, 0x7fffffff, v28
	v_exp_f32_e32 v45, v45
	v_cndmask_b32_e32 v41, v43, v47, vcc
	v_and_b32_e32 v43, 0x7fffffff, v29
	v_pk_fma_f32 v[42:43], v[42:43], s[64:65], 1.0 op_sel_hi:[1,0,0]
	v_cmp_gt_f32_e32 vcc, 0, v28
	v_rcp_f32_e32 v42, v42
	v_rcp_f32_e32 v43, v43
	s_nop 0
	v_pk_fma_f32 v[46:47], v[42:43], s[66:67], v[26:27] op_sel_hi:[1,0,0]
	s_nop 0
	v_pk_fma_f32 v[46:47], v[42:43], v[46:47], s[70:71] op_sel_hi:[1,1,0]
	s_nop 0
	v_pk_fma_f32 v[46:47], v[42:43], v[46:47], s[72:73] op_sel_hi:[1,1,0]
	s_nop 0
	v_pk_fma_f32 v[46:47], v[42:43], v[46:47], s[74:75] op_sel_hi:[1,1,0]
	s_nop 0
	v_pk_mul_f32 v[42:43], v[42:43], v[46:47]
	v_pk_mul_f32 v[46:47], v[22:23], v[22:23]
	v_pk_mul_f32 v[42:43], v[44:45], v[42:43]
	v_pk_mul_f32 v[46:47], v[46:47], s[76:77] op_sel_hi:[1,0]
	v_pk_mul_f32 v[44:45], v[28:29], v[42:43]
	v_pk_fma_f32 v[42:43], v[28:29], v[42:43], v[28:29] neg_lo:[1,0,0] neg_hi:[1,0,0]
	v_exp_f32_e32 v46, v46
	v_cndmask_b32_e32 v28, v42, v44, vcc
	v_cmp_gt_f32_e32 vcc, 0, v29
	v_cvt_pk_bf16_f32 v42, v30, v31
	v_exp_f32_e32 v47, v47
	s_nop 0
	v_cndmask_b32_e32 v29, v43, v45, vcc
	v_cvt_pk_bf16_f32 v43, v32, v33
	v_cvt_pk_bf16_f32 v44, v40, v41
	v_cvt_pk_bf16_f32 v45, v28, v29
	global_store_dwordx4 v[38:39], v[42:45], off
	v_cmp_gt_f32_e32 vcc, 0, v22
	s_nop 0
	v_pk_mul_f32 v[42:43], v[18:19], v[0:1] op_sel_hi:[1,0]
	v_and_b32_e32 v19, 0x7fffffff, v23
	v_and_b32_e32 v18, 0x7fffffff, v22
	v_pk_fma_f32 v[18:19], v[18:19], s[64:65], 1.0 op_sel_hi:[1,0,0]
	s_nop 0
	v_rcp_f32_e32 v18, v18
	v_rcp_f32_e32 v19, v19
	s_nop 0
	v_pk_fma_f32 v[44:45], v[18:19], s[66:67], v[26:27] op_sel_hi:[1,0,0]
	s_nop 0
	v_pk_fma_f32 v[44:45], v[18:19], v[44:45], s[70:71] op_sel_hi:[1,1,0]
	s_nop 0
	v_pk_fma_f32 v[44:45], v[18:19], v[44:45], s[72:73] op_sel_hi:[1,1,0]
	s_nop 0
; __device__ __forceinline__ unsigned cvt_pk_bf16(float lo, float hi) { unsigned r; asm volatile("v_cvt_pk_bf16_f32 %0, %1, %2" : "=v"(r) : "v"(lo), "v"(hi)); return r; }
; __device__ __forceinline__ f32x2 gelu_pk(f32x2 v) {
;     const f32x2 av = __builtin_elementwise_abs(v), d = av * 0.2316418882f + 1.0f;
;     f32x2 t; t.x = __builtin_amdgcn_rcpf(d.x); t.y = __builtin_amdgcn_rcpf(d.y);
;     f32x2 q = t * 0.5307027145f + (-0.7265760135f); q = q * t + 0.7107068705f; q = q * t + (-0.142248368f); q = q * t + 0.127414796f; q = q * t;
;     const f32x2 s = (v * v) * (-0.72134752044f);
;     f32x2 e; e.x = __builtin_amdgcn_exp2f(s.x); e.y = __builtin_amdgcn_exp2f(s.y);
;     const f32x2 m = v * (q * e), r = v - m;
;     f32x2 o; o.x = v.x < 0.f ? m.x : r.x; o.y = v.y < 0.f ? m.y : r.y; return o;
;     __device__ __forceinline__ void operator()(const f32x4 (&acc)[2][2][4][2], const Unit& u, int wr, int wc, int fr, int fq) const {
;     ...
;                 for (int bj = 0; bj < 2; ++bj) { f32x4 v0 = acc[ai][bj][m][0] * rs, v1 = acc[ai][bj][m][1] * rs;
;                     const f32x2 a = gelu_pk((f32x2){v0[0], v0[1]}), b = gelu_pk((f32x2){v0[2], v0[3]}), c = gelu_pk((f32x2){v1[0], v1[1]}), d = gelu_pk((f32x2){v1[2], v1[3]});
;                     s1 += ((a.x + a.y) + (b.x + b.y)) + ((c.x + c.y) + (d.x + d.y));
;                     s2 += ((a.x * a.x + a.y * a.y) + (b.x * b.x + b.y * b.y)) + ((c.x * c.x + c.y * c.y) + (d.x * d.x + d.y * d.y));
;                     u32x4 w; w.x = cvt_pk_bf16(a.x, a.y); w.y = cvt_pk_bf16(b.x, b.y); w.z = cvt_pk_bf16(c.x, c.y); w.w = cvt_pk_bf16(d.x, d.y);
;                     *(u32x4*)(rowp + bj * HALF) = w; }
;                 if (isv) { s1 += __shfl_xor(s1, 16); s1 += __shfl_xor(s1, 32); s2 += __shfl_xor(s2, 16); s2 += __shfl_xor(s2, 32);
;                     if (fq == 0) { const int rl = ai * HALF + wr * 64 + m * 16 + fr; part[rl * 4 + wc] = s1; part[1024 + rl * 4 + wc] = s2; } } }
	v_pk_fma_f32 v[44:45], v[18:19], v[44:45], s[74:75] op_sel_hi:[1,1,0]
	s_nop 0
	v_pk_mul_f32 v[18:19], v[18:19], v[44:45]
	v_pk_mul_f32 v[44:45], v[24:25], v[24:25]
	v_pk_mul_f32 v[18:19], v[46:47], v[18:19]
	v_pk_mul_f32 v[44:45], v[44:45], s[76:77] op_sel_hi:[1,0]
	v_pk_mul_f32 v[46:47], v[22:23], v[18:19]
	v_pk_fma_f32 v[18:19], v[22:23], v[18:19], v[22:23] neg_lo:[1,0,0] neg_hi:[1,0,0]
	v_and_b32_e32 v22, 0x7fffffff, v24
	v_cndmask_b32_e32 v0, v18, v46, vcc
	v_cmp_gt_f32_e32 vcc, 0, v23
	v_and_b32_e32 v23, 0x7fffffff, v25
	v_pk_fma_f32 v[22:23], v[22:23], s[64:65], 1.0 op_sel_hi:[1,0,0]
	v_cndmask_b32_e32 v18, v19, v47, vcc
	v_rcp_f32_e32 v22, v22
	v_rcp_f32_e32 v23, v23
	v_exp_f32_e32 v44, v44
	v_exp_f32_e32 v45, v45
	v_cmp_gt_f32_e32 vcc, 0, v24
	v_pk_fma_f32 v[46:47], v[22:23], s[66:67], v[26:27] op_sel_hi:[1,0,0]
	s_nop 0
	v_pk_fma_f32 v[46:47], v[22:23], v[46:47], s[70:71] op_sel_hi:[1,1,0]
	s_nop 0
	v_pk_fma_f32 v[46:47], v[22:23], v[46:47], s[72:73] op_sel_hi:[1,1,0]
	s_nop 0
	v_pk_fma_f32 v[46:47], v[22:23], v[46:47], s[74:75] op_sel_hi:[1,1,0]
	s_nop 0
	v_pk_mul_f32 v[22:23], v[22:23], v[46:47]
	v_pk_mul_f32 v[46:47], v[42:43], v[42:43]
	v_pk_mul_f32 v[22:23], v[44:45], v[22:23]
	v_pk_mul_f32 v[46:47], v[46:47], s[76:77] op_sel_hi:[1,0]
	v_pk_mul_f32 v[44:45], v[24:25], v[22:23]
	v_pk_fma_f32 v[22:23], v[24:25], v[22:23], v[24:25] neg_lo:[1,0,0] neg_hi:[1,0,0]
	v_and_b32_e32 v24, 0x7fffffff, v42
	v_cndmask_b32_e32 v19, v22, v44, vcc
	v_cmp_gt_f32_e32 vcc, 0, v25
	v_and_b32_e32 v25, 0x7fffffff, v43
	v_pk_fma_f32 v[24:25], v[24:25], s[64:65], 1.0 op_sel_hi:[1,0,0]
	v_cndmask_b32_e32 v22, v23, v45, vcc
	v_rcp_f32_e32 v24, v24
	v_rcp_f32_e32 v25, v25
	v_exp_f32_e32 v46, v46
	v_exp_f32_e32 v47, v47
	v_cmp_gt_f32_e32 vcc, 0, v42
	v_pk_fma_f32 v[44:45], v[24:25], s[66:67], v[26:27] op_sel_hi:[1,0,0]
	s_nop 0
	v_pk_fma_f32 v[44:45], v[24:25], v[44:45], s[70:71] op_sel_hi:[1,1,0]
	s_nop 0
	v_pk_fma_f32 v[44:45], v[24:25], v[44:45], s[72:73] op_sel_hi:[1,1,0]
	s_nop 0
	v_pk_fma_f32 v[44:45], v[24:25], v[44:45], s[74:75] op_sel_hi:[1,1,0]
	s_nop 0
	v_pk_mul_f32 v[24:25], v[24:25], v[44:45]
	v_pk_mul_f32 v[44:45], v[20:21], v[20:21]
	v_pk_mul_f32 v[24:25], v[46:47], v[24:25]
	s_nop 0
	v_pk_mul_f32 v[46:47], v[42:43], v[24:25]
	v_pk_fma_f32 v[24:25], v[42:43], v[24:25], v[42:43] neg_lo:[1,0,0] neg_hi:[1,0,0]
	v_and_b32_e32 v42, 0x7fffffff, v20
	v_cndmask_b32_e32 v23, v24, v46, vcc
	v_cmp_gt_f32_e32 vcc, 0, v43
	v_and_b32_e32 v43, 0x7fffffff, v21
	v_pk_fma_f32 v[42:43], v[42:43], s[64:65], 1.0 op_sel_hi:[1,0,0]
	v_cndmask_b32_e32 v24, v25, v47, vcc
	v_rcp_f32_e32 v42, v42
	v_rcp_f32_e32 v43, v43
	v_cmp_gt_f32_e32 vcc, 0, v20
	v_pk_fma_f32 v[26:27], v[42:43], s[66:67], v[26:27] op_sel_hi:[1,0,0]
	s_nop 0
	v_pk_fma_f32 v[26:27], v[42:43], v[26:27], s[70:71] op_sel_hi:[1,1,0]
	s_nop 0
	v_pk_fma_f32 v[26:27], v[42:43], v[26:27], s[72:73] op_sel_hi:[1,1,0]
	s_nop 0
	v_pk_fma_f32 v[26:27], v[42:43], v[26:27], s[74:75] op_sel_hi:[1,1,0]
	s_nop 0
	v_pk_mul_f32 v[26:27], v[42:43], v[26:27]
	v_pk_mul_f32 v[42:43], v[44:45], s[76:77] op_sel_hi:[1,0]
	s_nop 0
	v_exp_f32_e32 v42, v42
	v_exp_f32_e32 v43, v43
	s_nop 0
	v_pk_mul_f32 v[26:27], v[42:43], v[26:27]
	s_nop 0
	v_pk_mul_f32 v[42:43], v[20:21], v[26:27]
	v_pk_fma_f32 v[26:27], v[20:21], v[26:27], v[20:21] neg_lo:[1,0,0] neg_hi:[1,0,0]
	s_nop 0
	v_cndmask_b32_e32 v20, v26, v42, vcc
	v_cmp_gt_f32_e32 vcc, 0, v21
	v_cvt_pk_bf16_f32 v42, v0, v18
	s_nop 1
	v_cndmask_b32_e32 v21, v27, v43, vcc
	s_and_b64 vcc, exec, s[10:11]
	v_cvt_pk_bf16_f32 v43, v19, v22
	v_cvt_pk_bf16_f32 v44, v23, v24
	v_cvt_pk_bf16_f32 v45, v20, v21
	global_store_dwordx4 v[38:39], v[42:45], off offset:256
	s_cbranch_vccnz .LBB0_380
	v_mul_f32_e32 v25, v31, v31
	v_mul_f32_e32 v26, v33, v33
	v_fmac_f32_e32 v25, v30, v30
	v_fmac_f32_e32 v26, v32, v32
	v_add_f32_e32 v25, v25, v26
	v_mul_f32_e32 v26, v41, v41
	v_mul_f32_e32 v27, v29, v29
	v_fmac_f32_e32 v26, v40, v40
	v_fmac_f32_e32 v27, v28, v28
	v_add_f32_e32 v26, v26, v27
	v_add_f32_e32 v25, v25, v26
	v_mul_f32_e32 v26, v18, v18
	v_fmac_f32_e32 v26, v0, v0
	v_mul_f32_e32 v27, v22, v22
	v_add_f32_e32 v0, v0, v18
	v_add_f32_e32 v18, v19, v22
	v_fmac_f32_e32 v27, v19, v19
	v_add_f32_e32 v30, v30, v31
	v_add_f32_e32 v31, v32, v33
	v_add_f32_e32 v0, v0, v18
	v_add_f32_e32 v18, v23, v24
	v_add_f32_e32 v19, v20, v21
	v_add_f32_e32 v30, v30, v31
	v_add_f32_e32 v31, v40, v41
	v_add_f32_e32 v28, v28, v29
	v_add_f32_e32 v18, v18, v19
	v_and_b32_e32 v19, 64, v226
	v_add_f32_e32 v28, v31, v28
	v_add_f32_e32 v0, v0, v18
	v_xor_b32_e32 v18, 16, v226
	v_add_u32_e32 v19, 64, v19
	v_add_f32_e32 v28, v30, v28
	v_cmp_lt_i32_e32 vcc, v18, v19
	v_add_f32_e32 v26, v26, v27
	v_mul_f32_e32 v27, v24, v24
	v_mul_f32_e32 v38, v21, v21
	v_add_f32_e32 v28, 0, v28
	v_cndmask_b32_e32 v18, v226, v18, vcc
	v_fmac_f32_e32 v27, v23, v23
	v_add_f32_e32 v0, v0, v28
	v_lshlrev_b32_e32 v18, 2, v18
	v_fmac_f32_e32 v38, v20, v20
	v_mov_b32_e32 v21, v0
	s_nop 1
	v_permlane16_swap_b32_e32 v21, v0
	v_add_f32_e32 v20, v27, v38
	v_add_f32_e32 v20, v26, v20
	v_add_f32_e32 v20, v25, v20
	v_mov_b32_e32 v22, v20
	s_nop 1
	v_permlane16_swap_b32_e32 v22, v20
	s_waitcnt lgkmcnt(0)
	v_add_f32_e32 v0, v0, v21
	v_xor_b32_e32 v21, 32, v226
	v_cmp_lt_i32_e32 vcc, v21, v19
	v_add_f32_e32 v19, v20, v22
	s_nop 0
	v_cndmask_b32_e32 v18, v226, v21, vcc
	v_lshlrev_b32_e32 v21, 2, v18
	v_mov_b32_e32 v18, v0
	s_nop 1
	v_permlane32_swap_b32_e32 v18, v0
	v_mov_b32_e32 v20, v19
	s_nop 1
	v_permlane32_swap_b32_e32 v20, v19
	s_and_saveexec_b64 s[4:5], s[6:7]
	s_cbranch_execz .LBB0_379
	s_waitcnt lgkmcnt(0)
	v_add_f32_e32 v19, v19, v20
	v_add_f32_e32 v0, v0, v18
	ds_write2st64_b32 v186, v0, v19 offset0:10 offset1:26

; __device__ __forceinline__ unsigned cvt_pk_bf16(float lo, float hi) { unsigned r; asm volatile("v_cvt_pk_bf16_f32 %0, %1, %2" : "=v"(r) : "v"(lo), "v"(hi)); return r; }
; __device__ __forceinline__ f32x2 gelu_pk(f32x2 v) {
;     const f32x2 av = __builtin_elementwise_abs(v), d = av * 0.2316418882f + 1.0f;
;     f32x2 t; t.x = __builtin_amdgcn_rcpf(d.x); t.y = __builtin_amdgcn_rcpf(d.y);
;     f32x2 q = t * 0.5307027145f + (-0.7265760135f); q = q * t + 0.7107068705f; q = q * t + (-0.142248368f); q = q * t + 0.127414796f; q = q * t;
;     const f32x2 s = (v * v) * (-0.72134752044f);
;     f32x2 e; e.x = __builtin_amdgcn_exp2f(s.x); e.y = __builtin_amdgcn_exp2f(s.y);
;     const f32x2 m = v * (q * e), r = v - m;
;     f32x2 o; o.x = v.x < 0.f ? m.x : r.x; o.y = v.y < 0.f ? m.y : r.y; return o;
;     __device__ __forceinline__ void operator()(const f32x4 (&acc)[2][2][4][2], const Unit& u, int wr, int wc, int fr, int fq) const {
;     ...
;             for (int m = 0; m < 4; ++m) { const int row = row0 + ai * HALF + m * 16; const float rs = rsv[ai][m]; bf16_t* rowp = O + (size_t)row * ldc + col0; float s1 = 0.f, s2 = 0.f;
; #pragma unroll
;                 for (int bj = 0; bj < 2; ++bj) { f32x4 v0 = acc[ai][bj][m][0] * rs, v1 = acc[ai][bj][m][1] * rs;
;                     const f32x2 a = gelu_pk((f32x2){v0[0], v0[1]}), b = gelu_pk((f32x2){v0[2], v0[3]}), c = gelu_pk((f32x2){v1[0], v1[1]}), d = gelu_pk((f32x2){v1[2], v1[3]});
;                     s1 += ((a.x + a.y) + (b.x + b.y)) + ((c.x + c.y) + (d.x + d.y));
;                     s2 += ((a.x * a.x + a.y * a.y) + (b.x * b.x + b.y * b.y)) + ((c.x * c.x + c.y * c.y) + (d.x * d.x + d.y * d.y));
;                     u32x4 w; w.x = cvt_pk_bf16(a.x, a.y); w.y = cvt_pk_bf16(b.x, b.y); w.z = cvt_pk_bf16(c.x, c.y); w.w = cvt_pk_bf16(d.x, d.y);
;                     *(u32x4*)(rowp + bj * HALF) = w; }
.LBB0_380:
	v_add_f32_e32 v0, v34, v35
	s_waitcnt lgkmcnt(0)
	v_add_f32_e32 v18, v36, v37
	v_add_f32_e32 v0, v0, v18
	v_fmamk_f32 v0, v0, 0x3a800000, v224
	v_rsq_f32_e32 v0, v0
	s_mov_b32 s4, 0xbf3a00e3
	v_lshlrev_b64 v[18:19], 12, v[162:163]
	v_lshl_add_u64 v[18:19], s[20:21], 0, v[18:19]
	v_pk_mul_f32 v[14:15], v[14:15], v[0:1] op_sel_hi:[1,0]
	v_pk_mul_f32 v[20:21], v[10:11], v[0:1] op_sel_hi:[1,0]
	v_and_b32_e32 v11, 0x7fffffff, v15
	v_and_b32_e32 v10, 0x7fffffff, v14
	v_pk_fma_f32 v[10:11], v[10:11], s[64:65], 1.0 op_sel_hi:[1,0,0]
	v_pk_mul_f32 v[26:27], v[14:15], v[14:15]
	v_rcp_f32_e32 v22, v10
	v_rcp_f32_e32 v23, v11
	v_mov_b64_e32 v[10:11], s[4:5]
	v_pk_mul_f32 v[26:27], v[26:27], s[76:77] op_sel_hi:[1,0]
	v_cmp_gt_f32_e32 vcc, 0, v14
	v_pk_fma_f32 v[24:25], v[22:23], s[66:67], v[10:11] op_sel_hi:[1,0,0]
	v_exp_f32_e32 v26, v26
	v_pk_fma_f32 v[24:25], v[22:23], v[24:25], s[70:71] op_sel_hi:[1,1,0]
	v_exp_f32_e32 v27, v27
	v_pk_fma_f32 v[24:25], v[22:23], v[24:25], s[72:73] op_sel_hi:[1,1,0]
	v_pk_mul_f32 v[16:17], v[16:17], v[0:1] op_sel_hi:[1,0]
	v_pk_fma_f32 v[24:25], v[22:23], v[24:25], s[74:75] op_sel_hi:[1,1,0]
	v_pk_mul_f32 v[12:13], v[12:13], v[0:1] op_sel_hi:[1,0]
	v_pk_mul_f32 v[22:23], v[22:23], v[24:25]
	v_pk_mul_f32 v[24:25], v[16:17], v[16:17]
	v_pk_mul_f32 v[22:23], v[26:27], v[22:23]
	v_pk_mul_f32 v[24:25], v[24:25], s[76:77] op_sel_hi:[1,0]
	v_pk_mul_f32 v[26:27], v[14:15], v[22:23]
	v_pk_fma_f32 v[22:23], v[14:15], v[22:23], v[14:15] neg_lo:[1,0,0] neg_hi:[1,0,0]
	v_exp_f32_e32 v24, v24
	v_cndmask_b32_e32 v14, v22, v26, vcc
	v_cmp_gt_f32_e32 vcc, 0, v15
	v_and_b32_e32 v22, 0x7fffffff, v16
	v_exp_f32_e32 v25, v25
	v_cndmask_b32_e32 v15, v23, v27, vcc
	v_and_b32_e32 v23, 0x7fffffff, v17
	v_pk_fma_f32 v[22:23], v[22:23], s[64:65], 1.0 op_sel_hi:[1,0,0]
	v_cmp_gt_f32_e32 vcc, 0, v16
	v_rcp_f32_e32 v22, v22
	v_rcp_f32_e32 v23, v23
	v_lshl_add_u64 v[18:19], v[160:161], 1, v[18:19]
	v_pk_mul_f32 v[6:7], v[6:7], v[0:1] op_sel_hi:[1,0]
	v_pk_mul_f32 v[8:9], v[8:9], v[0:1] op_sel_hi:[1,0]
	v_pk_fma_f32 v[26:27], v[22:23], s[66:67], v[10:11] op_sel_hi:[1,0,0]
	v_pk_mul_f32 v[4:5], v[4:5], v[0:1] op_sel_hi:[1,0]
	v_pk_fma_f32 v[26:27], v[22:23], v[26:27], s[70:71] op_sel_hi:[1,1,0]
	s_nop 0
	v_pk_fma_f32 v[26:27], v[22:23], v[26:27], s[72:73] op_sel_hi:[1,1,0]
	s_nop 0
	v_pk_fma_f32 v[26:27], v[22:23], v[26:27], s[74:75] op_sel_hi:[1,1,0]
	s_nop 0
	v_pk_mul_f32 v[22:23], v[22:23], v[26:27]
	v_pk_mul_f32 v[26:27], v[20:21], v[20:21]
	v_pk_mul_f32 v[22:23], v[24:25], v[22:23]
	v_pk_mul_f32 v[26:27], v[26:27], s[76:77] op_sel_hi:[1,0]
	v_pk_mul_f32 v[24:25], v[16:17], v[22:23]
	v_pk_fma_f32 v[22:23], v[16:17], v[22:23], v[16:17] neg_lo:[1,0,0] neg_hi:[1,0,0]
	v_exp_f32_e32 v26, v26
	v_cndmask_b32_e32 v16, v22, v24, vcc
	v_cmp_gt_f32_e32 vcc, 0, v17
	v_and_b32_e32 v22, 0x7fffffff, v20
	v_exp_f32_e32 v27, v27
	v_cndmask_b32_e32 v17, v23, v25, vcc
	v_and_b32_e32 v23, 0x7fffffff, v21
	v_pk_fma_f32 v[22:23], v[22:23], s[64:65], 1.0 op_sel_hi:[1,0,0]
	v_cmp_gt_f32_e32 vcc, 0, v20
	v_rcp_f32_e32 v22, v22
	v_rcp_f32_e32 v23, v23
	s_nop 0
	v_pk_fma_f32 v[24:25], v[22:23], s[66:67], v[10:11] op_sel_hi:[1,0,0]
	s_nop 0
	v_pk_fma_f32 v[24:25], v[22:23], v[24:25], s[70:71] op_sel_hi:[1,1,0]
	s_nop 0
	v_pk_fma_f32 v[24:25], v[22:23], v[24:25], s[72:73] op_sel_hi:[1,1,0]
	s_nop 0
	v_pk_fma_f32 v[24:25], v[22:23], v[24:25], s[74:75] op_sel_hi:[1,1,0]
	s_nop 0
	v_pk_mul_f32 v[22:23], v[22:23], v[24:25]
	v_pk_mul_f32 v[24:25], v[12:13], v[12:13]
	v_pk_mul_f32 v[22:23], v[26:27], v[22:23]
	v_pk_mul_f32 v[24:25], v[24:25], s[76:77] op_sel_hi:[1,0]
	v_pk_mul_f32 v[26:27], v[20:21], v[22:23]
	v_pk_fma_f32 v[22:23], v[20:21], v[22:23], v[20:21] neg_lo:[1,0,0] neg_hi:[1,0,0]
	v_exp_f32_e32 v24, v24
	v_cndmask_b32_e32 v20, v22, v26, vcc
	v_cmp_gt_f32_e32 vcc, 0, v21
	v_and_b32_e32 v22, 0x7fffffff, v12
	v_exp_f32_e32 v25, v25
	v_cndmask_b32_e32 v21, v23, v27, vcc
	v_and_b32_e32 v23, 0x7fffffff, v13
	v_pk_fma_f32 v[22:23], v[22:23], s[64:65], 1.0 op_sel_hi:[1,0,0]
	v_cmp_gt_f32_e32 vcc, 0, v12
	v_rcp_f32_e32 v22, v22
	v_rcp_f32_e32 v23, v23
	s_nop 0
	v_pk_fma_f32 v[26:27], v[22:23], s[66:67], v[10:11] op_sel_hi:[1,0,0]
	s_nop 0
	v_pk_fma_f32 v[26:27], v[22:23], v[26:27], s[70:71] op_sel_hi:[1,1,0]
	s_nop 0
	v_pk_fma_f32 v[26:27], v[22:23], v[26:27], s[72:73] op_sel_hi:[1,1,0]
	s_nop 0
	v_pk_fma_f32 v[26:27], v[22:23], v[26:27], s[74:75] op_sel_hi:[1,1,0]
	s_nop 0
	v_pk_mul_f32 v[22:23], v[22:23], v[26:27]
	v_pk_mul_f32 v[26:27], v[6:7], v[6:7]
	v_pk_mul_f32 v[22:23], v[24:25], v[22:23]
	v_pk_mul_f32 v[26:27], v[26:27], s[76:77] op_sel_hi:[1,0]
	v_pk_mul_f32 v[24:25], v[12:13], v[22:23]
	v_pk_fma_f32 v[22:23], v[12:13], v[22:23], v[12:13] neg_lo:[1,0,0] neg_hi:[1,0,0]
	v_exp_f32_e32 v26, v26
	v_cndmask_b32_e32 v12, v22, v24, vcc
	v_cmp_gt_f32_e32 vcc, 0, v13
	v_cvt_pk_bf16_f32 v22, v14, v15
	v_exp_f32_e32 v27, v27
	s_nop 0
	v_cndmask_b32_e32 v13, v23, v25, vcc
	v_cvt_pk_bf16_f32 v23, v16, v17
	v_cvt_pk_bf16_f32 v24, v20, v21
	v_cvt_pk_bf16_f32 v25, v12, v13
	global_store_dwordx4 v[18:19], v[22:25], off
	v_cmp_gt_f32_e32 vcc, 0, v6
	s_nop 0
	v_pk_mul_f32 v[22:23], v[2:3], v[0:1] op_sel_hi:[1,0]
	v_and_b32_e32 v3, 0x7fffffff, v7
	v_and_b32_e32 v2, 0x7fffffff, v6
	v_pk_fma_f32 v[2:3], v[2:3], s[64:65], 1.0 op_sel_hi:[1,0,0]
	s_nop 0
	v_rcp_f32_e32 v2, v2
	v_rcp_f32_e32 v3, v3
	s_nop 0
	v_pk_fma_f32 v[24:25], v[2:3], s[66:67], v[10:11] op_sel_hi:[1,0,0]
	s_nop 0
	v_pk_fma_f32 v[24:25], v[2:3], v[24:25], s[70:71] op_sel_hi:[1,1,0]
	s_nop 0
; __device__ __forceinline__ unsigned cvt_pk_bf16(float lo, float hi) { unsigned r; asm volatile("v_cvt_pk_bf16_f32 %0, %1, %2" : "=v"(r) : "v"(lo), "v"(hi)); return r; }
; __device__ __forceinline__ f32x2 gelu_pk(f32x2 v) {
;     const f32x2 av = __builtin_elementwise_abs(v), d = av * 0.2316418882f + 1.0f;
;     f32x2 t; t.x = __builtin_amdgcn_rcpf(d.x); t.y = __builtin_amdgcn_rcpf(d.y);
;     f32x2 q = t * 0.5307027145f + (-0.7265760135f); q = q * t + 0.7107068705f; q = q * t + (-0.142248368f); q = q * t + 0.127414796f; q = q * t;
;     const f32x2 s = (v * v) * (-0.72134752044f);
;     f32x2 e; e.x = __builtin_amdgcn_exp2f(s.x); e.y = __builtin_amdgcn_exp2f(s.y);
;     const f32x2 m = v * (q * e), r = v - m;
;     f32x2 o; o.x = v.x < 0.f ? m.x : r.x; o.y = v.y < 0.f ? m.y : r.y; return o;
;     __device__ __forceinline__ void operator()(const f32x4 (&acc)[2][2][4][2], const Unit& u, int wr, int wc, int fr, int fq) const {
;     ...
;                 for (int bj = 0; bj < 2; ++bj) { f32x4 v0 = acc[ai][bj][m][0] * rs, v1 = acc[ai][bj][m][1] * rs;
;                     const f32x2 a = gelu_pk((f32x2){v0[0], v0[1]}), b = gelu_pk((f32x2){v0[2], v0[3]}), c = gelu_pk((f32x2){v1[0], v1[1]}), d = gelu_pk((f32x2){v1[2], v1[3]});
;                     s1 += ((a.x + a.y) + (b.x + b.y)) + ((c.x + c.y) + (d.x + d.y));
;                     s2 += ((a.x * a.x + a.y * a.y) + (b.x * b.x + b.y * b.y)) + ((c.x * c.x + c.y * c.y) + (d.x * d.x + d.y * d.y));
;                     u32x4 w; w.x = cvt_pk_bf16(a.x, a.y); w.y = cvt_pk_bf16(b.x, b.y); w.z = cvt_pk_bf16(c.x, c.y); w.w = cvt_pk_bf16(d.x, d.y);
;                     *(u32x4*)(rowp + bj * HALF) = w; }
;                 if (isv) { s1 += __shfl_xor(s1, 16); s1 += __shfl_xor(s1, 32); s2 += __shfl_xor(s2, 16); s2 += __shfl_xor(s2, 32);
;                     if (fq == 0) { const int rl = ai * HALF + wr * 64 + m * 16 + fr; part[rl * 4 + wc] = s1; part[1024 + rl * 4 + wc] = s2; } } }
	v_pk_fma_f32 v[24:25], v[2:3], v[24:25], s[72:73] op_sel_hi:[1,1,0]
	s_nop 0
	v_pk_fma_f32 v[24:25], v[2:3], v[24:25], s[74:75] op_sel_hi:[1,1,0]
	s_nop 0
	v_pk_mul_f32 v[2:3], v[2:3], v[24:25]
	v_pk_mul_f32 v[24:25], v[8:9], v[8:9]
	v_pk_mul_f32 v[2:3], v[26:27], v[2:3]
	v_pk_mul_f32 v[24:25], v[24:25], s[76:77] op_sel_hi:[1,0]
	v_pk_mul_f32 v[26:27], v[6:7], v[2:3]
	v_pk_fma_f32 v[2:3], v[6:7], v[2:3], v[6:7] neg_lo:[1,0,0] neg_hi:[1,0,0]
	v_and_b32_e32 v6, 0x7fffffff, v8
	v_cndmask_b32_e32 v0, v2, v26, vcc
	v_cmp_gt_f32_e32 vcc, 0, v7
	v_and_b32_e32 v7, 0x7fffffff, v9
	v_pk_fma_f32 v[6:7], v[6:7], s[64:65], 1.0 op_sel_hi:[1,0,0]
	v_cndmask_b32_e32 v2, v3, v27, vcc
	v_rcp_f32_e32 v6, v6
	v_rcp_f32_e32 v7, v7
	v_exp_f32_e32 v24, v24
	v_exp_f32_e32 v25, v25
	v_cmp_gt_f32_e32 vcc, 0, v8
	v_pk_fma_f32 v[26:27], v[6:7], s[66:67], v[10:11] op_sel_hi:[1,0,0]
	s_nop 0
	v_pk_fma_f32 v[26:27], v[6:7], v[26:27], s[70:71] op_sel_hi:[1,1,0]
	s_nop 0
	v_pk_fma_f32 v[26:27], v[6:7], v[26:27], s[72:73] op_sel_hi:[1,1,0]
	s_nop 0
	v_pk_fma_f32 v[26:27], v[6:7], v[26:27], s[74:75] op_sel_hi:[1,1,0]
	s_nop 0
	v_pk_mul_f32 v[6:7], v[6:7], v[26:27]
	v_pk_mul_f32 v[26:27], v[22:23], v[22:23]
	v_pk_mul_f32 v[6:7], v[24:25], v[6:7]
	v_pk_mul_f32 v[26:27], v[26:27], s[76:77] op_sel_hi:[1,0]
	v_pk_mul_f32 v[24:25], v[8:9], v[6:7]
	v_pk_fma_f32 v[6:7], v[8:9], v[6:7], v[8:9] neg_lo:[1,0,0] neg_hi:[1,0,0]
	v_and_b32_e32 v8, 0x7fffffff, v22
	v_cndmask_b32_e32 v3, v6, v24, vcc
	v_cmp_gt_f32_e32 vcc, 0, v9
	v_and_b32_e32 v9, 0x7fffffff, v23
	v_pk_fma_f32 v[8:9], v[8:9], s[64:65], 1.0 op_sel_hi:[1,0,0]
	v_cndmask_b32_e32 v6, v7, v25, vcc
	v_rcp_f32_e32 v8, v8
	v_rcp_f32_e32 v9, v9
	v_exp_f32_e32 v26, v26
	v_exp_f32_e32 v27, v27
	v_cmp_gt_f32_e32 vcc, 0, v22
	v_pk_fma_f32 v[24:25], v[8:9], s[66:67], v[10:11] op_sel_hi:[1,0,0]
	s_nop 0
	v_pk_fma_f32 v[24:25], v[8:9], v[24:25], s[70:71] op_sel_hi:[1,1,0]
	s_nop 0
	v_pk_fma_f32 v[24:25], v[8:9], v[24:25], s[72:73] op_sel_hi:[1,1,0]
	s_nop 0
	v_pk_fma_f32 v[24:25], v[8:9], v[24:25], s[74:75] op_sel_hi:[1,1,0]
	s_nop 0
	v_pk_mul_f32 v[8:9], v[8:9], v[24:25]
	v_pk_mul_f32 v[24:25], v[4:5], v[4:5]
	v_pk_mul_f32 v[8:9], v[26:27], v[8:9]
	s_nop 0
	v_pk_mul_f32 v[26:27], v[22:23], v[8:9]
	v_pk_fma_f32 v[8:9], v[22:23], v[8:9], v[22:23] neg_lo:[1,0,0] neg_hi:[1,0,0]
	v_and_b32_e32 v22, 0x7fffffff, v4
	v_cndmask_b32_e32 v7, v8, v26, vcc
	v_cmp_gt_f32_e32 vcc, 0, v23
	v_and_b32_e32 v23, 0x7fffffff, v5
	v_pk_fma_f32 v[22:23], v[22:23], s[64:65], 1.0 op_sel_hi:[1,0,0]
	v_cndmask_b32_e32 v8, v9, v27, vcc
	v_rcp_f32_e32 v22, v22
	v_rcp_f32_e32 v23, v23
	v_cmp_gt_f32_e32 vcc, 0, v4
	v_pk_fma_f32 v[10:11], v[22:23], s[66:67], v[10:11] op_sel_hi:[1,0,0]
	s_nop 0
	v_pk_fma_f32 v[10:11], v[22:23], v[10:11], s[70:71] op_sel_hi:[1,1,0]
	s_nop 0
	v_pk_fma_f32 v[10:11], v[22:23], v[10:11], s[72:73] op_sel_hi:[1,1,0]
	s_nop 0
	v_pk_fma_f32 v[10:11], v[22:23], v[10:11], s[74:75] op_sel_hi:[1,1,0]
	s_nop 0
	v_pk_mul_f32 v[10:11], v[22:23], v[10:11]
	v_pk_mul_f32 v[22:23], v[24:25], s[76:77] op_sel_hi:[1,0]
	s_nop 0
	v_exp_f32_e32 v22, v22
	v_exp_f32_e32 v23, v23
	s_nop 0
	v_pk_mul_f32 v[10:11], v[22:23], v[10:11]
	s_nop 0
	v_pk_mul_f32 v[22:23], v[4:5], v[10:11]
	v_pk_fma_f32 v[10:11], v[4:5], v[10:11], v[4:5] neg_lo:[1,0,0] neg_hi:[1,0,0]
	s_nop 0
	v_cndmask_b32_e32 v4, v10, v22, vcc
	v_cmp_gt_f32_e32 vcc, 0, v5
	v_cvt_pk_bf16_f32 v22, v0, v2
	s_nop 1
	v_cndmask_b32_e32 v5, v11, v23, vcc
	s_and_b64 vcc, exec, s[10:11]
	v_cvt_pk_bf16_f32 v23, v3, v6
	v_cvt_pk_bf16_f32 v24, v7, v8
	v_cvt_pk_bf16_f32 v25, v4, v5
	global_store_dwordx4 v[18:19], v[22:25], off offset:256
	s_cbranch_vccnz .LBB0_384
	v_mul_f32_e32 v9, v15, v15
	v_mul_f32_e32 v10, v17, v17
	v_fmac_f32_e32 v9, v14, v14
	v_fmac_f32_e32 v10, v16, v16
	v_add_f32_e32 v9, v9, v10
	v_mul_f32_e32 v10, v21, v21
	v_mul_f32_e32 v11, v13, v13
	v_fmac_f32_e32 v10, v20, v20
	v_fmac_f32_e32 v11, v12, v12
	v_add_f32_e32 v10, v10, v11
	v_add_f32_e32 v9, v9, v10
	v_mul_f32_e32 v10, v2, v2
	v_fmac_f32_e32 v10, v0, v0
	v_mul_f32_e32 v11, v6, v6
	v_add_f32_e32 v0, v0, v2
	v_add_f32_e32 v2, v3, v6
	v_fmac_f32_e32 v11, v3, v3
	v_add_f32_e32 v14, v14, v15
	v_add_f32_e32 v15, v16, v17
	v_add_f32_e32 v0, v0, v2
	v_add_f32_e32 v2, v7, v8
	v_add_f32_e32 v3, v4, v5
	v_add_f32_e32 v14, v14, v15
	v_add_f32_e32 v15, v20, v21
	v_add_f32_e32 v12, v12, v13
	v_add_f32_e32 v2, v2, v3
	v_and_b32_e32 v3, 64, v226
	v_add_f32_e32 v12, v15, v12
	v_add_f32_e32 v0, v0, v2
	v_xor_b32_e32 v2, 16, v226
	v_add_u32_e32 v3, 64, v3
	v_add_f32_e32 v12, v14, v12
	v_cmp_lt_i32_e32 vcc, v2, v3
	v_add_f32_e32 v10, v10, v11
	v_mul_f32_e32 v11, v8, v8
	v_mul_f32_e32 v18, v5, v5
	v_add_f32_e32 v12, 0, v12
	v_cndmask_b32_e32 v2, v226, v2, vcc
	v_fmac_f32_e32 v11, v7, v7
	v_add_f32_e32 v0, v0, v12
	v_lshlrev_b32_e32 v2, 2, v2
	v_fmac_f32_e32 v18, v4, v4
	v_mov_b32_e32 v5, v0
	s_nop 1
	v_permlane16_swap_b32_e32 v5, v0
	v_add_f32_e32 v4, v11, v18
	v_add_f32_e32 v4, v10, v4
	v_add_f32_e32 v4, v9, v4
	v_mov_b32_e32 v6, v4
	s_nop 1
	v_permlane16_swap_b32_e32 v6, v4
	s_waitcnt lgkmcnt(0)
	v_add_f32_e32 v0, v0, v5
	v_xor_b32_e32 v5, 32, v226
	v_cmp_lt_i32_e32 vcc, v5, v3
	v_add_f32_e32 v3, v4, v6
	s_nop 0
	v_cndmask_b32_e32 v2, v226, v5, vcc
	v_lshlrev_b32_e32 v5, 2, v2
	v_mov_b32_e32 v2, v0
	s_nop 1
	v_permlane32_swap_b32_e32 v2, v0
	v_mov_b32_e32 v4, v3
	s_nop 1
	v_permlane32_swap_b32_e32 v4, v3
	s_and_saveexec_b64 s[4:5], s[6:7]
	s_cbranch_execz .LBB0_383
	s_waitcnt lgkmcnt(0)
	v_add_f32_e32 v3, v3, v4
	v_add_f32_e32 v0, v0, v2
	ds_write2st64_b32 v186, v0, v3 offset0:11 offset1:27

; __device__ __forceinline__ unsigned pk2(float lo, float hi) { return pg8::cvt_pk_bf16(lo, hi); }
; __device__ __forceinline__ float wave_sum(float v) {
; #pragma unroll
;     for (int o = 1; o < 64; o <<= 1) v += __shfl_xor(v, o);
;     return v;
; __device__ __forceinline__ void prep_phase(const PT& T, LAS unsigned char* lds) {
;     ...
;     for (int m = 4 * gw; m < M; m += 4 * NGW) {
;         f32x4 v[4][4];
; #pragma unroll
;         for (int r = 0; r < 4; ++r)
; #pragma unroll
;             for (int j = 0; j < 4; ++j) v[r][j] = ((const f32x4*)(xin + (size_t)(m + r) * D) + lane)[64 * j];
; #pragma unroll
;         for (int r = 0; r < 4; ++r) { u32x2* o8 = (u32x2*)(XB + (size_t)(m + r) * D) + lane; float sq = 0.f;
; #pragma unroll
;             for (int j = 0; j < 4; ++j) { u32x2 w; w.x = pk2(v[r][j].x, v[r][j].y); w.y = pk2(v[r][j].z, v[r][j].w); o8[64 * j] = w;
;                 const float r0 = bflo(w.x), r1 = bfhi(w.x), r2 = bflo(w.y), r3 = bfhi(w.y); sq += (r0 * r0 + r1 * r1) + (r2 * r2 + r3 * r3); }
;             sq = wave_sum(sq); if (lane == 0) *(f32x4*)(ss0 + 4 * (size_t)(m + r)) = (f32x4){sq, 0.f, 0.f, 0.f}; }
.LBB0_711:
	s_waitcnt lgkmcnt(0)
	v_add_co_u32_e32 v2, vcc, 0xffffc400, v54
	s_movk_i32 s4, 0xfc00
	s_nop 0
	v_addc_co_u32_e32 v3, vcc, -1, v55, vcc
	v_add_co_u32_e32 v4, vcc, 0xffffc800, v54
	v_lshl_add_u64 v[56:57], s[0:1], 0, v[52:53]
	s_nop 0
	v_addc_co_u32_e32 v5, vcc, -1, v55, vcc
	global_load_dwordx4 v[58:61], v[2:3], off
	global_load_dwordx4 v[62:65], v[4:5], off
	v_add_co_u32_e32 v2, vcc, 0xffffcc00, v54
	s_nop 1
	v_addc_co_u32_e32 v3, vcc, -1, v55, vcc
	v_add_co_u32_e32 v4, vcc, 0xffffd000, v54
	s_nop 1
	v_addc_co_u32_e32 v5, vcc, -1, v55, vcc
	global_load_dwordx4 v[66:69], v[2:3], off
	global_load_dwordx4 v[70:73], v[4:5], off
	v_add_co_u32_e32 v2, vcc, 0xffffd400, v54
	s_nop 1
	v_addc_co_u32_e32 v3, vcc, -1, v55, vcc
	v_add_co_u32_e32 v4, vcc, 0xffffd800, v54
	s_nop 1
	v_addc_co_u32_e32 v5, vcc, -1, v55, vcc
	global_load_dwordx4 v[48:51], v[2:3], off
	global_load_dwordx4 v[44:47], v[4:5], off
	v_add_co_u32_e32 v2, vcc, 0xffffdc00, v54
	s_nop 1
	v_addc_co_u32_e32 v3, vcc, -1, v55, vcc
	v_add_co_u32_e32 v4, vcc, 0xffffe000, v54
	s_nop 1
	v_addc_co_u32_e32 v5, vcc, -1, v55, vcc
	global_load_dwordx4 v[40:43], v[2:3], off
	global_load_dwordx4 v[36:39], v[4:5], off
	v_add_co_u32_e32 v2, vcc, 0xffffe400, v54
	s_nop 1
	v_addc_co_u32_e32 v3, vcc, -1, v55, vcc
	v_add_co_u32_e32 v4, vcc, 0xffffe800, v54
	s_nop 1
	v_addc_co_u32_e32 v5, vcc, -1, v55, vcc
	global_load_dwordx4 v[32:35], v[2:3], off
	global_load_dwordx4 v[28:31], v[4:5], off
	v_add_co_u32_e32 v2, vcc, 0xffffec00, v54
	s_nop 1
	v_addc_co_u32_e32 v3, vcc, -1, v55, vcc
	v_add_co_u32_e32 v4, vcc, 0xfffff000, v54
	s_nop 1
	v_addc_co_u32_e32 v5, vcc, -1, v55, vcc
	global_load_dwordx4 v[24:27], v[2:3], off
	global_load_dwordx4 v[20:23], v[4:5], off
	v_add_co_u32_e32 v2, vcc, 0xfffff400, v54
	s_nop 1
	v_addc_co_u32_e32 v3, vcc, -1, v55, vcc
	v_add_co_u32_e32 v4, vcc, 0xfffff800, v54
	s_nop 1
	v_addc_co_u32_e32 v5, vcc, -1, v55, vcc
	global_load_dwordx4 v[16:19], v[2:3], off
	global_load_dwordx4 v[12:15], v[4:5], off
	v_add_co_u32_e32 v2, vcc, s4, v54
	s_nop 1
	v_addc_co_u32_e32 v3, vcc, -1, v55, vcc
	global_load_dwordx4 v[8:11], v[2:3], off
	global_load_dwordx4 v[4:7], v[54:55], off
	v_add_co_u32_e32 v74, vcc, s2, v56
	s_waitcnt vmcnt(0) lgkmcnt(0)
	v_cvt_pk_bf16_f32 v2, v58, v59
	s_nop 0
	v_addc_co_u32_e32 v75, vcc, 0, v57, vcc
	v_cvt_pk_bf16_f32 v3, v60, v61
	global_store_dwordx2 v[74:75], v[2:3], off
	v_lshlrev_b32_e32 v0, 16, v2
	v_and_b32_e32 v2, 0xffff0000, v2
	v_lshlrev_b32_e32 v58, 16, v3
	v_and_b32_e32 v3, 0xffff0000, v3
	v_mul_f32_e32 v2, v2, v2
	v_fmac_f32_e32 v2, v0, v0
	v_mul_f32_e32 v0, v3, v3
	v_fmac_f32_e32 v0, v58, v58
	v_add_f32_e32 v0, v2, v0
	v_cvt_pk_bf16_f32 v2, v62, v63
	v_cvt_pk_bf16_f32 v3, v64, v65
	global_store_dwordx2 v[74:75], v[2:3], off offset:512
	v_lshlrev_b32_e32 v58, 16, v2
	v_and_b32_e32 v2, 0xffff0000, v2
	v_lshlrev_b32_e32 v59, 16, v3
	v_and_b32_e32 v3, 0xffff0000, v3
	v_mul_f32_e32 v2, v2, v2
	v_mul_f32_e32 v3, v3, v3
	v_fmac_f32_e32 v2, v58, v58
	v_fmac_f32_e32 v3, v59, v59
	v_add_f32_e32 v2, v2, v3
	v_add_f32_e32 v0, v0, v2
	v_cvt_pk_bf16_f32 v2, v66, v67
	v_cvt_pk_bf16_f32 v3, v68, v69
	global_store_dwordx2 v[74:75], v[2:3], off offset:1024
	v_lshlrev_b32_e32 v58, 16, v2
	v_and_b32_e32 v2, 0xffff0000, v2
	v_lshlrev_b32_e32 v59, 16, v3
	v_and_b32_e32 v3, 0xffff0000, v3
	v_mul_f32_e32 v2, v2, v2
	v_mul_f32_e32 v3, v3, v3
	v_fmac_f32_e32 v2, v58, v58
	v_fmac_f32_e32 v3, v59, v59
	v_add_f32_e32 v2, v2, v3
	v_cvt_pk_bf16_f32 v64, v70, v71
	v_add_f32_e32 v0, v0, v2
	v_and_b32_e32 v3, 0xffff0000, v64
	v_cvt_pk_bf16_f32 v65, v72, v73
	v_lshlrev_b32_e32 v2, 16, v64
	v_and_b32_e32 v59, 0xffff0000, v65
	v_mul_f32_e32 v3, v3, v3
	v_lshlrev_b32_e32 v58, 16, v65
	v_fmac_f32_e32 v3, v2, v2
	v_mul_f32_e32 v2, v59, v59
	v_fmac_f32_e32 v2, v58, v58
	v_add_f32_e32 v2, v3, v2
	v_add_f32_e32 v0, v0, v2
	v_and_b32_e32 v2, 64, v226
	v_add_u32_e32 v2, 64, v2
	v_xor_b32_e32 v3, 1, v226
	v_cmp_lt_i32_e32 vcc, v3, v2
	global_store_dwordx2 v[74:75], v[64:65], off offset:1536
	s_nop 0
	v_cndmask_b32_e32 v3, v226, v3, vcc
	v_lshlrev_b32_e32 v58, 2, v3
	ds_bpermute_b32 v3, v58, v0
	s_waitcnt lgkmcnt(0)
	v_add_f32_e32 v0, v0, v3
	v_xor_b32_e32 v3, 2, v226
	v_cmp_lt_i32_e32 vcc, v3, v2
	s_nop 1
	v_cndmask_b32_e32 v3, v226, v3, vcc
	v_lshlrev_b32_e32 v59, 2, v3
	ds_bpermute_b32 v3, v59, v0
	s_waitcnt lgkmcnt(0)
	v_add_f32_e32 v0, v0, v3
	v_xor_b32_e32 v3, 4, v226
	v_cmp_lt_i32_e32 vcc, v3, v2
	s_nop 1
	v_cndmask_b32_e32 v3, v226, v3, vcc
	v_lshlrev_b32_e32 v60, 2, v3
	ds_bpermute_b32 v3, v60, v0
	s_waitcnt lgkmcnt(0)
	v_add_f32_e32 v0, v0, v3
	v_xor_b32_e32 v3, 8, v226
	v_cmp_lt_i32_e32 vcc, v3, v2
	s_nop 1
	v_cndmask_b32_e32 v3, v226, v3, vcc
	v_lshlrev_b32_e32 v61, 2, v3
	ds_bpermute_b32 v3, v61, v0
	s_waitcnt lgkmcnt(0)
	v_add_f32_e32 v0, v0, v3
	v_xor_b32_e32 v3, 16, v226
	v_cmp_lt_i32_e32 vcc, v3, v2
	s_nop 1
	v_cndmask_b32_e32 v3, v226, v3, vcc
	v_lshlrev_b32_e32 v62, 2, v3
	v_mov_b32_e32 v3, v0
	s_nop 1
	v_permlane16_swap_b32_e32 v3, v0
	s_waitcnt lgkmcnt(0)
	v_add_f32_e32 v0, v0, v3
	v_xor_b32_e32 v3, 32, v226
	v_cmp_lt_i32_e32 vcc, v3, v2
	s_nop 1
	v_cndmask_b32_e32 v2, v226, v3, vcc
	v_lshlrev_b32_e32 v63, 2, v2
	v_mov_b32_e32 v2, v0
	s_nop 1
	v_permlane32_swap_b32_e32 v2, v0
	s_and_saveexec_b64 s[4:5], s[6:7]
	s_cbranch_execz .LBB0_713
	s_add_u32 s9, s0, s16
	s_waitcnt lgkmcnt(0)
	v_add_f32_e32 v0, v0, v2
	s_addc_u32 s11, s1, s17
	v_mov_b32_e32 v2, s9
	v_add_co_u32_e32 v64, vcc, 0x19000000, v2
	v_mov_b32_e32 v2, s11
	s_nop 0
	v_addc_co_u32_e32 v65, vcc, 0, v2, vcc
	v_mov_b32_e32 v2, v1
	v_mov_b32_e32 v3, v1
	global_store_dwordx4 v[64:65], v[0:3], off
; __device__ __forceinline__ unsigned pk2(float lo, float hi) { return pg8::cvt_pk_bf16(lo, hi); }
; __device__ __forceinline__ float wave_sum(float v) {
; #pragma unroll
;     for (int o = 1; o < 64; o <<= 1) v += __shfl_xor(v, o);
;     return v;
; __device__ __forceinline__ void prep_phase(const PT& T, LAS unsigned char* lds) {
;     ...
;         for (int r = 0; r < 4; ++r) { u32x2* o8 = (u32x2*)(XB + (size_t)(m + r) * D) + lane; float sq = 0.f;
; #pragma unroll
;             for (int j = 0; j < 4; ++j) { u32x2 w; w.x = pk2(v[r][j].x, v[r][j].y); w.y = pk2(v[r][j].z, v[r][j].w); o8[64 * j] = w;
;                 const float r0 = bflo(w.x), r1 = bfhi(w.x), r2 = bflo(w.y), r3 = bfhi(w.y); sq += (r0 * r0 + r1 * r1) + (r2 * r2 + r3 * r3); }
;             sq = wave_sum(sq); if (lane == 0) *(f32x4*)(ss0 + 4 * (size_t)(m + r)) = (f32x4){sq, 0.f, 0.f, 0.f}; }
.LBB0_713:
	s_or_b64 exec, exec, s[4:5]
	s_waitcnt lgkmcnt(0)
	v_cvt_pk_bf16_f32 v2, v48, v49
	v_add_co_u32_e32 v48, vcc, 0x6000000, v56
	v_cvt_pk_bf16_f32 v3, v50, v51
	v_lshlrev_b32_e32 v0, 16, v2
	s_nop 0
	v_addc_co_u32_e32 v49, vcc, 0, v57, vcc
	global_store_dwordx2 v[48:49], v[2:3], off offset:2048
	v_and_b32_e32 v2, 0xffff0000, v2
	v_lshlrev_b32_e32 v50, 16, v3
	v_and_b32_e32 v3, 0xffff0000, v3
	v_mul_f32_e32 v2, v2, v2
	v_fmac_f32_e32 v2, v0, v0
	v_mul_f32_e32 v0, v3, v3
	v_fmac_f32_e32 v0, v50, v50
	v_add_f32_e32 v0, v2, v0
	v_cvt_pk_bf16_f32 v2, v44, v45
	v_cvt_pk_bf16_f32 v3, v46, v47
	global_store_dwordx2 v[48:49], v[2:3], off offset:2560
	v_lshlrev_b32_e32 v44, 16, v2
	v_and_b32_e32 v2, 0xffff0000, v2
	v_lshlrev_b32_e32 v45, 16, v3
	v_and_b32_e32 v3, 0xffff0000, v3
	v_mul_f32_e32 v2, v2, v2
	v_mul_f32_e32 v3, v3, v3
	v_fmac_f32_e32 v2, v44, v44
	v_fmac_f32_e32 v3, v45, v45
	v_add_f32_e32 v2, v2, v3
	v_add_f32_e32 v0, v0, v2
	v_cvt_pk_bf16_f32 v2, v40, v41
	v_cvt_pk_bf16_f32 v3, v42, v43
	global_store_dwordx2 v[48:49], v[2:3], off offset:3072
	v_lshlrev_b32_e32 v40, 16, v2
	v_and_b32_e32 v2, 0xffff0000, v2
	v_lshlrev_b32_e32 v41, 16, v3
	v_and_b32_e32 v3, 0xffff0000, v3
	v_mul_f32_e32 v2, v2, v2
	v_mul_f32_e32 v3, v3, v3
	v_fmac_f32_e32 v2, v40, v40
	v_fmac_f32_e32 v3, v41, v41
	v_add_f32_e32 v2, v2, v3
	v_cvt_pk_bf16_f32 v36, v36, v37
	v_add_f32_e32 v0, v0, v2
	v_and_b32_e32 v3, 0xffff0000, v36
	v_cvt_pk_bf16_f32 v37, v38, v39
	v_lshlrev_b32_e32 v2, 16, v36
	v_and_b32_e32 v39, 0xffff0000, v37
	v_mul_f32_e32 v3, v3, v3
	v_lshlrev_b32_e32 v38, 16, v37
	v_fmac_f32_e32 v3, v2, v2
	v_mul_f32_e32 v2, v39, v39
	v_fmac_f32_e32 v2, v38, v38
	v_add_f32_e32 v2, v3, v2
	v_add_f32_e32 v0, v0, v2
	ds_bpermute_b32 v2, v58, v0
	global_store_dwordx2 v[48:49], v[36:37], off offset:3584
	s_waitcnt lgkmcnt(0)
	v_add_f32_e32 v0, v0, v2
	ds_bpermute_b32 v2, v59, v0
	s_waitcnt lgkmcnt(0)
	v_add_f32_e32 v0, v0, v2
	ds_bpermute_b32 v2, v60, v0
	s_waitcnt lgkmcnt(0)
	v_add_f32_e32 v0, v0, v2
	ds_bpermute_b32 v2, v61, v0
	s_waitcnt lgkmcnt(0)
	v_add_f32_e32 v0, v0, v2
	v_mov_b32_e32 v2, v0
	s_nop 1
	v_permlane16_swap_b32_e32 v2, v0
	s_waitcnt lgkmcnt(0)
	v_add_f32_e32 v0, v0, v2
	v_mov_b32_e32 v2, v0
	s_nop 1
	v_permlane32_swap_b32_e32 v2, v0
	s_and_saveexec_b64 s[4:5], s[6:7]
	s_cbranch_execz .LBB0_715
	s_add_u32 s9, s0, s16
	s_waitcnt lgkmcnt(0)
	v_add_f32_e32 v0, v0, v2
	s_addc_u32 s11, s1, s17
	v_mov_b32_e32 v2, s9
	v_add_co_u32_e32 v36, vcc, 0x19000000, v2
	v_mov_b32_e32 v2, s11
	s_nop 0
	v_addc_co_u32_e32 v37, vcc, 0, v2, vcc
	v_mov_b32_e32 v2, v1
	v_mov_b32_e32 v3, v1
	global_store_dwordx4 v[36:37], v[0:3], off offset:16
; __device__ __forceinline__ unsigned pk2(float lo, float hi) { return pg8::cvt_pk_bf16(lo, hi); }
; __device__ __forceinline__ float wave_sum(float v) {
; #pragma unroll
;     for (int o = 1; o < 64; o <<= 1) v += __shfl_xor(v, o);
;     return v;
; __device__ __forceinline__ void prep_phase(const PT& T, LAS unsigned char* lds) {
;     ...
;         for (int r = 0; r < 4; ++r) { u32x2* o8 = (u32x2*)(XB + (size_t)(m + r) * D) + lane; float sq = 0.f;
; #pragma unroll
;             for (int j = 0; j < 4; ++j) { u32x2 w; w.x = pk2(v[r][j].x, v[r][j].y); w.y = pk2(v[r][j].z, v[r][j].w); o8[64 * j] = w;
;                 const float r0 = bflo(w.x), r1 = bfhi(w.x), r2 = bflo(w.y), r3 = bfhi(w.y); sq += (r0 * r0 + r1 * r1) + (r2 * r2 + r3 * r3); }
;             sq = wave_sum(sq); if (lane == 0) *(f32x4*)(ss0 + 4 * (size_t)(m + r)) = (f32x4){sq, 0.f, 0.f, 0.f}; }
.LBB0_715:
	s_or_b64 exec, exec, s[4:5]
	s_waitcnt lgkmcnt(0)
	v_cvt_pk_bf16_f32 v2, v32, v33
	v_add_co_u32_e32 v32, vcc, 0x6001000, v56
	v_cvt_pk_bf16_f32 v3, v34, v35
	v_lshlrev_b32_e32 v0, 16, v2
	s_nop 0
	v_addc_co_u32_e32 v33, vcc, 0, v57, vcc
	global_store_dwordx2 v[32:33], v[2:3], off
	v_and_b32_e32 v2, 0xffff0000, v2
	v_lshlrev_b32_e32 v34, 16, v3
	v_and_b32_e32 v3, 0xffff0000, v3
	v_mul_f32_e32 v2, v2, v2
	v_fmac_f32_e32 v2, v0, v0
	v_mul_f32_e32 v0, v3, v3
	v_fmac_f32_e32 v0, v34, v34
	v_add_f32_e32 v0, v2, v0
	v_cvt_pk_bf16_f32 v2, v28, v29
	v_cvt_pk_bf16_f32 v3, v30, v31
	global_store_dwordx2 v[32:33], v[2:3], off offset:512
	v_lshlrev_b32_e32 v28, 16, v2
	v_and_b32_e32 v2, 0xffff0000, v2
	v_lshlrev_b32_e32 v29, 16, v3
	v_and_b32_e32 v3, 0xffff0000, v3
	v_mul_f32_e32 v2, v2, v2
	v_mul_f32_e32 v3, v3, v3
	v_fmac_f32_e32 v2, v28, v28
	v_fmac_f32_e32 v3, v29, v29
	v_add_f32_e32 v2, v2, v3
	v_add_f32_e32 v0, v0, v2
	v_cvt_pk_bf16_f32 v2, v24, v25
	v_cvt_pk_bf16_f32 v3, v26, v27
	global_store_dwordx2 v[32:33], v[2:3], off offset:1024
	v_lshlrev_b32_e32 v24, 16, v2
	v_and_b32_e32 v2, 0xffff0000, v2
	v_lshlrev_b32_e32 v25, 16, v3
	v_and_b32_e32 v3, 0xffff0000, v3
	v_mul_f32_e32 v2, v2, v2
	v_mul_f32_e32 v3, v3, v3
	v_fmac_f32_e32 v2, v24, v24
	v_fmac_f32_e32 v3, v25, v25
	v_add_f32_e32 v2, v2, v3
	v_cvt_pk_bf16_f32 v20, v20, v21
	v_add_f32_e32 v0, v0, v2
	v_and_b32_e32 v3, 0xffff0000, v20
	v_cvt_pk_bf16_f32 v21, v22, v23
	v_lshlrev_b32_e32 v2, 16, v20
	v_and_b32_e32 v23, 0xffff0000, v21
	v_mul_f32_e32 v3, v3, v3
	v_lshlrev_b32_e32 v22, 16, v21
	v_fmac_f32_e32 v3, v2, v2
	v_mul_f32_e32 v2, v23, v23
	v_fmac_f32_e32 v2, v22, v22
	v_add_f32_e32 v2, v3, v2
	v_add_f32_e32 v0, v0, v2
	ds_bpermute_b32 v2, v58, v0
	global_store_dwordx2 v[32:33], v[20:21], off offset:1536
	s_waitcnt lgkmcnt(0)
	v_add_f32_e32 v0, v0, v2
	ds_bpermute_b32 v2, v59, v0
	s_waitcnt lgkmcnt(0)
	v_add_f32_e32 v0, v0, v2
	ds_bpermute_b32 v2, v60, v0
	s_waitcnt lgkmcnt(0)
	v_add_f32_e32 v0, v0, v2
	ds_bpermute_b32 v2, v61, v0
	s_waitcnt lgkmcnt(0)
	v_add_f32_e32 v0, v0, v2
	v_mov_b32_e32 v2, v0
	s_nop 1
	v_permlane16_swap_b32_e32 v2, v0
	s_waitcnt lgkmcnt(0)
	v_add_f32_e32 v0, v0, v2
	v_mov_b32_e32 v2, v0
	s_nop 1
	v_permlane32_swap_b32_e32 v2, v0
	s_and_saveexec_b64 s[4:5], s[6:7]
	s_cbranch_execz .LBB0_717
	s_add_u32 s9, s0, s16
	s_waitcnt lgkmcnt(0)
	v_add_f32_e32 v0, v0, v2
	s_addc_u32 s11, s1, s17
	v_mov_b32_e32 v2, s9
	v_add_co_u32_e32 v20, vcc, 0x19000000, v2
	v_mov_b32_e32 v2, s11
	s_nop 0
	v_addc_co_u32_e32 v21, vcc, 0, v2, vcc
	v_mov_b32_e32 v2, v1
	v_mov_b32_e32 v3, v1
	global_store_dwordx4 v[20:21], v[0:3], off offset:32
.LBB0_717:
	s_or_b64 exec, exec, s[4:5]
	s_waitcnt lgkmcnt(0)
	v_cvt_pk_bf16_f32 v2, v16, v17
	v_add_co_u32_e32 v16, vcc, 0x6001000, v56
	v_cvt_pk_bf16_f32 v3, v18, v19
	v_lshlrev_b32_e32 v0, 16, v2
	s_nop 0
	v_addc_co_u32_e32 v17, vcc, 0, v57, vcc
	global_store_dwordx2 v[16:17], v[2:3], off offset:2048
	v_and_b32_e32 v2, 0xffff0000, v2
	v_lshlrev_b32_e32 v18, 16, v3
	v_and_b32_e32 v3, 0xffff0000, v3
	v_mul_f32_e32 v2, v2, v2
	v_fmac_f32_e32 v2, v0, v0
	v_mul_f32_e32 v0, v3, v3
	v_fmac_f32_e32 v0, v18, v18
	v_add_f32_e32 v0, v2, v0
	v_cvt_pk_bf16_f32 v2, v12, v13
	v_cvt_pk_bf16_f32 v3, v14, v15
	global_store_dwordx2 v[16:17], v[2:3], off offset:2560
	v_lshlrev_b32_e32 v12, 16, v2
	v_and_b32_e32 v2, 0xffff0000, v2
	v_lshlrev_b32_e32 v13, 16, v3
	v_and_b32_e32 v3, 0xffff0000, v3
	v_mul_f32_e32 v2, v2, v2
	v_mul_f32_e32 v3, v3, v3
	v_fmac_f32_e32 v2, v12, v12
	v_fmac_f32_e32 v3, v13, v13
	v_add_f32_e32 v2, v2, v3
	v_add_f32_e32 v0, v0, v2
	v_cvt_pk_bf16_f32 v2, v8, v9
	v_cvt_pk_bf16_f32 v3, v10, v11
	global_store_dwordx2 v[16:17], v[2:3], off offset:3072
	v_lshlrev_b32_e32 v8, 16, v2
	v_and_b32_e32 v2, 0xffff0000, v2
	v_lshlrev_b32_e32 v9, 16, v3
	v_and_b32_e32 v3, 0xffff0000, v3
	v_mul_f32_e32 v2, v2, v2
	v_mul_f32_e32 v3, v3, v3
	v_fmac_f32_e32 v2, v8, v8
	v_fmac_f32_e32 v3, v9, v9
	v_add_f32_e32 v2, v2, v3
	v_cvt_pk_bf16_f32 v4, v4, v5
	v_add_f32_e32 v0, v0, v2
	v_and_b32_e32 v3, 0xffff0000, v4
	v_cvt_pk_bf16_f32 v5, v6, v7
	v_lshlrev_b32_e32 v2, 16, v4
	v_and_b32_e32 v7, 0xffff0000, v5
	v_mul_f32_e32 v3, v3, v3
	v_lshlrev_b32_e32 v6, 16, v5
	v_fmac_f32_e32 v3, v2, v2
	v_mul_f32_e32 v2, v7, v7
	v_fmac_f32_e32 v2, v6, v6
	v_add_f32_e32 v2, v3, v2
	v_add_f32_e32 v0, v0, v2
	ds_bpermute_b32 v2, v58, v0
	global_store_dwordx2 v[16:17], v[4:5], off offset:3584
	s_waitcnt lgkmcnt(0)
	v_add_f32_e32 v0, v0, v2
	ds_bpermute_b32 v2, v59, v0
	s_waitcnt lgkmcnt(0)
	v_add_f32_e32 v0, v0, v2
	ds_bpermute_b32 v2, v60, v0
	s_waitcnt lgkmcnt(0)
	v_add_f32_e32 v0, v0, v2
	ds_bpermute_b32 v2, v61, v0
	s_waitcnt lgkmcnt(0)
	v_add_f32_e32 v0, v0, v2
	v_mov_b32_e32 v2, v0
	s_nop 1
	v_permlane16_swap_b32_e32 v2, v0
	s_waitcnt lgkmcnt(0)
	v_add_f32_e32 v0, v0, v2
	v_mov_b32_e32 v2, v0
	s_nop 1
	v_permlane32_swap_b32_e32 v2, v0
	s_and_saveexec_b64 s[4:5], s[6:7]
	s_cbranch_execz .LBB0_710
	s_add_u32 s9, s0, s16
	s_waitcnt lgkmcnt(0)
	v_add_f32_e32 v0, v0, v2
	s_addc_u32 s11, s1, s17
	v_mov_b32_e32 v2, s9
	v_add_co_u32_e32 v4, vcc, 0x19000000, v2
	v_mov_b32_e32 v2, s11
	s_nop 0
	v_addc_co_u32_e32 v5, vcc, 0, v2, vcc
	v_mov_b32_e32 v2, v1
	v_mov_b32_e32 v3, v1
	global_store_dwordx4 v[4:5], v[0:3], off offset:48
	s_branch .LBB0_710
